# attention: static s_setprio 1 for waves 4-7 on top of the 16x16x32 hand-written attention body
# speedup vs baseline: 1.0968x; 1.0043x over previous
; __device__ __forceinline__ int v_st(int k, int c) { const int kk = (k & ~0xC) | ((k & 4) << 1) | ((k & 8) >> 1); return ((kk >> 3) * 4 + (c >> 5)) * 512 + ((kk & 7) * 32 + (c & 31)) * 2; }
; __device__ __forceinline__ int v_rd_base(int lane) { return ((lane & 3) << 3) | (((lane >> 2) & 3) << 6) | (((lane >> 4) & 1) << 5) | (((lane >> 5) & 1) << 8); }
; #define QF(d, e) __uint_as_float(((unsigned)(unsigned short)qr[d][e]) << 16)
; template <typename TQ> ...
;     ...
;   const TQ* Qw = Qb + (long)(wid * QBLK + r32) * LDQ + hi * 8;
; #pragma unroll
;   for (int d0 = 0; d0 < 8; ++d0) qr[d0] = SQ::tobf(SQ::ld8(Qw + d0 * 16));
;   const int sr = tid >> 4, sc = (tid & 15) * 8, vst0 = v_st(sr, sc), vst1 = v_st(32 + sr, sc);
;   const int vb0 = (int)(uintptr_t)V_lds + v_rd_base(lane);
;   struct { typename St::T vs0, vs1, ks0, ks1; } sr_[SDEPTH];
;     ...
;   constexpr int SE = 0, SO = SDEPTH - 1;
;   SLOAD(SE, 0);
;   {
;     float ss = 0.f;
;     ...
; #pragma unroll
;     for (int d0 = 0; d0 < 8; ++d0)
; #pragma unroll
;       for (int e = 0; e < 8; ++e) { const float x = QF(d0, e); ss += x * x; }
;     ss += __shfl_xor(ss, 32);
;     const float rn = (SCALE * 1.4426950408889634f) / sqrtf(ss * (1.0f / 128.0f) + 1e-6f);
;     const int t = trow0 + wid * QBLK + r32; const int prow = t >> 6, pcol = t & 63;
; #pragma unroll
;     for (int hf = 0; hf < 2; ++hf)
; #pragma unroll
;       for (int dd = 0; dd < 2; ++dd) {
;         const int dl = 4 * hf + dd, du = dl + 2;
;         const int f0 = 16 * dd + 8 * hi;
;         const float* cp = rc + (hf ? pcol : prow) * 32 + f0; const float* sp = rsn + (hf ? pcol : prow) * 32 + f0;
;         const float* gl = gq + 16 * dl + 8 * hi; const float* gu = gq + 16 * du + 8 * hi;
; __global__ void __launch_bounds__(NTHR, 2) fwd_megakernel(KArgs a) {
;     ...
;         for (int i = 0; i < upb; ++i) {
;             const int unit = vcu * upb + i; if (unit >= 512) break;
;             const int grp = unit >> 7, rem = unit & 127, gq = rem >> 5, qb = rem & 31, b = grp >> 1, kvh = grp & 1, h = kvh * 4 + gq;
;             const size_t qoff = ((size_t)(b * SEQ + qb * 256)) * DM + h * 128, koff = (size_t)b * SKV * 256 + kvh * 128;
;             att::attn_dense_body<att::bf16>(Q + qoff, Kb + koff, Vb + koff, O + qoff, SKV, (char*)lds_raw, mC, a.g_q, (const float*)(ws + WS_ROPE), (const float*)(ws + WS_ROPE) + 4096, qb * 256);
.LBB0_819:
	s_add_i32 s12, s74, s73
	s_cmpk_gt_i32 s12, 0x1ff
	s_mov_b64 s[0:1], -1
	s_cbranch_scc1 .LBB0_818
	s_lshl_b32 s0, s94, 1
	s_ashr_i32 s96, s12, 8
	s_lshl_b32 s1, s12, 8
	s_and_b32 s95, s0, 0x100
	s_lshl_b32 s0, s96, 13
	s_and_b32 s33, s1, 0x1f00
	s_bfe_u32 s15, s12, 0x10007
	s_or_b32 s0, s0, s33
	s_lshl_b32 s12, s12, 2
	s_ashr_i32 s1, s0, 31
	s_lshl_b32 s13, s15, 9
	s_and_b32 s12, s12, 0x180
	s_lshl_b64 s[0:1], s[0:1], 10
	s_or_b32 s12, s13, s12
	s_or_b32 s0, s0, s12
	s_mul_i32 s12, s96, 0x210000
	s_lshl_b32 s15, s15, 7
	s_or_b32 s12, s12, s15
	s_lshl_b64 s[48:49], s[0:1], 1
	s_mul_hi_i32 s13, s96, 0x210000
	s_add_u32 s0, s20, s48
	s_addc_u32 s1, s21, s49
	s_lshl_b64 s[12:13], s[12:13], 1
	s_add_u32 s54, s69, s12
	s_addc_u32 s55, s70, s13
	v_mov_b32_e32 v114, v0
	s_add_u32 s64, s67, s12
	s_addc_u32 s65, s68, s13
	v_readfirstlane_b32 s53, v114
	s_lshr_b32 s15, s53, 6
	s_lshl_b32 s80, s15, 11
	s_add_u32 s79, s80, 0x10000
	s_lshl_b32 s52, s15, 5
	s_lshl_b32 s12, s15, 3
	v_and_b32_e32 v1, 63, v0
	v_and_b32_e32 v16, 15, v1
	v_lshrrev_b32_e32 v17, 4, v1
	v_add_u32_e32 v12, s12, v17
	v_and_b32_e32 v6, 15, v12
	v_xor_b32_e32 v6, v6, v16
	v_lshlrev_b32_e32 v6, 4, v6
	v_lshl_or_b32 v246, v12, 9, v6
	v_and_b32_e32 v6, 7, v12
	v_lshrrev_b32_e32 v7, 1, v16
	v_xor_b32_e32 v6, v6, v7
	v_and_b32_e32 v7, 1, v16
	v_lshl_or_b32 v6, v6, 1, v7
	v_lshlrev_b32_e32 v6, 4, v6
	v_lshl_or_b32 v248, v12, 9, v6
	v_add_u32_e32 v12, s12, v17
	v_add_u32_e32 v12, 4, v12
	v_and_b32_e32 v6, 15, v12
	v_xor_b32_e32 v6, v6, v16
	v_lshlrev_b32_e32 v6, 4, v6
	v_lshl_or_b32 v247, v12, 9, v6
	v_and_b32_e32 v6, 7, v12
	v_lshrrev_b32_e32 v7, 1, v16
	v_xor_b32_e32 v6, v6, v7
	v_and_b32_e32 v7, 1, v16
	v_lshl_or_b32 v6, v6, 1, v7
	v_lshlrev_b32_e32 v6, 4, v6
	v_lshl_or_b32 v249, v12, 9, v6
	s_mov_b32 s98, s54
	s_mov_b32 s99, s55
	s_mov_b32 s100, s64
	s_mov_b32 s101, s65
	s_add_u32 m0, s79, 0
	s_nop 0
	global_load_lds_dwordx4 v246, s[98:99]
	s_add_u32 m0, s79, 1024
	s_nop 0
	global_load_lds_dwordx4 v247, s[98:99]
	s_add_u32 m0, s80, 0
	s_nop 0
	global_load_lds_dwordx4 v248, s[100:101]
	s_add_u32 m0, s80, 1024
	s_nop 0
	global_load_lds_dwordx4 v249, s[100:101]
	s_add_u32 s98, s98, 0x8000
	s_addc_u32 s99, s99, 0
	s_add_u32 s100, s100, 0x8000
	s_addc_u32 s101, s101, 0
	s_add_u32 m0, s79, 16384
	s_nop 0
	global_load_lds_dwordx4 v246, s[98:99]
	s_add_u32 m0, s79, 17408
	s_nop 0
	global_load_lds_dwordx4 v247, s[98:99]
	s_add_u32 m0, s80, 16384
	s_nop 0
	global_load_lds_dwordx4 v248, s[100:101]
	s_add_u32 m0, s80, 17408
	s_nop 0
	global_load_lds_dwordx4 v249, s[100:101]
	s_add_u32 s98, s98, 0x8000
	s_addc_u32 s99, s99, 0
	s_add_u32 s100, s100, 0x8000
	s_addc_u32 s101, s101, 0
	s_add_u32 m0, s79, 32768
	s_nop 0
	global_load_lds_dwordx4 v246, s[98:99]
	s_add_u32 m0, s79, 33792
	s_nop 0
	global_load_lds_dwordx4 v247, s[98:99]
	s_add_u32 m0, s80, 32768
	s_nop 0
	global_load_lds_dwordx4 v248, s[100:101]
	s_add_u32 m0, s80, 33792
	s_nop 0
	global_load_lds_dwordx4 v249, s[100:101]
	s_add_u32 s98, s98, 0x8000
	s_addc_u32 s99, s99, 0
	s_add_u32 m0, s79, 49152
	s_nop 0
	global_load_lds_dwordx4 v246, s[98:99]
	s_add_u32 m0, s79, 50176
	s_nop 0
	global_load_lds_dwordx4 v247, s[98:99]
	v_add_u32_e32 v6, s52, v16
	v_lshlrev_b32_e32 v6, 11, v6
	v_lshl_or_b32 v13, v17, 4, v6
	v_add_u32_e32 v14, 0x8000, v13
	global_load_dwordx4 v[146:149], v13, s[0:1] offset:0
	global_load_dwordx4 v[150:153], v13, s[0:1] offset:64
	global_load_dwordx4 v[154:157], v13, s[0:1] offset:128
	global_load_dwordx4 v[158:161], v13, s[0:1] offset:192
	global_load_dwordx4 v[162:165], v14, s[0:1] offset:0
	global_load_dwordx4 v[166:169], v14, s[0:1] offset:64
	global_load_dwordx4 v[170:173], v14, s[0:1] offset:128
	global_load_dwordx4 v[174:177], v14, s[0:1] offset:192
	v_lshlrev_b32_e32 v15, 5, v17
	global_load_dwordx4 v[18:21], v15, s[26:27] offset:0
	global_load_dwordx4 v[22:25], v15, s[26:27] offset:16
	global_load_dwordx4 v[26:29], v15, s[26:27] offset:128
	global_load_dwordx4 v[30:33], v15, s[26:27] offset:144
	global_load_dwordx4 v[34:37], v15, s[26:27] offset:256
	global_load_dwordx4 v[38:41], v15, s[26:27] offset:272
	global_load_dwordx4 v[42:45], v15, s[26:27] offset:384
	global_load_dwordx4 v[46:49], v15, s[26:27] offset:400
	s_add_u32 s13, s33, s52
	s_lshr_b32 s13, s13, 6
	s_lshl_b32 s13, s13, 7
	v_add_u32_e32 v200, s13, v15
	global_load_dwordx4 v[82:85], v200, s[4:5] offset:0
	global_load_dwordx4 v[90:93], v200, s[6:7] offset:0
	global_load_dwordx4 v[86:89], v200, s[4:5] offset:16
	global_load_dwordx4 v[94:97], v200, s[6:7] offset:16
	v_add_u32_e32 v6, s52, v16
	v_and_b32_e32 v6, 63, v6
	v_lshl_or_b32 v200, v6, 7, v15
	global_load_dwordx4 v[98:101], v200, s[4:5] offset:0
	global_load_dwordx4 v[106:109], v200, s[6:7] offset:0
	global_load_dwordx4 v[102:105], v200, s[4:5] offset:16
	global_load_dwordx4 v[110:113], v200, s[6:7] offset:16
	v_add_u32_e32 v6, s52, v16
	v_add_u32_e32 v6, 16, v6
	v_and_b32_e32 v6, 63, v6
	v_lshl_or_b32 v200, v6, 7, v15
	global_load_dwordx4 v[114:117], v200, s[4:5] offset:0
	global_load_dwordx4 v[122:125], v200, s[6:7] offset:0
	global_load_dwordx4 v[118:121], v200, s[4:5] offset:16
	global_load_dwordx4 v[126:129], v200, s[6:7] offset:16
	v_lshlrev_b32_e32 v7, 8, v16
	v_or_b32_e32 v6, 0, v17
	v_xor_b32_e32 v6, v6, v16
	v_lshl_or_b32 v6, v6, 4, v7
	v_add_u32_e32 v234, 0x10000, v6
	v_or_b32_e32 v6, 4, v17
	v_xor_b32_e32 v6, v6, v16
	v_lshl_or_b32 v6, v6, 4, v7
	v_add_u32_e32 v235, 0x10000, v6
	v_or_b32_e32 v6, 8, v17
	v_xor_b32_e32 v6, v6, v16
	v_lshl_or_b32 v6, v6, 4, v7
	v_add_u32_e32 v236, 0x10000, v6
	v_or_b32_e32 v6, 12, v17
	v_xor_b32_e32 v6, v6, v16
	v_lshl_or_b32 v6, v6, 4, v7
	v_add_u32_e32 v237, 0x10000, v6
	v_bfe_u32 v6, v1, 2, 2
	v_lshl_or_b32 v6, v17, 2, v6
	v_and_b32_e32 v201, 7, v6
	v_and_b32_e32 v7, 3, v1
	v_lshlrev_b32_e32 v7, 3, v7
	v_lshl_or_b32 v7, v6, 8, v7
	v_xor_b32_e32 v12, 0, v201
	v_lshl_or_b32 v238, v12, 5, v7
	v_xor_b32_e32 v12, 1, v201
	v_lshl_or_b32 v239, v12, 5, v7
	v_xor_b32_e32 v12, 2, v201
	v_lshl_or_b32 v240, v12, 5, v7
	v_xor_b32_e32 v12, 3, v201
	v_lshl_or_b32 v241, v12, 5, v7
	v_xor_b32_e32 v12, 4, v201
	v_lshl_or_b32 v242, v12, 5, v7
	v_xor_b32_e32 v12, 5, v201
	v_lshl_or_b32 v243, v12, 5, v7
	v_xor_b32_e32 v12, 6, v201
	v_lshl_or_b32 v244, v12, 5, v7
	v_xor_b32_e32 v12, 7, v201
	v_lshl_or_b32 v245, v12, 5, v7
	s_waitcnt vmcnt(0)
; #define QF(d, e) __uint_as_float(((unsigned)(unsigned short)qr[d][e]) << 16)
; template <typename TQ> ...
;     ...
;   {
;     float ss = 0.f;
;     ...
; #pragma unroll
;     for (int d0 = 0; d0 < 8; ++d0)
; #pragma unroll
;       for (int e = 0; e < 8; ++e) { const float x = QF(d0, e); ss += x * x; }
;     ss += __shfl_xor(ss, 32);
;     const float rn = (SCALE * 1.4426950408889634f) / sqrtf(ss * (1.0f / 128.0f) + 1e-6f);
;     const int t = trow0 + wid * QBLK + r32; const int prow = t >> 6, pcol = t & 63;
; #pragma unroll
;     for (int hf = 0; hf < 2; ++hf)
; #pragma unroll
;       for (int dd = 0; dd < 2; ++dd) {
;         const int dl = 4 * hf + dd, du = dl + 2;
;         const int f0 = 16 * dd + 8 * hi;
;         const float* cp = rc + (hf ? pcol : prow) * 32 + f0; const float* sp = rsn + (hf ? pcol : prow) * 32 + f0;
;         const float* gl = gq + 16 * dl + 8 * hi; const float* gu = gq + 16 * du + 8 * hi;
;         unsigned wl[4], wu[4];
; #pragma unroll
;         for (int e = 0; e < 8; e += 2) {
;           float o1[2], o2[2];
; #pragma unroll
;           for (int k = 0; k < 2; ++k) { const float x1 = QF(dl, e + k) * rn * gl[e + k], x2 = QF(du, e + k) * rn * gu[e + k]; const float c = cp[e + k], sn = sp[e + k];
;             o1[k] = x1 * c - x2 * sn; o2[k] = x2 * c + x1 * sn; }
;           wl[e >> 1] = cvtpk(o1[0], o1[1]); wu[e >> 1] = cvtpk(o2[0], o2[1]);
;         }
;         u32x4 vl = {wl[0], wl[1], wl[2], wl[3]}, vu = {wu[0], wu[1], wu[2], wu[3]};
;         qr[dl] = *reinterpret_cast<bf16x8*>(&vl); qr[du] = *reinterpret_cast<bf16x8*>(&vu);
;       }
	v_lshlrev_b32_e32 v50, 16, v146
	v_and_b32_e32 v51, 0xffff0000, v146
	v_lshlrev_b32_e32 v52, 16, v147
	v_and_b32_e32 v53, 0xffff0000, v147
	v_lshlrev_b32_e32 v54, 16, v148
	v_and_b32_e32 v55, 0xffff0000, v148
	v_lshlrev_b32_e32 v56, 16, v149
	v_and_b32_e32 v57, 0xffff0000, v149
	v_lshlrev_b32_e32 v58, 16, v150
	v_and_b32_e32 v59, 0xffff0000, v150
	v_lshlrev_b32_e32 v60, 16, v151
	v_and_b32_e32 v61, 0xffff0000, v151
	v_lshlrev_b32_e32 v62, 16, v152
	v_and_b32_e32 v63, 0xffff0000, v152
	v_lshlrev_b32_e32 v64, 16, v153
	v_and_b32_e32 v65, 0xffff0000, v153
	v_lshlrev_b32_e32 v66, 16, v154
	v_and_b32_e32 v67, 0xffff0000, v154
	v_lshlrev_b32_e32 v68, 16, v155
	v_and_b32_e32 v69, 0xffff0000, v155
	v_lshlrev_b32_e32 v70, 16, v156
	v_and_b32_e32 v71, 0xffff0000, v156
	v_lshlrev_b32_e32 v72, 16, v157
	v_and_b32_e32 v73, 0xffff0000, v157
	v_lshlrev_b32_e32 v74, 16, v158
	v_and_b32_e32 v75, 0xffff0000, v158
	v_lshlrev_b32_e32 v76, 16, v159
	v_and_b32_e32 v77, 0xffff0000, v159
	v_lshlrev_b32_e32 v78, 16, v160
	v_and_b32_e32 v79, 0xffff0000, v160
	v_lshlrev_b32_e32 v80, 16, v161
	v_and_b32_e32 v81, 0xffff0000, v161
	v_mul_f32_e32 v130, v50, v50
	v_fmac_f32_e32 v130, v51, v51
	v_fmac_f32_e32 v130, v52, v52
	v_fmac_f32_e32 v130, v53, v53
	v_fmac_f32_e32 v130, v54, v54
	v_fmac_f32_e32 v130, v55, v55
	v_fmac_f32_e32 v130, v56, v56
	v_fmac_f32_e32 v130, v57, v57
	v_fmac_f32_e32 v130, v58, v58
	v_fmac_f32_e32 v130, v59, v59
	v_fmac_f32_e32 v130, v60, v60
	v_fmac_f32_e32 v130, v61, v61
	v_fmac_f32_e32 v130, v62, v62
	v_fmac_f32_e32 v130, v63, v63
	v_fmac_f32_e32 v130, v64, v64
	v_fmac_f32_e32 v130, v65, v65
	v_fmac_f32_e32 v130, v66, v66
	v_fmac_f32_e32 v130, v67, v67
	v_fmac_f32_e32 v130, v68, v68
	v_fmac_f32_e32 v130, v69, v69
	v_fmac_f32_e32 v130, v70, v70
	v_fmac_f32_e32 v130, v71, v71
	v_fmac_f32_e32 v130, v72, v72
	v_fmac_f32_e32 v130, v73, v73
	v_fmac_f32_e32 v130, v74, v74
	v_fmac_f32_e32 v130, v75, v75
	v_fmac_f32_e32 v130, v76, v76
	v_fmac_f32_e32 v130, v77, v77
	v_fmac_f32_e32 v130, v78, v78
	v_fmac_f32_e32 v130, v79, v79
	v_fmac_f32_e32 v130, v80, v80
	v_fmac_f32_e32 v130, v81, v81
	ds_swizzle_b32 v132, v130 offset:swizzle(SWAP,16)
	s_waitcnt lgkmcnt(0)
	v_add_f32_e32 v130, v130, v132
	v_mov_b32_e32 v132, v130
	s_nop 1
	v_permlane32_swap_b32_e32 v130, v132
	v_add_f32_e32 v130, v130, v132
	v_fmamk_f32 v130, v130, 0x3c000000, v199
	v_rsq_f32_e32 v130, v130
	s_nop 0
	v_mul_f32_e32 v131, s77, v130
	v_mul_f32_e32 v50, v50, v131
	v_mul_f32_e32 v50, v50, v18
	v_mul_f32_e32 v51, v51, v131
	v_mul_f32_e32 v51, v51, v19
	v_mul_f32_e32 v52, v52, v131
	v_mul_f32_e32 v52, v52, v20
	v_mul_f32_e32 v53, v53, v131
	v_mul_f32_e32 v53, v53, v21
	v_mul_f32_e32 v54, v54, v131
	v_mul_f32_e32 v54, v54, v22
	v_mul_f32_e32 v55, v55, v131
	v_mul_f32_e32 v55, v55, v23
	v_mul_f32_e32 v56, v56, v131
	v_mul_f32_e32 v56, v56, v24
	v_mul_f32_e32 v57, v57, v131
	v_mul_f32_e32 v57, v57, v25
	v_mul_f32_e32 v58, v58, v131
	v_mul_f32_e32 v58, v58, v26
	v_mul_f32_e32 v59, v59, v131
	v_mul_f32_e32 v59, v59, v27
	v_mul_f32_e32 v60, v60, v131
	v_mul_f32_e32 v60, v60, v28
	v_mul_f32_e32 v61, v61, v131
	v_mul_f32_e32 v61, v61, v29
	v_mul_f32_e32 v62, v62, v131
	v_mul_f32_e32 v62, v62, v30
	v_mul_f32_e32 v63, v63, v131
	v_mul_f32_e32 v63, v63, v31
	v_mul_f32_e32 v64, v64, v131
	v_mul_f32_e32 v64, v64, v32
	v_mul_f32_e32 v65, v65, v131
	v_mul_f32_e32 v65, v65, v33
	v_mul_f32_e32 v66, v66, v131
	v_mul_f32_e32 v66, v66, v34
	v_mul_f32_e32 v67, v67, v131
	v_mul_f32_e32 v67, v67, v35
	v_mul_f32_e32 v68, v68, v131
	v_mul_f32_e32 v68, v68, v36
	v_mul_f32_e32 v69, v69, v131
	v_mul_f32_e32 v69, v69, v37
	v_mul_f32_e32 v70, v70, v131
	v_mul_f32_e32 v70, v70, v38
	v_mul_f32_e32 v71, v71, v131
	v_mul_f32_e32 v71, v71, v39
	v_mul_f32_e32 v72, v72, v131
	v_mul_f32_e32 v72, v72, v40
	v_mul_f32_e32 v73, v73, v131
	v_mul_f32_e32 v73, v73, v41
	v_mul_f32_e32 v74, v74, v131
	v_mul_f32_e32 v74, v74, v42
	v_mul_f32_e32 v75, v75, v131
	v_mul_f32_e32 v75, v75, v43
	v_mul_f32_e32 v76, v76, v131
	v_mul_f32_e32 v76, v76, v44
	v_mul_f32_e32 v77, v77, v131
	v_mul_f32_e32 v77, v77, v45
	v_mul_f32_e32 v78, v78, v131
	v_mul_f32_e32 v78, v78, v46
	v_mul_f32_e32 v79, v79, v131
	v_mul_f32_e32 v79, v79, v47
	v_mul_f32_e32 v80, v80, v131
	v_mul_f32_e32 v80, v80, v48
	v_mul_f32_e32 v81, v81, v131
	v_mul_f32_e32 v81, v81, v49
	v_mul_f32_e32 v133, v58, v90
	v_mul_f32_e32 v134, v50, v90
	v_fma_f32 v50, v50, v82, -v133
	v_fma_f32 v58, v58, v82, v134
	v_mul_f32_e32 v133, v59, v91
	v_mul_f32_e32 v134, v51, v91
	v_fma_f32 v51, v51, v83, -v133
	v_fma_f32 v59, v59, v83, v134
	v_mul_f32_e32 v133, v60, v92
	v_mul_f32_e32 v134, v52, v92
	v_fma_f32 v52, v52, v84, -v133
	v_fma_f32 v60, v60, v84, v134
	v_mul_f32_e32 v133, v61, v93
	v_mul_f32_e32 v134, v53, v93
	v_fma_f32 v53, v53, v85, -v133
	v_fma_f32 v61, v61, v85, v134
	v_mul_f32_e32 v133, v62, v94
	v_mul_f32_e32 v134, v54, v94
	v_fma_f32 v54, v54, v86, -v133
	v_fma_f32 v62, v62, v86, v134
	v_mul_f32_e32 v133, v63, v95
	v_mul_f32_e32 v134, v55, v95
	v_fma_f32 v55, v55, v87, -v133
	v_fma_f32 v63, v63, v87, v134
	v_mul_f32_e32 v133, v64, v96
	v_mul_f32_e32 v134, v56, v96
	v_fma_f32 v56, v56, v88, -v133
	v_fma_f32 v64, v64, v88, v134
	v_mul_f32_e32 v133, v65, v97
	v_mul_f32_e32 v134, v57, v97
	v_fma_f32 v57, v57, v89, -v133
	v_fma_f32 v65, v65, v89, v134
	v_mul_f32_e32 v133, v74, v106
	v_mul_f32_e32 v134, v66, v106
	v_fma_f32 v66, v66, v98, -v133
	v_fma_f32 v74, v74, v98, v134
	v_mul_f32_e32 v133, v75, v107
	v_mul_f32_e32 v134, v67, v107
	v_fma_f32 v67, v67, v99, -v133
	v_fma_f32 v75, v75, v99, v134
	v_mul_f32_e32 v133, v76, v108
	v_mul_f32_e32 v134, v68, v108
	v_fma_f32 v68, v68, v100, -v133
; #define QF(d, e) __uint_as_float(((unsigned)(unsigned short)qr[d][e]) << 16)
; template <typename TQ> ...
;     ...
;   {
;     float ss = 0.f;
;     ...
; #pragma unroll
;     for (int d0 = 0; d0 < 8; ++d0)
; #pragma unroll
;       for (int e = 0; e < 8; ++e) { const float x = QF(d0, e); ss += x * x; }
;     ss += __shfl_xor(ss, 32);
;     const float rn = (SCALE * 1.4426950408889634f) / sqrtf(ss * (1.0f / 128.0f) + 1e-6f);
;     const int t = trow0 + wid * QBLK + r32; const int prow = t >> 6, pcol = t & 63;
; #pragma unroll
;     for (int hf = 0; hf < 2; ++hf)
; #pragma unroll
;       for (int dd = 0; dd < 2; ++dd) {
;         const int dl = 4 * hf + dd, du = dl + 2;
;         const int f0 = 16 * dd + 8 * hi;
;         const float* cp = rc + (hf ? pcol : prow) * 32 + f0; const float* sp = rsn + (hf ? pcol : prow) * 32 + f0;
;         const float* gl = gq + 16 * dl + 8 * hi; const float* gu = gq + 16 * du + 8 * hi;
;         unsigned wl[4], wu[4];
; #pragma unroll
;         for (int e = 0; e < 8; e += 2) {
;           float o1[2], o2[2];
; #pragma unroll
;           for (int k = 0; k < 2; ++k) { const float x1 = QF(dl, e + k) * rn * gl[e + k], x2 = QF(du, e + k) * rn * gu[e + k]; const float c = cp[e + k], sn = sp[e + k];
;             o1[k] = x1 * c - x2 * sn; o2[k] = x2 * c + x1 * sn; }
;           wl[e >> 1] = cvtpk(o1[0], o1[1]); wu[e >> 1] = cvtpk(o2[0], o2[1]);
;         }
;         u32x4 vl = {wl[0], wl[1], wl[2], wl[3]}, vu = {wu[0], wu[1], wu[2], wu[3]};
;         qr[dl] = *reinterpret_cast<bf16x8*>(&vl); qr[du] = *reinterpret_cast<bf16x8*>(&vu);
;       }
	v_fma_f32 v76, v76, v100, v134
	v_mul_f32_e32 v133, v77, v109
	v_mul_f32_e32 v134, v69, v109
	v_fma_f32 v69, v69, v101, -v133
	v_fma_f32 v77, v77, v101, v134
	v_mul_f32_e32 v133, v78, v110
	v_mul_f32_e32 v134, v70, v110
	v_fma_f32 v70, v70, v102, -v133
	v_fma_f32 v78, v78, v102, v134
	v_mul_f32_e32 v133, v79, v111
	v_mul_f32_e32 v134, v71, v111
	v_fma_f32 v71, v71, v103, -v133
	v_fma_f32 v79, v79, v103, v134
	v_mul_f32_e32 v133, v80, v112
	v_mul_f32_e32 v134, v72, v112
	v_fma_f32 v72, v72, v104, -v133
	v_fma_f32 v80, v80, v104, v134
	v_mul_f32_e32 v133, v81, v113
	v_mul_f32_e32 v134, v73, v113
	v_fma_f32 v73, v73, v105, -v133
	v_fma_f32 v81, v81, v105, v134
	v_cvt_pk_bf16_f32 v146, v50, v51
	v_cvt_pk_bf16_f32 v147, v52, v53
	v_cvt_pk_bf16_f32 v148, v54, v55
	v_cvt_pk_bf16_f32 v149, v56, v57
	v_cvt_pk_bf16_f32 v150, v58, v59
	v_cvt_pk_bf16_f32 v151, v60, v61
	v_cvt_pk_bf16_f32 v152, v62, v63
	v_cvt_pk_bf16_f32 v153, v64, v65
	v_cvt_pk_bf16_f32 v154, v66, v67
	v_cvt_pk_bf16_f32 v155, v68, v69
	v_cvt_pk_bf16_f32 v156, v70, v71
	v_cvt_pk_bf16_f32 v157, v72, v73
	v_cvt_pk_bf16_f32 v158, v74, v75
	v_cvt_pk_bf16_f32 v159, v76, v77
	v_cvt_pk_bf16_f32 v160, v78, v79
	v_cvt_pk_bf16_f32 v161, v80, v81
	v_lshlrev_b32_e32 v50, 16, v162
	v_and_b32_e32 v51, 0xffff0000, v162
	v_lshlrev_b32_e32 v52, 16, v163
	v_and_b32_e32 v53, 0xffff0000, v163
	v_lshlrev_b32_e32 v54, 16, v164
	v_and_b32_e32 v55, 0xffff0000, v164
	v_lshlrev_b32_e32 v56, 16, v165
	v_and_b32_e32 v57, 0xffff0000, v165
	v_lshlrev_b32_e32 v58, 16, v166
	v_and_b32_e32 v59, 0xffff0000, v166
	v_lshlrev_b32_e32 v60, 16, v167
	v_and_b32_e32 v61, 0xffff0000, v167
	v_lshlrev_b32_e32 v62, 16, v168
	v_and_b32_e32 v63, 0xffff0000, v168
	v_lshlrev_b32_e32 v64, 16, v169
	v_and_b32_e32 v65, 0xffff0000, v169
	v_lshlrev_b32_e32 v66, 16, v170
	v_and_b32_e32 v67, 0xffff0000, v170
	v_lshlrev_b32_e32 v68, 16, v171
	v_and_b32_e32 v69, 0xffff0000, v171
	v_lshlrev_b32_e32 v70, 16, v172
	v_and_b32_e32 v71, 0xffff0000, v172
	v_lshlrev_b32_e32 v72, 16, v173
	v_and_b32_e32 v73, 0xffff0000, v173
	v_lshlrev_b32_e32 v74, 16, v174
	v_and_b32_e32 v75, 0xffff0000, v174
	v_lshlrev_b32_e32 v76, 16, v175
	v_and_b32_e32 v77, 0xffff0000, v175
	v_lshlrev_b32_e32 v78, 16, v176
	v_and_b32_e32 v79, 0xffff0000, v176
	v_lshlrev_b32_e32 v80, 16, v177
	v_and_b32_e32 v81, 0xffff0000, v177
	v_mul_f32_e32 v130, v50, v50
	v_fmac_f32_e32 v130, v51, v51
	v_fmac_f32_e32 v130, v52, v52
	v_fmac_f32_e32 v130, v53, v53
	v_fmac_f32_e32 v130, v54, v54
	v_fmac_f32_e32 v130, v55, v55
	v_fmac_f32_e32 v130, v56, v56
	v_fmac_f32_e32 v130, v57, v57
	v_fmac_f32_e32 v130, v58, v58
	v_fmac_f32_e32 v130, v59, v59
	v_fmac_f32_e32 v130, v60, v60
	v_fmac_f32_e32 v130, v61, v61
	v_fmac_f32_e32 v130, v62, v62
	v_fmac_f32_e32 v130, v63, v63
	v_fmac_f32_e32 v130, v64, v64
	v_fmac_f32_e32 v130, v65, v65
	v_fmac_f32_e32 v130, v66, v66
	v_fmac_f32_e32 v130, v67, v67
	v_fmac_f32_e32 v130, v68, v68
	v_fmac_f32_e32 v130, v69, v69
	v_fmac_f32_e32 v130, v70, v70
	v_fmac_f32_e32 v130, v71, v71
	v_fmac_f32_e32 v130, v72, v72
	v_fmac_f32_e32 v130, v73, v73
	v_fmac_f32_e32 v130, v74, v74
	v_fmac_f32_e32 v130, v75, v75
	v_fmac_f32_e32 v130, v76, v76
	v_fmac_f32_e32 v130, v77, v77
	v_fmac_f32_e32 v130, v78, v78
	v_fmac_f32_e32 v130, v79, v79
	v_fmac_f32_e32 v130, v80, v80
	v_fmac_f32_e32 v130, v81, v81
	ds_swizzle_b32 v132, v130 offset:swizzle(SWAP,16)
	s_waitcnt lgkmcnt(0)
	v_add_f32_e32 v130, v130, v132
	v_mov_b32_e32 v132, v130
	s_nop 1
	v_permlane32_swap_b32_e32 v130, v132
	v_add_f32_e32 v130, v130, v132
	v_fmamk_f32 v130, v130, 0x3c000000, v199
	v_rsq_f32_e32 v130, v130
	s_nop 0
	v_mul_f32_e32 v131, s77, v130
	v_mul_f32_e32 v50, v50, v131
	v_mul_f32_e32 v50, v50, v18
	v_mul_f32_e32 v51, v51, v131
	v_mul_f32_e32 v51, v51, v19
	v_mul_f32_e32 v52, v52, v131
	v_mul_f32_e32 v52, v52, v20
	v_mul_f32_e32 v53, v53, v131
	v_mul_f32_e32 v53, v53, v21
	v_mul_f32_e32 v54, v54, v131
	v_mul_f32_e32 v54, v54, v22
	v_mul_f32_e32 v55, v55, v131
	v_mul_f32_e32 v55, v55, v23
	v_mul_f32_e32 v56, v56, v131
	v_mul_f32_e32 v56, v56, v24
	v_mul_f32_e32 v57, v57, v131
	v_mul_f32_e32 v57, v57, v25
	v_mul_f32_e32 v58, v58, v131
	v_mul_f32_e32 v58, v58, v26
	v_mul_f32_e32 v59, v59, v131
	v_mul_f32_e32 v59, v59, v27
	v_mul_f32_e32 v60, v60, v131
	v_mul_f32_e32 v60, v60, v28
	v_mul_f32_e32 v61, v61, v131
	v_mul_f32_e32 v61, v61, v29
	v_mul_f32_e32 v62, v62, v131
	v_mul_f32_e32 v62, v62, v30
	v_mul_f32_e32 v63, v63, v131
	v_mul_f32_e32 v63, v63, v31
	v_mul_f32_e32 v64, v64, v131
	v_mul_f32_e32 v64, v64, v32
	v_mul_f32_e32 v65, v65, v131
	v_mul_f32_e32 v65, v65, v33
	v_mul_f32_e32 v66, v66, v131
	v_mul_f32_e32 v66, v66, v34
	v_mul_f32_e32 v67, v67, v131
	v_mul_f32_e32 v67, v67, v35
	v_mul_f32_e32 v68, v68, v131
	v_mul_f32_e32 v68, v68, v36
	v_mul_f32_e32 v69, v69, v131
	v_mul_f32_e32 v69, v69, v37
	v_mul_f32_e32 v70, v70, v131
	v_mul_f32_e32 v70, v70, v38
	v_mul_f32_e32 v71, v71, v131
	v_mul_f32_e32 v71, v71, v39
	v_mul_f32_e32 v72, v72, v131
	v_mul_f32_e32 v72, v72, v40
	v_mul_f32_e32 v73, v73, v131
	v_mul_f32_e32 v73, v73, v41
	v_mul_f32_e32 v74, v74, v131
	v_mul_f32_e32 v74, v74, v42
	v_mul_f32_e32 v75, v75, v131
	v_mul_f32_e32 v75, v75, v43
	v_mul_f32_e32 v76, v76, v131
	v_mul_f32_e32 v76, v76, v44
	v_mul_f32_e32 v77, v77, v131
	v_mul_f32_e32 v77, v77, v45
	v_mul_f32_e32 v78, v78, v131
	v_mul_f32_e32 v78, v78, v46
	v_mul_f32_e32 v79, v79, v131
	v_mul_f32_e32 v79, v79, v47
	v_mul_f32_e32 v80, v80, v131
	v_mul_f32_e32 v80, v80, v48
	v_mul_f32_e32 v81, v81, v131
	v_mul_f32_e32 v81, v81, v49
	v_mul_f32_e32 v133, v58, v90
	v_mul_f32_e32 v134, v50, v90
	v_fma_f32 v50, v50, v82, -v133
	v_fma_f32 v58, v58, v82, v134
; #define SBAR() __builtin_amdgcn_sched_barrier(0)
; #define QF(d, e) __uint_as_float(((unsigned)(unsigned short)qr[d][e]) << 16)
; __device__ __forceinline__ void qkt(f32x16& p0, f32x16& p1, const bf16* Ks, const bf16x8* qr, int r32, int hi, const f32x16& negm) {
; #pragma unroll
;   for (int d0 = 0; d0 < 8; ++d0) { int cb = (d0 * 16 + hi * 8) * 2;
;     bf16x8 b0 = *reinterpret_cast<const bf16x8*>((const char*)Ks + KSWZ(r32, cb));
;     bf16x8 b1 = *reinterpret_cast<const bf16x8*>((const char*)Ks + KSWZ(32 + r32, cb));
;     if (d0 == 0) { p0 = __builtin_amdgcn_mfma_f32_32x32x16_bf16(b0, qr[0], negm, 0, 0, 0); p1 = __builtin_amdgcn_mfma_f32_32x32x16_bf16(b1, qr[0], negm, 0, 0, 0); }
;     else { p0 = __builtin_amdgcn_mfma_f32_32x32x16_bf16(b0, qr[d0], p0, 0, 0, 0); p1 = __builtin_amdgcn_mfma_f32_32x32x16_bf16(b1, qr[d0], p1, 0, 0, 0); } }
; template <typename TQ> ...
;     ...
;         for (int e = 0; e < 8; e += 2) {
;           float o1[2], o2[2];
; #pragma unroll
;           for (int k = 0; k < 2; ++k) { const float x1 = QF(dl, e + k) * rn * gl[e + k], x2 = QF(du, e + k) * rn * gu[e + k]; const float c = cp[e + k], sn = sp[e + k];
;             o1[k] = x1 * c - x2 * sn; o2[k] = x2 * c + x1 * sn; }
;           wl[e >> 1] = cvtpk(o1[0], o1[1]); wu[e >> 1] = cvtpk(o2[0], o2[1]);
;         }
;         u32x4 vl = {wl[0], wl[1], wl[2], wl[3]}, vu = {wu[0], wu[1], wu[2], wu[3]};
;         qr[dl] = *reinterpret_cast<bf16x8*>(&vl); qr[du] = *reinterpret_cast<bf16x8*>(&vu);
;       }
;   }
;     ...
;   SBAR();
;   f32x16 pA0, pA1, pB0, pB1; bf16x8 pa0, pa1, pa2, pa3; const int NT = seq / KVBLK;
;   f32x16 negm;
; #pragma unroll
;   for (int r = 0; r < 16; ++r) negm[r] = -mC;
;   asm volatile("" : "+v"(negm));
;   asm volatile("s_waitcnt vmcnt(0)" ::: "memory"); SWRITE(0, SE); __syncthreads();
;   qkt(pA0, pA1, K_lds, qr, r32, hi, negm); partialSM(pA0, pA1, mC);
	v_mul_f32_e32 v133, v59, v91
	v_mul_f32_e32 v134, v51, v91
	v_fma_f32 v51, v51, v83, -v133
	v_fma_f32 v59, v59, v83, v134
	v_mul_f32_e32 v133, v60, v92
	v_mul_f32_e32 v134, v52, v92
	v_fma_f32 v52, v52, v84, -v133
	v_fma_f32 v60, v60, v84, v134
	v_mul_f32_e32 v133, v61, v93
	v_mul_f32_e32 v134, v53, v93
	v_fma_f32 v53, v53, v85, -v133
	v_fma_f32 v61, v61, v85, v134
	v_mul_f32_e32 v133, v62, v94
	v_mul_f32_e32 v134, v54, v94
	v_fma_f32 v54, v54, v86, -v133
	v_fma_f32 v62, v62, v86, v134
	v_mul_f32_e32 v133, v63, v95
	v_mul_f32_e32 v134, v55, v95
	v_fma_f32 v55, v55, v87, -v133
	v_fma_f32 v63, v63, v87, v134
	v_mul_f32_e32 v133, v64, v96
	v_mul_f32_e32 v134, v56, v96
	v_fma_f32 v56, v56, v88, -v133
	v_fma_f32 v64, v64, v88, v134
	v_mul_f32_e32 v133, v65, v97
	v_mul_f32_e32 v134, v57, v97
	v_fma_f32 v57, v57, v89, -v133
	v_fma_f32 v65, v65, v89, v134
	v_mul_f32_e32 v133, v74, v122
	v_mul_f32_e32 v134, v66, v122
	v_fma_f32 v66, v66, v114, -v133
	v_fma_f32 v74, v74, v114, v134
	v_mul_f32_e32 v133, v75, v123
	v_mul_f32_e32 v134, v67, v123
	v_fma_f32 v67, v67, v115, -v133
	v_fma_f32 v75, v75, v115, v134
	v_mul_f32_e32 v133, v76, v124
	v_mul_f32_e32 v134, v68, v124
	v_fma_f32 v68, v68, v116, -v133
	v_fma_f32 v76, v76, v116, v134
	v_mul_f32_e32 v133, v77, v125
	v_mul_f32_e32 v134, v69, v125
	v_fma_f32 v69, v69, v117, -v133
	v_fma_f32 v77, v77, v117, v134
	v_mul_f32_e32 v133, v78, v126
	v_mul_f32_e32 v134, v70, v126
	v_fma_f32 v70, v70, v118, -v133
	v_fma_f32 v78, v78, v118, v134
	v_mul_f32_e32 v133, v79, v127
	v_mul_f32_e32 v134, v71, v127
	v_fma_f32 v71, v71, v119, -v133
	v_fma_f32 v79, v79, v119, v134
	v_mul_f32_e32 v133, v80, v128
	v_mul_f32_e32 v134, v72, v128
	v_fma_f32 v72, v72, v120, -v133
	v_fma_f32 v80, v80, v120, v134
	v_mul_f32_e32 v133, v81, v129
	v_mul_f32_e32 v134, v73, v129
	v_fma_f32 v73, v73, v121, -v133
	v_fma_f32 v81, v81, v121, v134
	v_cvt_pk_bf16_f32 v162, v50, v51
	v_cvt_pk_bf16_f32 v163, v52, v53
	v_cvt_pk_bf16_f32 v164, v54, v55
	v_cvt_pk_bf16_f32 v165, v56, v57
	v_cvt_pk_bf16_f32 v166, v58, v59
	v_cvt_pk_bf16_f32 v167, v60, v61
	v_cvt_pk_bf16_f32 v168, v62, v63
	v_cvt_pk_bf16_f32 v169, v64, v65
	v_cvt_pk_bf16_f32 v170, v66, v67
	v_cvt_pk_bf16_f32 v171, v68, v69
	v_cvt_pk_bf16_f32 v172, v70, v71
	v_cvt_pk_bf16_f32 v173, v72, v73
	v_cvt_pk_bf16_f32 v174, v74, v75
	v_cvt_pk_bf16_f32 v175, v76, v77
	v_cvt_pk_bf16_f32 v176, v78, v79
	v_cvt_pk_bf16_f32 v177, v80, v81
	v_mov_b32_e32 v18, 0
	v_mov_b32_e32 v19, 0
	v_mov_b32_e32 v20, 0
	v_mov_b32_e32 v21, 0
	v_mov_b32_e32 v22, 0
	v_mov_b32_e32 v23, 0
	v_mov_b32_e32 v24, 0
	v_mov_b32_e32 v25, 0
	v_mov_b32_e32 v26, 0
	v_mov_b32_e32 v27, 0
	v_mov_b32_e32 v28, 0
	v_mov_b32_e32 v29, 0
	v_mov_b32_e32 v30, 0
	v_mov_b32_e32 v31, 0
	v_mov_b32_e32 v32, 0
	v_mov_b32_e32 v33, 0
	v_mov_b32_e32 v34, 0
	v_mov_b32_e32 v35, 0
	v_mov_b32_e32 v36, 0
	v_mov_b32_e32 v37, 0
	v_mov_b32_e32 v38, 0
	v_mov_b32_e32 v39, 0
	v_mov_b32_e32 v40, 0
	v_mov_b32_e32 v41, 0
	v_mov_b32_e32 v42, 0
	v_mov_b32_e32 v43, 0
	v_mov_b32_e32 v44, 0
	v_mov_b32_e32 v45, 0
	v_mov_b32_e32 v46, 0
	v_mov_b32_e32 v47, 0
	v_mov_b32_e32 v48, 0
	v_mov_b32_e32 v49, 0
	v_mov_b32_e32 v50, 0
	v_mov_b32_e32 v51, 0
	v_mov_b32_e32 v52, 0
	v_mov_b32_e32 v53, 0
	v_mov_b32_e32 v54, 0
	v_mov_b32_e32 v55, 0
	v_mov_b32_e32 v56, 0
	v_mov_b32_e32 v57, 0
	v_mov_b32_e32 v58, 0
	v_mov_b32_e32 v59, 0
	v_mov_b32_e32 v60, 0
	v_mov_b32_e32 v61, 0
	v_mov_b32_e32 v62, 0
	v_mov_b32_e32 v63, 0
	v_mov_b32_e32 v64, 0
	v_mov_b32_e32 v65, 0
	v_mov_b32_e32 v66, 0
	v_mov_b32_e32 v67, 0
	v_mov_b32_e32 v68, 0
	v_mov_b32_e32 v69, 0
	v_mov_b32_e32 v70, 0
	v_mov_b32_e32 v71, 0
	v_mov_b32_e32 v72, 0
	v_mov_b32_e32 v73, 0
	v_mov_b32_e32 v74, 0
	v_mov_b32_e32 v75, 0
	v_mov_b32_e32 v76, 0
	v_mov_b32_e32 v77, 0
	v_mov_b32_e32 v78, 0
	v_mov_b32_e32 v79, 0
	v_mov_b32_e32 v80, 0
	v_mov_b32_e32 v81, 0
	v_mov_b32_e32 v250, 0
	v_mov_b32_e32 v251, 0
	s_barrier
	ds_read_b128 v[178:181], v234 offset:0
	ds_read_b128 v[182:185], v234 offset:4096
	ds_read_b128 v[186:189], v234 offset:8192
	ds_read_b128 v[190:193], v234 offset:12288
	s_waitcnt lgkmcnt(3)
	v_mfma_f32_16x16x32_bf16 v[82:85], v[178:181], v[146:149], v[2:5]
	v_mfma_f32_16x16x32_bf16 v[86:89], v[178:181], v[162:165], v[2:5]
	ds_read_b128 v[178:181], v235 offset:0
	s_waitcnt lgkmcnt(3)
	v_mfma_f32_16x16x32_bf16 v[90:93], v[182:185], v[146:149], v[2:5]
	v_mfma_f32_16x16x32_bf16 v[94:97], v[182:185], v[162:165], v[2:5]
	ds_read_b128 v[182:185], v235 offset:4096
	s_waitcnt lgkmcnt(3)
	v_mfma_f32_16x16x32_bf16 v[98:101], v[186:189], v[146:149], v[2:5]
	v_mfma_f32_16x16x32_bf16 v[102:105], v[186:189], v[162:165], v[2:5]
	ds_read_b128 v[186:189], v235 offset:8192
	s_waitcnt lgkmcnt(3)
	v_mfma_f32_16x16x32_bf16 v[106:109], v[190:193], v[146:149], v[2:5]
	v_mfma_f32_16x16x32_bf16 v[110:113], v[190:193], v[162:165], v[2:5]
	ds_read_b128 v[190:193], v235 offset:12288
	s_waitcnt lgkmcnt(3)
	v_mfma_f32_16x16x32_bf16 v[82:85], v[178:181], v[150:153], v[82:85]
	v_mfma_f32_16x16x32_bf16 v[86:89], v[178:181], v[166:169], v[86:89]
	ds_read_b128 v[178:181], v236 offset:0
	s_waitcnt lgkmcnt(3)
	v_mfma_f32_16x16x32_bf16 v[90:93], v[182:185], v[150:153], v[90:93]
	v_mfma_f32_16x16x32_bf16 v[94:97], v[182:185], v[166:169], v[94:97]
	ds_read_b128 v[182:185], v236 offset:4096
	s_waitcnt lgkmcnt(3)
	v_mfma_f32_16x16x32_bf16 v[98:101], v[186:189], v[150:153], v[98:101]
	v_mfma_f32_16x16x32_bf16 v[102:105], v[186:189], v[166:169], v[102:105]
	ds_read_b128 v[186:189], v236 offset:8192
	s_waitcnt lgkmcnt(3)
	v_mfma_f32_16x16x32_bf16 v[106:109], v[190:193], v[150:153], v[106:109]
	v_mfma_f32_16x16x32_bf16 v[110:113], v[190:193], v[166:169], v[110:113]
	ds_read_b128 v[190:193], v236 offset:12288
	s_waitcnt lgkmcnt(3)
; #define SBAR() __builtin_amdgcn_sched_barrier(0)
; #define SLOAD(i, k0) do { sr_[i].vs0 = St::ld8(&Vh[(long)((k0) + sr) * LDK + sc]); sr_[i].vs1 = St::ld8(&Vh[(long)((k0) + 32 + sr) * LDK + sc]); \
;     sr_[i].ks0 = St::ld8(&Kh[(long)((k0) + sr) * LDK + sc]); sr_[i].ks1 = St::ld8(&Kh[(long)((k0) + 32 + sr) * LDK + sc]); } while (0)
; #define SWAIT() do { if constexpr (SDEPTH == 2) asm volatile("s_waitcnt vmcnt(4)" ::: "memory"); else asm volatile("s_waitcnt vmcnt(0)" ::: "memory"); } while (0)
; template <typename TQ> ...
;     ...
;   qkt(pA0, pA1, K_lds, qr, r32, hi, negm); partialSM(pA0, pA1, mC);
;   SLOAD(SO, KVBLK); if constexpr (SDEPTH == 2) { if (2 < NT) SLOAD(SE, 2 * KVBLK); }
;   SWAIT(); SWRITE(1, SO); __syncthreads();
;   for (int j = 1; j + 1 < NT; j += 2) {
;     SBAR(); SLOAD(SO, (j + SDEPTH) * KVBLK); SBAR();
;     qkt(pB0, pB1, (bf16*)((char*)K_lds + SHM_K), qr, r32, hi, negm);
;     finishSM(pA0, pA1, l_reg, pa0, pa1, pa2, pa3); SBAR();
;     pv_d0(o, vb0, pa0, pa1, pa2, pa3); partialSM(pB0, pB1, mC);
;     __syncthreads(); SWAIT(); SWRITE(0, SE);
;     __syncthreads();
;     SBAR(); if (SDEPTH == 1 || j + 3 < NT) SLOAD(SE, (j + 1 + SDEPTH) * KVBLK); SBAR();
;     qkt(pA0, pA1, K_lds, qr, r32, hi, negm);
;     finishSM(pB0, pB1, l_reg, pa0, pa1, pa2, pa3); SBAR();
;     pv_d0(o, vb0 + (int)SHM_V, pa0, pa1, pa2, pa3); partialSM(pA0, pA1, mC);
	v_mfma_f32_16x16x32_bf16 v[82:85], v[178:181], v[154:157], v[82:85]
	v_mfma_f32_16x16x32_bf16 v[86:89], v[178:181], v[170:173], v[86:89]
	ds_read_b128 v[178:181], v237 offset:0
	s_waitcnt lgkmcnt(3)
	v_mfma_f32_16x16x32_bf16 v[90:93], v[182:185], v[154:157], v[90:93]
	v_mfma_f32_16x16x32_bf16 v[94:97], v[182:185], v[170:173], v[94:97]
	ds_read_b128 v[182:185], v237 offset:4096
	s_waitcnt lgkmcnt(3)
	v_mfma_f32_16x16x32_bf16 v[98:101], v[186:189], v[154:157], v[98:101]
	v_mfma_f32_16x16x32_bf16 v[102:105], v[186:189], v[170:173], v[102:105]
	ds_read_b128 v[186:189], v237 offset:8192
	s_waitcnt lgkmcnt(3)
	v_mfma_f32_16x16x32_bf16 v[106:109], v[190:193], v[154:157], v[106:109]
	v_mfma_f32_16x16x32_bf16 v[110:113], v[190:193], v[170:173], v[110:113]
	ds_read_b128 v[190:193], v237 offset:12288
	s_waitcnt lgkmcnt(3)
	v_mfma_f32_16x16x32_bf16 v[82:85], v[178:181], v[158:161], v[82:85]
	v_mfma_f32_16x16x32_bf16 v[86:89], v[178:181], v[174:177], v[86:89]
	s_waitcnt lgkmcnt(2)
	v_mfma_f32_16x16x32_bf16 v[90:93], v[182:185], v[158:161], v[90:93]
	v_mfma_f32_16x16x32_bf16 v[94:97], v[182:185], v[174:177], v[94:97]
	s_waitcnt lgkmcnt(1)
	v_mfma_f32_16x16x32_bf16 v[98:101], v[186:189], v[158:161], v[98:101]
	v_mfma_f32_16x16x32_bf16 v[102:105], v[186:189], v[174:177], v[102:105]
	s_waitcnt lgkmcnt(0)
	v_mfma_f32_16x16x32_bf16 v[106:109], v[190:193], v[158:161], v[106:109]
	v_mfma_f32_16x16x32_bf16 v[110:113], v[190:193], v[174:177], v[110:113]
	s_nop 7
	v_exp_f32_e32 v82, v82
	v_exp_f32_e32 v83, v83
	v_exp_f32_e32 v84, v84
	v_exp_f32_e32 v85, v85
	v_exp_f32_e32 v86, v86
	v_exp_f32_e32 v87, v87
	v_exp_f32_e32 v88, v88
	v_exp_f32_e32 v89, v89
	v_exp_f32_e32 v90, v90
	v_exp_f32_e32 v91, v91
	v_exp_f32_e32 v92, v92
	v_exp_f32_e32 v93, v93
	v_exp_f32_e32 v94, v94
	v_exp_f32_e32 v95, v95
	v_exp_f32_e32 v96, v96
	v_exp_f32_e32 v97, v97
	v_exp_f32_e32 v98, v98
	v_exp_f32_e32 v99, v99
	v_exp_f32_e32 v100, v100
	v_exp_f32_e32 v101, v101
	v_exp_f32_e32 v102, v102
	v_exp_f32_e32 v103, v103
	v_exp_f32_e32 v104, v104
	v_exp_f32_e32 v105, v105
	v_exp_f32_e32 v106, v106
	v_exp_f32_e32 v107, v107
	v_exp_f32_e32 v108, v108
	v_exp_f32_e32 v109, v109
	v_exp_f32_e32 v110, v110
	v_exp_f32_e32 v111, v111
	v_exp_f32_e32 v112, v112
	v_exp_f32_e32 v113, v113
	ds_read_b128 v[178:181], v234 offset:16384
	ds_read_b128 v[182:185], v234 offset:20480
	ds_read_b128 v[186:189], v234 offset:24576
	ds_read_b128 v[190:193], v234 offset:28672
	s_cmp_lt_u32 s53, 256
	s_cbranch_scc1 .Lattn_noprio
	s_setprio 1
.Lattn_noprio:
	s_mov_b32 s15, 0
.Lattn_loop:
	s_barrier
	s_waitcnt lgkmcnt(3)
	v_mfma_f32_16x16x32_bf16 v[114:117], v[178:181], v[146:149], v[2:5]
	v_add_f32_e32 v250, v82, v250
	s_add_u32 s98, s98, 0x8000
	s_addc_u32 s99, s99, 0
	s_add_u32 s100, s100, 0x8000
	s_addc_u32 s101, s101, 0
	v_mfma_f32_16x16x32_bf16 v[118:121], v[178:181], v[162:165], v[2:5]
	ds_read_b128 v[178:181], v235 offset:16384
	v_add_f32_e32 v250, v83, v250
	v_add_f32_e32 v250, v84, v250
	s_waitcnt lgkmcnt(3)
	v_mfma_f32_16x16x32_bf16 v[122:125], v[182:185], v[146:149], v[2:5]
	v_add_f32_e32 v250, v85, v250
	s_add_u32 m0, s79, 0
	s_nop 0
	global_load_lds_dwordx4 v246, s[98:99]
	v_mfma_f32_16x16x32_bf16 v[126:129], v[182:185], v[162:165], v[2:5]
	ds_read_b128 v[182:185], v235 offset:20480
	v_add_f32_e32 v250, v90, v250
	v_add_f32_e32 v250, v91, v250
	s_waitcnt lgkmcnt(3)
	v_mfma_f32_16x16x32_bf16 v[130:133], v[186:189], v[146:149], v[2:5]
	v_add_f32_e32 v250, v92, v250
	v_mfma_f32_16x16x32_bf16 v[134:137], v[186:189], v[162:165], v[2:5]
	ds_read_b128 v[186:189], v235 offset:24576
	v_add_f32_e32 v250, v93, v250
	v_cvt_pk_bf16_f32 v82, v82, v83
	s_waitcnt lgkmcnt(3)
	v_mfma_f32_16x16x32_bf16 v[138:141], v[190:193], v[146:149], v[2:5]
	v_cvt_pk_bf16_f32 v83, v84, v85
	s_add_u32 m0, s79, 1024
	s_nop 0
	global_load_lds_dwordx4 v247, s[98:99]
	v_mfma_f32_16x16x32_bf16 v[142:145], v[190:193], v[162:165], v[2:5]
	ds_read_b128 v[190:193], v235 offset:28672
	v_cvt_pk_bf16_f32 v84, v90, v91
	v_cvt_pk_bf16_f32 v85, v92, v93
	s_waitcnt lgkmcnt(3)
	v_mfma_f32_16x16x32_bf16 v[114:117], v[178:181], v[150:153], v[114:117]
	v_add_f32_e32 v251, v86, v251
	v_mfma_f32_16x16x32_bf16 v[118:121], v[178:181], v[166:169], v[118:121]
	ds_read_b128 v[178:181], v236 offset:16384
	v_add_f32_e32 v251, v87, v251
	v_add_f32_e32 v251, v88, v251
	s_waitcnt lgkmcnt(3)
	v_mfma_f32_16x16x32_bf16 v[122:125], v[182:185], v[150:153], v[122:125]
	v_add_f32_e32 v251, v89, v251
	s_add_u32 m0, s80, 49152
	s_nop 0
	global_load_lds_dwordx4 v248, s[100:101]
	v_mfma_f32_16x16x32_bf16 v[126:129], v[182:185], v[166:169], v[126:129]
	ds_read_b128 v[182:185], v236 offset:20480
	v_add_f32_e32 v251, v94, v251
	v_add_f32_e32 v251, v95, v251
	s_waitcnt lgkmcnt(3)
	v_mfma_f32_16x16x32_bf16 v[130:133], v[186:189], v[150:153], v[130:133]
	v_add_f32_e32 v251, v96, v251
	v_mfma_f32_16x16x32_bf16 v[134:137], v[186:189], v[166:169], v[134:137]
	ds_read_b128 v[186:189], v236 offset:24576
	v_add_f32_e32 v251, v97, v251
	v_cvt_pk_bf16_f32 v86, v86, v87
	s_waitcnt lgkmcnt(3)
	v_mfma_f32_16x16x32_bf16 v[138:141], v[190:193], v[150:153], v[138:141]
	v_cvt_pk_bf16_f32 v87, v88, v89
	s_add_u32 m0, s80, 50176
	s_nop 0
	global_load_lds_dwordx4 v249, s[100:101]
	v_mfma_f32_16x16x32_bf16 v[142:145], v[190:193], v[166:169], v[142:145]
	ds_read_b128 v[190:193], v236 offset:28672
	v_cvt_pk_bf16_f32 v88, v94, v95
	v_cvt_pk_bf16_f32 v89, v96, v97
	s_waitcnt lgkmcnt(3)
	v_mfma_f32_16x16x32_bf16 v[114:117], v[178:181], v[154:157], v[114:117]
	v_add_f32_e32 v250, v98, v250
	v_mfma_f32_16x16x32_bf16 v[118:121], v[178:181], v[170:173], v[118:121]
	ds_read_b128 v[178:181], v237 offset:16384
	v_add_f32_e32 v250, v99, v250
	v_add_f32_e32 v250, v100, v250
	s_waitcnt lgkmcnt(3)
; #define SBAR() __builtin_amdgcn_sched_barrier(0)
; #define SLOAD(i, k0) do { sr_[i].vs0 = St::ld8(&Vh[(long)((k0) + sr) * LDK + sc]); sr_[i].vs1 = St::ld8(&Vh[(long)((k0) + 32 + sr) * LDK + sc]); \
;     sr_[i].ks0 = St::ld8(&Kh[(long)((k0) + sr) * LDK + sc]); sr_[i].ks1 = St::ld8(&Kh[(long)((k0) + 32 + sr) * LDK + sc]); } while (0)
; #define SWAIT() do { if constexpr (SDEPTH == 2) asm volatile("s_waitcnt vmcnt(4)" ::: "memory"); else asm volatile("s_waitcnt vmcnt(0)" ::: "memory"); } while (0)
; template <typename TQ> ...
;     ...
;   for (int j = 1; j + 1 < NT; j += 2) {
;     SBAR(); SLOAD(SO, (j + SDEPTH) * KVBLK); SBAR();
;     qkt(pB0, pB1, (bf16*)((char*)K_lds + SHM_K), qr, r32, hi, negm);
;     finishSM(pA0, pA1, l_reg, pa0, pa1, pa2, pa3); SBAR();
;     pv_d0(o, vb0, pa0, pa1, pa2, pa3); partialSM(pB0, pB1, mC);
;     __syncthreads(); SWAIT(); SWRITE(0, SE);
;     __syncthreads();
;     SBAR(); if (SDEPTH == 1 || j + 3 < NT) SLOAD(SE, (j + 1 + SDEPTH) * KVBLK); SBAR();
;     qkt(pA0, pA1, K_lds, qr, r32, hi, negm);
;     finishSM(pB0, pB1, l_reg, pa0, pa1, pa2, pa3); SBAR();
;     pv_d0(o, vb0 + (int)SHM_V, pa0, pa1, pa2, pa3); partialSM(pA0, pA1, mC);
;     __syncthreads(); SWAIT(); SWRITE(1, SO);
;     __syncthreads();
;   }
	v_mfma_f32_16x16x32_bf16 v[122:125], v[182:185], v[154:157], v[122:125]
	v_add_f32_e32 v250, v101, v250
	v_mfma_f32_16x16x32_bf16 v[126:129], v[182:185], v[170:173], v[126:129]
	ds_read_b128 v[182:185], v237 offset:20480
	v_add_f32_e32 v250, v106, v250
	v_add_f32_e32 v250, v107, v250
	s_waitcnt lgkmcnt(3)
	v_mfma_f32_16x16x32_bf16 v[130:133], v[186:189], v[154:157], v[130:133]
	v_add_f32_e32 v250, v108, v250
	ds_read_b64_tr_b16 v[202:203], v238 offset:0
	ds_read_b64_tr_b16 v[204:205], v238 offset:4096
	v_mfma_f32_16x16x32_bf16 v[134:137], v[186:189], v[170:173], v[134:137]
	ds_read_b128 v[186:189], v237 offset:24576
	v_add_f32_e32 v250, v109, v250
	v_cvt_pk_bf16_f32 v98, v98, v99
	s_waitcnt lgkmcnt(5)
	v_mfma_f32_16x16x32_bf16 v[138:141], v[190:193], v[154:157], v[138:141]
	v_cvt_pk_bf16_f32 v99, v100, v101
	ds_read_b64_tr_b16 v[206:207], v239 offset:0
	ds_read_b64_tr_b16 v[208:209], v239 offset:4096
	v_mfma_f32_16x16x32_bf16 v[142:145], v[190:193], v[170:173], v[142:145]
	ds_read_b128 v[190:193], v237 offset:28672
	v_cvt_pk_bf16_f32 v100, v106, v107
	v_cvt_pk_bf16_f32 v101, v108, v109
	s_waitcnt lgkmcnt(7)
	v_mfma_f32_16x16x32_bf16 v[114:117], v[178:181], v[158:161], v[114:117]
	v_add_f32_e32 v251, v102, v251
	ds_read_b64_tr_b16 v[210:211], v240 offset:0
	ds_read_b64_tr_b16 v[212:213], v240 offset:4096
	v_mfma_f32_16x16x32_bf16 v[118:121], v[178:181], v[174:177], v[118:121]
	v_add_f32_e32 v251, v103, v251
	v_add_f32_e32 v251, v104, v251
	s_waitcnt lgkmcnt(8)
	v_mfma_f32_16x16x32_bf16 v[122:125], v[182:185], v[158:161], v[122:125]
	v_add_f32_e32 v251, v105, v251
	ds_read_b64_tr_b16 v[214:215], v241 offset:0
	ds_read_b64_tr_b16 v[216:217], v241 offset:4096
	v_mfma_f32_16x16x32_bf16 v[126:129], v[182:185], v[174:177], v[126:129]
	v_add_f32_e32 v251, v110, v251
	v_add_f32_e32 v251, v111, v251
	s_waitcnt lgkmcnt(7)
	v_mfma_f32_16x16x32_bf16 v[130:133], v[186:189], v[158:161], v[130:133]
	v_add_f32_e32 v251, v112, v251
	ds_read_b64_tr_b16 v[218:219], v242 offset:0
	ds_read_b64_tr_b16 v[220:221], v242 offset:4096
	v_mfma_f32_16x16x32_bf16 v[134:137], v[186:189], v[174:177], v[134:137]
	v_add_f32_e32 v251, v113, v251
	v_cvt_pk_bf16_f32 v102, v102, v103
	s_waitcnt lgkmcnt(6)
	v_mfma_f32_16x16x32_bf16 v[138:141], v[190:193], v[158:161], v[138:141]
	v_cvt_pk_bf16_f32 v103, v104, v105
	ds_read_b64_tr_b16 v[222:223], v243 offset:0
	ds_read_b64_tr_b16 v[224:225], v243 offset:4096
	v_mfma_f32_16x16x32_bf16 v[142:145], v[190:193], v[174:177], v[142:145]
	v_cvt_pk_bf16_f32 v104, v110, v111
	v_cvt_pk_bf16_f32 v105, v112, v113
	v_mfma_f32_16x16x32_bf16 v[18:21], v[202:205], v[82:85], v[18:21]
	v_exp_f32_e32 v114, v114
	v_mfma_f32_16x16x32_bf16 v[22:25], v[202:205], v[86:89], v[22:25]
	ds_read_b64_tr_b16 v[202:203], v244 offset:0
	ds_read_b64_tr_b16 v[204:205], v244 offset:4096
	v_exp_f32_e32 v115, v115
	v_mfma_f32_16x16x32_bf16 v[26:29], v[206:209], v[82:85], v[26:29]
	v_exp_f32_e32 v116, v116
	v_mfma_f32_16x16x32_bf16 v[30:33], v[206:209], v[86:89], v[30:33]
	ds_read_b64_tr_b16 v[206:207], v245 offset:0
	ds_read_b64_tr_b16 v[208:209], v245 offset:4096
	v_exp_f32_e32 v117, v117
	s_waitcnt lgkmcnt(10)
	v_mfma_f32_16x16x32_bf16 v[34:37], v[210:213], v[82:85], v[34:37]
	v_exp_f32_e32 v118, v118
	v_mfma_f32_16x16x32_bf16 v[38:41], v[210:213], v[86:89], v[38:41]
	ds_read_b64_tr_b16 v[210:211], v238 offset:8192
	ds_read_b64_tr_b16 v[212:213], v238 offset:12288
	v_exp_f32_e32 v119, v119
	s_waitcnt lgkmcnt(10)
	v_mfma_f32_16x16x32_bf16 v[42:45], v[214:217], v[82:85], v[42:45]
	v_exp_f32_e32 v120, v120
	v_mfma_f32_16x16x32_bf16 v[46:49], v[214:217], v[86:89], v[46:49]
	ds_read_b64_tr_b16 v[214:215], v239 offset:8192
	ds_read_b64_tr_b16 v[216:217], v239 offset:12288
	v_exp_f32_e32 v121, v121
	s_waitcnt lgkmcnt(10)
	v_mfma_f32_16x16x32_bf16 v[50:53], v[218:221], v[82:85], v[50:53]
	v_exp_f32_e32 v122, v122
	v_mfma_f32_16x16x32_bf16 v[54:57], v[218:221], v[86:89], v[54:57]
	ds_read_b64_tr_b16 v[218:219], v240 offset:8192
	ds_read_b64_tr_b16 v[220:221], v240 offset:12288
	v_exp_f32_e32 v123, v123
	s_waitcnt lgkmcnt(10)
	v_mfma_f32_16x16x32_bf16 v[58:61], v[222:225], v[82:85], v[58:61]
	v_exp_f32_e32 v124, v124
	v_mfma_f32_16x16x32_bf16 v[62:65], v[222:225], v[86:89], v[62:65]
	ds_read_b64_tr_b16 v[222:223], v241 offset:8192
	ds_read_b64_tr_b16 v[224:225], v241 offset:12288
	v_exp_f32_e32 v125, v125
	s_waitcnt lgkmcnt(10)
	v_mfma_f32_16x16x32_bf16 v[66:69], v[202:205], v[82:85], v[66:69]
	v_exp_f32_e32 v126, v126
	v_mfma_f32_16x16x32_bf16 v[70:73], v[202:205], v[86:89], v[70:73]
	ds_read_b64_tr_b16 v[202:203], v242 offset:8192
	ds_read_b64_tr_b16 v[204:205], v242 offset:12288
	v_exp_f32_e32 v127, v127
	s_waitcnt lgkmcnt(10)
	v_mfma_f32_16x16x32_bf16 v[74:77], v[206:209], v[82:85], v[74:77]
	v_exp_f32_e32 v128, v128
	v_mfma_f32_16x16x32_bf16 v[78:81], v[206:209], v[86:89], v[78:81]
	ds_read_b64_tr_b16 v[206:207], v243 offset:8192
	ds_read_b64_tr_b16 v[208:209], v243 offset:12288
	v_exp_f32_e32 v129, v129
	s_waitcnt lgkmcnt(10)
	v_mfma_f32_16x16x32_bf16 v[18:21], v[210:213], v[98:101], v[18:21]
	v_exp_f32_e32 v130, v130
	v_mfma_f32_16x16x32_bf16 v[22:25], v[210:213], v[102:105], v[22:25]
	ds_read_b64_tr_b16 v[210:211], v244 offset:8192
	ds_read_b64_tr_b16 v[212:213], v244 offset:12288
	v_exp_f32_e32 v131, v131
	s_waitcnt lgkmcnt(10)
	v_mfma_f32_16x16x32_bf16 v[26:29], v[214:217], v[98:101], v[26:29]
	v_exp_f32_e32 v132, v132
	v_mfma_f32_16x16x32_bf16 v[30:33], v[214:217], v[102:105], v[30:33]
	ds_read_b64_tr_b16 v[214:215], v245 offset:8192
	ds_read_b64_tr_b16 v[216:217], v245 offset:12288
	v_exp_f32_e32 v133, v133
	s_waitcnt lgkmcnt(10)
; #define SBAR() __builtin_amdgcn_sched_barrier(0)
; #define SLOAD(i, k0) do { sr_[i].vs0 = St::ld8(&Vh[(long)((k0) + sr) * LDK + sc]); sr_[i].vs1 = St::ld8(&Vh[(long)((k0) + 32 + sr) * LDK + sc]); \
;     sr_[i].ks0 = St::ld8(&Kh[(long)((k0) + sr) * LDK + sc]); sr_[i].ks1 = St::ld8(&Kh[(long)((k0) + 32 + sr) * LDK + sc]); } while (0)
; #define SWAIT() do { if constexpr (SDEPTH == 2) asm volatile("s_waitcnt vmcnt(4)" ::: "memory"); else asm volatile("s_waitcnt vmcnt(0)" ::: "memory"); } while (0)
; template <typename TQ> ...
;     ...
;   for (int j = 1; j + 1 < NT; j += 2) {
;     SBAR(); SLOAD(SO, (j + SDEPTH) * KVBLK); SBAR();
;     qkt(pB0, pB1, (bf16*)((char*)K_lds + SHM_K), qr, r32, hi, negm);
;     finishSM(pA0, pA1, l_reg, pa0, pa1, pa2, pa3); SBAR();
;     pv_d0(o, vb0, pa0, pa1, pa2, pa3); partialSM(pB0, pB1, mC);
;     __syncthreads(); SWAIT(); SWRITE(0, SE);
;     __syncthreads();
;     SBAR(); if (SDEPTH == 1 || j + 3 < NT) SLOAD(SE, (j + 1 + SDEPTH) * KVBLK); SBAR();
;     qkt(pA0, pA1, K_lds, qr, r32, hi, negm);
;     finishSM(pB0, pB1, l_reg, pa0, pa1, pa2, pa3); SBAR();
;     pv_d0(o, vb0 + (int)SHM_V, pa0, pa1, pa2, pa3); partialSM(pA0, pA1, mC);
;     __syncthreads(); SWAIT(); SWRITE(1, SO);
;     __syncthreads();
;   }
	v_mfma_f32_16x16x32_bf16 v[34:37], v[218:221], v[98:101], v[34:37]
	v_exp_f32_e32 v134, v134
	v_mfma_f32_16x16x32_bf16 v[38:41], v[218:221], v[102:105], v[38:41]
	v_exp_f32_e32 v135, v135
	s_waitcnt lgkmcnt(8)
	v_mfma_f32_16x16x32_bf16 v[42:45], v[222:225], v[98:101], v[42:45]
	v_exp_f32_e32 v136, v136
	v_mfma_f32_16x16x32_bf16 v[46:49], v[222:225], v[102:105], v[46:49]
	v_exp_f32_e32 v137, v137
	s_waitcnt lgkmcnt(6)
	v_mfma_f32_16x16x32_bf16 v[50:53], v[202:205], v[98:101], v[50:53]
	v_exp_f32_e32 v138, v138
	ds_read_b128 v[178:181], v234 offset:32768
	v_mfma_f32_16x16x32_bf16 v[54:57], v[202:205], v[102:105], v[54:57]
	v_exp_f32_e32 v139, v139
	s_waitcnt lgkmcnt(5)
	v_mfma_f32_16x16x32_bf16 v[58:61], v[206:209], v[98:101], v[58:61]
	v_exp_f32_e32 v140, v140
	ds_read_b128 v[182:185], v234 offset:36864
	v_mfma_f32_16x16x32_bf16 v[62:65], v[206:209], v[102:105], v[62:65]
	v_exp_f32_e32 v141, v141
	s_waitcnt lgkmcnt(4)
	v_mfma_f32_16x16x32_bf16 v[66:69], v[210:213], v[98:101], v[66:69]
	v_exp_f32_e32 v142, v142
	ds_read_b128 v[186:189], v234 offset:40960
	v_mfma_f32_16x16x32_bf16 v[70:73], v[210:213], v[102:105], v[70:73]
	v_exp_f32_e32 v143, v143
	s_waitcnt lgkmcnt(3)
	v_mfma_f32_16x16x32_bf16 v[74:77], v[214:217], v[98:101], v[74:77]
	v_exp_f32_e32 v144, v144
	ds_read_b128 v[190:193], v234 offset:45056
	v_mfma_f32_16x16x32_bf16 v[78:81], v[214:217], v[102:105], v[78:81]
	v_exp_f32_e32 v145, v145
	s_waitcnt vmcnt(4)
	s_barrier
	s_waitcnt lgkmcnt(3)
	v_mfma_f32_16x16x32_bf16 v[82:85], v[178:181], v[146:149], v[2:5]
	v_add_f32_e32 v250, v114, v250
	s_add_u32 s98, s98, 0x8000
	s_addc_u32 s99, s99, 0
	s_add_u32 s100, s100, 0x8000
	s_addc_u32 s101, s101, 0
	v_mfma_f32_16x16x32_bf16 v[86:89], v[178:181], v[162:165], v[2:5]
	ds_read_b128 v[178:181], v235 offset:32768
	v_add_f32_e32 v250, v115, v250
	v_add_f32_e32 v250, v116, v250
	s_waitcnt lgkmcnt(3)
	v_mfma_f32_16x16x32_bf16 v[90:93], v[182:185], v[146:149], v[2:5]
	v_add_f32_e32 v250, v117, v250
	s_add_u32 m0, s79, 16384
	s_nop 0
	global_load_lds_dwordx4 v246, s[98:99]
	v_mfma_f32_16x16x32_bf16 v[94:97], v[182:185], v[162:165], v[2:5]
	ds_read_b128 v[182:185], v235 offset:36864
	v_add_f32_e32 v250, v122, v250
	v_add_f32_e32 v250, v123, v250
	s_waitcnt lgkmcnt(3)
	v_mfma_f32_16x16x32_bf16 v[98:101], v[186:189], v[146:149], v[2:5]
	v_add_f32_e32 v250, v124, v250
	v_mfma_f32_16x16x32_bf16 v[102:105], v[186:189], v[162:165], v[2:5]
	ds_read_b128 v[186:189], v235 offset:40960
	v_add_f32_e32 v250, v125, v250
	v_cvt_pk_bf16_f32 v114, v114, v115
	s_waitcnt lgkmcnt(3)
	v_mfma_f32_16x16x32_bf16 v[106:109], v[190:193], v[146:149], v[2:5]
	v_cvt_pk_bf16_f32 v115, v116, v117
	s_add_u32 m0, s79, 17408
	s_nop 0
	global_load_lds_dwordx4 v247, s[98:99]
	v_mfma_f32_16x16x32_bf16 v[110:113], v[190:193], v[162:165], v[2:5]
	ds_read_b128 v[190:193], v235 offset:45056
	v_cvt_pk_bf16_f32 v116, v122, v123
	v_cvt_pk_bf16_f32 v117, v124, v125
	s_waitcnt lgkmcnt(3)
	v_mfma_f32_16x16x32_bf16 v[82:85], v[178:181], v[150:153], v[82:85]
	v_add_f32_e32 v251, v118, v251
	v_mfma_f32_16x16x32_bf16 v[86:89], v[178:181], v[166:169], v[86:89]
	ds_read_b128 v[178:181], v236 offset:32768
	v_add_f32_e32 v251, v119, v251
	v_add_f32_e32 v251, v120, v251
	s_waitcnt lgkmcnt(3)
	v_mfma_f32_16x16x32_bf16 v[90:93], v[182:185], v[150:153], v[90:93]
	v_add_f32_e32 v251, v121, v251
	s_add_u32 m0, s80, 0
	s_nop 0
	global_load_lds_dwordx4 v248, s[100:101]
	v_mfma_f32_16x16x32_bf16 v[94:97], v[182:185], v[166:169], v[94:97]
	ds_read_b128 v[182:185], v236 offset:36864
	v_add_f32_e32 v251, v126, v251
	v_add_f32_e32 v251, v127, v251
	s_waitcnt lgkmcnt(3)
	v_mfma_f32_16x16x32_bf16 v[98:101], v[186:189], v[150:153], v[98:101]
	v_add_f32_e32 v251, v128, v251
	v_mfma_f32_16x16x32_bf16 v[102:105], v[186:189], v[166:169], v[102:105]
	ds_read_b128 v[186:189], v236 offset:40960
	v_add_f32_e32 v251, v129, v251
	v_cvt_pk_bf16_f32 v118, v118, v119
	s_waitcnt lgkmcnt(3)
	v_mfma_f32_16x16x32_bf16 v[106:109], v[190:193], v[150:153], v[106:109]
	v_cvt_pk_bf16_f32 v119, v120, v121
	s_add_u32 m0, s80, 1024
	s_nop 0
	global_load_lds_dwordx4 v249, s[100:101]
	v_mfma_f32_16x16x32_bf16 v[110:113], v[190:193], v[166:169], v[110:113]
	ds_read_b128 v[190:193], v236 offset:45056
	v_cvt_pk_bf16_f32 v120, v126, v127
	v_cvt_pk_bf16_f32 v121, v128, v129
	s_waitcnt lgkmcnt(3)
	v_mfma_f32_16x16x32_bf16 v[82:85], v[178:181], v[154:157], v[82:85]
	v_add_f32_e32 v250, v130, v250
	v_mfma_f32_16x16x32_bf16 v[86:89], v[178:181], v[170:173], v[86:89]
	ds_read_b128 v[178:181], v237 offset:32768
	v_add_f32_e32 v250, v131, v250
	v_add_f32_e32 v250, v132, v250
	s_waitcnt lgkmcnt(3)
	v_mfma_f32_16x16x32_bf16 v[90:93], v[182:185], v[154:157], v[90:93]
	v_add_f32_e32 v250, v133, v250
	v_mfma_f32_16x16x32_bf16 v[94:97], v[182:185], v[170:173], v[94:97]
	ds_read_b128 v[182:185], v237 offset:36864
	v_add_f32_e32 v250, v138, v250
	v_add_f32_e32 v250, v139, v250
	s_waitcnt lgkmcnt(3)
	v_mfma_f32_16x16x32_bf16 v[98:101], v[186:189], v[154:157], v[98:101]
	v_add_f32_e32 v250, v140, v250
	ds_read_b64_tr_b16 v[202:203], v238 offset:16384
	ds_read_b64_tr_b16 v[204:205], v238 offset:20480
	v_mfma_f32_16x16x32_bf16 v[102:105], v[186:189], v[170:173], v[102:105]
	ds_read_b128 v[186:189], v237 offset:40960
	v_add_f32_e32 v250, v141, v250
	v_cvt_pk_bf16_f32 v130, v130, v131
	s_waitcnt lgkmcnt(5)
	v_mfma_f32_16x16x32_bf16 v[106:109], v[190:193], v[154:157], v[106:109]
	v_cvt_pk_bf16_f32 v131, v132, v133
	ds_read_b64_tr_b16 v[206:207], v239 offset:16384
	ds_read_b64_tr_b16 v[208:209], v239 offset:20480
	v_mfma_f32_16x16x32_bf16 v[110:113], v[190:193], v[170:173], v[110:113]
	ds_read_b128 v[190:193], v237 offset:45056
	v_cvt_pk_bf16_f32 v132, v138, v139
	v_cvt_pk_bf16_f32 v133, v140, v141
	s_waitcnt lgkmcnt(7)
; #define SBAR() __builtin_amdgcn_sched_barrier(0)
; #define SLOAD(i, k0) do { sr_[i].vs0 = St::ld8(&Vh[(long)((k0) + sr) * LDK + sc]); sr_[i].vs1 = St::ld8(&Vh[(long)((k0) + 32 + sr) * LDK + sc]); \
;     sr_[i].ks0 = St::ld8(&Kh[(long)((k0) + sr) * LDK + sc]); sr_[i].ks1 = St::ld8(&Kh[(long)((k0) + 32 + sr) * LDK + sc]); } while (0)
; #define SWAIT() do { if constexpr (SDEPTH == 2) asm volatile("s_waitcnt vmcnt(4)" ::: "memory"); else asm volatile("s_waitcnt vmcnt(0)" ::: "memory"); } while (0)
; template <typename TQ> ...
;     ...
;   for (int j = 1; j + 1 < NT; j += 2) {
;     SBAR(); SLOAD(SO, (j + SDEPTH) * KVBLK); SBAR();
;     qkt(pB0, pB1, (bf16*)((char*)K_lds + SHM_K), qr, r32, hi, negm);
;     finishSM(pA0, pA1, l_reg, pa0, pa1, pa2, pa3); SBAR();
;     pv_d0(o, vb0, pa0, pa1, pa2, pa3); partialSM(pB0, pB1, mC);
;     __syncthreads(); SWAIT(); SWRITE(0, SE);
;     __syncthreads();
;     SBAR(); if (SDEPTH == 1 || j + 3 < NT) SLOAD(SE, (j + 1 + SDEPTH) * KVBLK); SBAR();
;     qkt(pA0, pA1, K_lds, qr, r32, hi, negm);
;     finishSM(pB0, pB1, l_reg, pa0, pa1, pa2, pa3); SBAR();
;     pv_d0(o, vb0 + (int)SHM_V, pa0, pa1, pa2, pa3); partialSM(pA0, pA1, mC);
;     __syncthreads(); SWAIT(); SWRITE(1, SO);
;     __syncthreads();
;   }
	v_mfma_f32_16x16x32_bf16 v[82:85], v[178:181], v[158:161], v[82:85]
	v_add_f32_e32 v251, v134, v251
	ds_read_b64_tr_b16 v[210:211], v240 offset:16384
	ds_read_b64_tr_b16 v[212:213], v240 offset:20480
	v_mfma_f32_16x16x32_bf16 v[86:89], v[178:181], v[174:177], v[86:89]
	v_add_f32_e32 v251, v135, v251
	v_add_f32_e32 v251, v136, v251
	s_waitcnt lgkmcnt(8)
	v_mfma_f32_16x16x32_bf16 v[90:93], v[182:185], v[158:161], v[90:93]
	v_add_f32_e32 v251, v137, v251
	ds_read_b64_tr_b16 v[214:215], v241 offset:16384
	ds_read_b64_tr_b16 v[216:217], v241 offset:20480
	v_mfma_f32_16x16x32_bf16 v[94:97], v[182:185], v[174:177], v[94:97]
	v_add_f32_e32 v251, v142, v251
	v_add_f32_e32 v251, v143, v251
	s_waitcnt lgkmcnt(7)
	v_mfma_f32_16x16x32_bf16 v[98:101], v[186:189], v[158:161], v[98:101]
	v_add_f32_e32 v251, v144, v251
	ds_read_b64_tr_b16 v[218:219], v242 offset:16384
	ds_read_b64_tr_b16 v[220:221], v242 offset:20480
	v_mfma_f32_16x16x32_bf16 v[102:105], v[186:189], v[174:177], v[102:105]
	v_add_f32_e32 v251, v145, v251
	v_cvt_pk_bf16_f32 v134, v134, v135
	s_waitcnt lgkmcnt(6)
	v_mfma_f32_16x16x32_bf16 v[106:109], v[190:193], v[158:161], v[106:109]
	v_cvt_pk_bf16_f32 v135, v136, v137
	ds_read_b64_tr_b16 v[222:223], v243 offset:16384
	ds_read_b64_tr_b16 v[224:225], v243 offset:20480
	v_mfma_f32_16x16x32_bf16 v[110:113], v[190:193], v[174:177], v[110:113]
	v_cvt_pk_bf16_f32 v136, v142, v143
	v_cvt_pk_bf16_f32 v137, v144, v145
	v_mfma_f32_16x16x32_bf16 v[18:21], v[202:205], v[114:117], v[18:21]
	v_exp_f32_e32 v82, v82
	v_mfma_f32_16x16x32_bf16 v[22:25], v[202:205], v[118:121], v[22:25]
	ds_read_b64_tr_b16 v[202:203], v244 offset:16384
	ds_read_b64_tr_b16 v[204:205], v244 offset:20480
	v_exp_f32_e32 v83, v83
	v_mfma_f32_16x16x32_bf16 v[26:29], v[206:209], v[114:117], v[26:29]
	v_exp_f32_e32 v84, v84
	v_mfma_f32_16x16x32_bf16 v[30:33], v[206:209], v[118:121], v[30:33]
	ds_read_b64_tr_b16 v[206:207], v245 offset:16384
	ds_read_b64_tr_b16 v[208:209], v245 offset:20480
	v_exp_f32_e32 v85, v85
	s_waitcnt lgkmcnt(10)
	v_mfma_f32_16x16x32_bf16 v[34:37], v[210:213], v[114:117], v[34:37]
	v_exp_f32_e32 v86, v86
	v_mfma_f32_16x16x32_bf16 v[38:41], v[210:213], v[118:121], v[38:41]
	ds_read_b64_tr_b16 v[210:211], v238 offset:24576
	ds_read_b64_tr_b16 v[212:213], v238 offset:28672
	v_exp_f32_e32 v87, v87
	s_waitcnt lgkmcnt(10)
	v_mfma_f32_16x16x32_bf16 v[42:45], v[214:217], v[114:117], v[42:45]
	v_exp_f32_e32 v88, v88
	v_mfma_f32_16x16x32_bf16 v[46:49], v[214:217], v[118:121], v[46:49]
	ds_read_b64_tr_b16 v[214:215], v239 offset:24576
	ds_read_b64_tr_b16 v[216:217], v239 offset:28672
	v_exp_f32_e32 v89, v89
	s_waitcnt lgkmcnt(10)
	v_mfma_f32_16x16x32_bf16 v[50:53], v[218:221], v[114:117], v[50:53]
	v_exp_f32_e32 v90, v90
	v_mfma_f32_16x16x32_bf16 v[54:57], v[218:221], v[118:121], v[54:57]
	ds_read_b64_tr_b16 v[218:219], v240 offset:24576
	ds_read_b64_tr_b16 v[220:221], v240 offset:28672
	v_exp_f32_e32 v91, v91
	s_waitcnt lgkmcnt(10)
	v_mfma_f32_16x16x32_bf16 v[58:61], v[222:225], v[114:117], v[58:61]
	v_exp_f32_e32 v92, v92
	v_mfma_f32_16x16x32_bf16 v[62:65], v[222:225], v[118:121], v[62:65]
	ds_read_b64_tr_b16 v[222:223], v241 offset:24576
	ds_read_b64_tr_b16 v[224:225], v241 offset:28672
	v_exp_f32_e32 v93, v93
	s_waitcnt lgkmcnt(10)
	v_mfma_f32_16x16x32_bf16 v[66:69], v[202:205], v[114:117], v[66:69]
	v_exp_f32_e32 v94, v94
	v_mfma_f32_16x16x32_bf16 v[70:73], v[202:205], v[118:121], v[70:73]
	ds_read_b64_tr_b16 v[202:203], v242 offset:24576
	ds_read_b64_tr_b16 v[204:205], v242 offset:28672
	v_exp_f32_e32 v95, v95
	s_waitcnt lgkmcnt(10)
	v_mfma_f32_16x16x32_bf16 v[74:77], v[206:209], v[114:117], v[74:77]
	v_exp_f32_e32 v96, v96
	v_mfma_f32_16x16x32_bf16 v[78:81], v[206:209], v[118:121], v[78:81]
	ds_read_b64_tr_b16 v[206:207], v243 offset:24576
	ds_read_b64_tr_b16 v[208:209], v243 offset:28672
	v_exp_f32_e32 v97, v97
	s_waitcnt lgkmcnt(10)
	v_mfma_f32_16x16x32_bf16 v[18:21], v[210:213], v[130:133], v[18:21]
	v_exp_f32_e32 v98, v98
	v_mfma_f32_16x16x32_bf16 v[22:25], v[210:213], v[134:137], v[22:25]
	ds_read_b64_tr_b16 v[210:211], v244 offset:24576
	ds_read_b64_tr_b16 v[212:213], v244 offset:28672
	v_exp_f32_e32 v99, v99
	s_waitcnt lgkmcnt(10)
	v_mfma_f32_16x16x32_bf16 v[26:29], v[214:217], v[130:133], v[26:29]
	v_exp_f32_e32 v100, v100
	v_mfma_f32_16x16x32_bf16 v[30:33], v[214:217], v[134:137], v[30:33]
	ds_read_b64_tr_b16 v[214:215], v245 offset:24576
	ds_read_b64_tr_b16 v[216:217], v245 offset:28672
	v_exp_f32_e32 v101, v101
	s_waitcnt lgkmcnt(10)
	v_mfma_f32_16x16x32_bf16 v[34:37], v[218:221], v[130:133], v[34:37]
	v_exp_f32_e32 v102, v102
	v_mfma_f32_16x16x32_bf16 v[38:41], v[218:221], v[134:137], v[38:41]
	v_exp_f32_e32 v103, v103
	s_waitcnt lgkmcnt(8)
	v_mfma_f32_16x16x32_bf16 v[42:45], v[222:225], v[130:133], v[42:45]
	v_exp_f32_e32 v104, v104
	v_mfma_f32_16x16x32_bf16 v[46:49], v[222:225], v[134:137], v[46:49]
	v_exp_f32_e32 v105, v105
	s_waitcnt lgkmcnt(6)
	v_mfma_f32_16x16x32_bf16 v[50:53], v[202:205], v[130:133], v[50:53]
	v_exp_f32_e32 v106, v106
	ds_read_b128 v[178:181], v234 offset:49152
	v_mfma_f32_16x16x32_bf16 v[54:57], v[202:205], v[134:137], v[54:57]
	v_exp_f32_e32 v107, v107
	s_waitcnt lgkmcnt(5)
	v_mfma_f32_16x16x32_bf16 v[58:61], v[206:209], v[130:133], v[58:61]
	v_exp_f32_e32 v108, v108
	ds_read_b128 v[182:185], v234 offset:53248
	v_mfma_f32_16x16x32_bf16 v[62:65], v[206:209], v[134:137], v[62:65]
	v_exp_f32_e32 v109, v109
	s_waitcnt lgkmcnt(4)
	v_mfma_f32_16x16x32_bf16 v[66:69], v[210:213], v[130:133], v[66:69]
	v_exp_f32_e32 v110, v110
	ds_read_b128 v[186:189], v234 offset:57344
	v_mfma_f32_16x16x32_bf16 v[70:73], v[210:213], v[134:137], v[70:73]
	v_exp_f32_e32 v111, v111
	s_waitcnt lgkmcnt(3)
	v_mfma_f32_16x16x32_bf16 v[74:77], v[214:217], v[130:133], v[74:77]
	v_exp_f32_e32 v112, v112
	ds_read_b128 v[190:193], v234 offset:61440
	v_mfma_f32_16x16x32_bf16 v[78:81], v[214:217], v[134:137], v[78:81]
	v_exp_f32_e32 v113, v113
	s_waitcnt vmcnt(4)
	s_barrier
; #define SBAR() __builtin_amdgcn_sched_barrier(0)
; #define SLOAD(i, k0) do { sr_[i].vs0 = St::ld8(&Vh[(long)((k0) + sr) * LDK + sc]); sr_[i].vs1 = St::ld8(&Vh[(long)((k0) + 32 + sr) * LDK + sc]); \
;     sr_[i].ks0 = St::ld8(&Kh[(long)((k0) + sr) * LDK + sc]); sr_[i].ks1 = St::ld8(&Kh[(long)((k0) + 32 + sr) * LDK + sc]); } while (0)
; #define SWAIT() do { if constexpr (SDEPTH == 2) asm volatile("s_waitcnt vmcnt(4)" ::: "memory"); else asm volatile("s_waitcnt vmcnt(0)" ::: "memory"); } while (0)
; template <typename TQ> ...
;     ...
;   for (int j = 1; j + 1 < NT; j += 2) {
;     SBAR(); SLOAD(SO, (j + SDEPTH) * KVBLK); SBAR();
;     qkt(pB0, pB1, (bf16*)((char*)K_lds + SHM_K), qr, r32, hi, negm);
;     finishSM(pA0, pA1, l_reg, pa0, pa1, pa2, pa3); SBAR();
;     pv_d0(o, vb0, pa0, pa1, pa2, pa3); partialSM(pB0, pB1, mC);
;     __syncthreads(); SWAIT(); SWRITE(0, SE);
;     __syncthreads();
;     SBAR(); if (SDEPTH == 1 || j + 3 < NT) SLOAD(SE, (j + 1 + SDEPTH) * KVBLK); SBAR();
;     qkt(pA0, pA1, K_lds, qr, r32, hi, negm);
;     finishSM(pB0, pB1, l_reg, pa0, pa1, pa2, pa3); SBAR();
;     pv_d0(o, vb0 + (int)SHM_V, pa0, pa1, pa2, pa3); partialSM(pA0, pA1, mC);
;     __syncthreads(); SWAIT(); SWRITE(1, SO);
;     __syncthreads();
;   }
	s_waitcnt lgkmcnt(3)
	v_mfma_f32_16x16x32_bf16 v[114:117], v[178:181], v[146:149], v[2:5]
	v_add_f32_e32 v250, v82, v250
	s_add_u32 s98, s98, 0x8000
	s_addc_u32 s99, s99, 0
	s_add_u32 s100, s100, 0x8000
	s_addc_u32 s101, s101, 0
	v_mfma_f32_16x16x32_bf16 v[118:121], v[178:181], v[162:165], v[2:5]
	ds_read_b128 v[178:181], v235 offset:49152
	v_add_f32_e32 v250, v83, v250
	v_add_f32_e32 v250, v84, v250
	s_waitcnt lgkmcnt(3)
	v_mfma_f32_16x16x32_bf16 v[122:125], v[182:185], v[146:149], v[2:5]
	v_add_f32_e32 v250, v85, v250
	s_add_u32 m0, s79, 32768
	s_nop 0
	global_load_lds_dwordx4 v246, s[98:99]
	v_mfma_f32_16x16x32_bf16 v[126:129], v[182:185], v[162:165], v[2:5]
	ds_read_b128 v[182:185], v235 offset:53248
	v_add_f32_e32 v250, v90, v250
	v_add_f32_e32 v250, v91, v250
	s_waitcnt lgkmcnt(3)
	v_mfma_f32_16x16x32_bf16 v[130:133], v[186:189], v[146:149], v[2:5]
	v_add_f32_e32 v250, v92, v250
	v_mfma_f32_16x16x32_bf16 v[134:137], v[186:189], v[162:165], v[2:5]
	ds_read_b128 v[186:189], v235 offset:57344
	v_add_f32_e32 v250, v93, v250
	v_cvt_pk_bf16_f32 v82, v82, v83
	s_waitcnt lgkmcnt(3)
	v_mfma_f32_16x16x32_bf16 v[138:141], v[190:193], v[146:149], v[2:5]
	v_cvt_pk_bf16_f32 v83, v84, v85
	s_add_u32 m0, s79, 33792
	s_nop 0
	global_load_lds_dwordx4 v247, s[98:99]
	v_mfma_f32_16x16x32_bf16 v[142:145], v[190:193], v[162:165], v[2:5]
	ds_read_b128 v[190:193], v235 offset:61440
	v_cvt_pk_bf16_f32 v84, v90, v91
	v_cvt_pk_bf16_f32 v85, v92, v93
	s_waitcnt lgkmcnt(3)
	v_mfma_f32_16x16x32_bf16 v[114:117], v[178:181], v[150:153], v[114:117]
	v_add_f32_e32 v251, v86, v251
	v_mfma_f32_16x16x32_bf16 v[118:121], v[178:181], v[166:169], v[118:121]
	ds_read_b128 v[178:181], v236 offset:49152
	v_add_f32_e32 v251, v87, v251
	v_add_f32_e32 v251, v88, v251
	s_waitcnt lgkmcnt(3)
	v_mfma_f32_16x16x32_bf16 v[122:125], v[182:185], v[150:153], v[122:125]
	v_add_f32_e32 v251, v89, v251
	s_add_u32 m0, s80, 16384
	s_nop 0
	global_load_lds_dwordx4 v248, s[100:101]
	v_mfma_f32_16x16x32_bf16 v[126:129], v[182:185], v[166:169], v[126:129]
	ds_read_b128 v[182:185], v236 offset:53248
	v_add_f32_e32 v251, v94, v251
	v_add_f32_e32 v251, v95, v251
	s_waitcnt lgkmcnt(3)
	v_mfma_f32_16x16x32_bf16 v[130:133], v[186:189], v[150:153], v[130:133]
	v_add_f32_e32 v251, v96, v251
	v_mfma_f32_16x16x32_bf16 v[134:137], v[186:189], v[166:169], v[134:137]
	ds_read_b128 v[186:189], v236 offset:57344
	v_add_f32_e32 v251, v97, v251
	v_cvt_pk_bf16_f32 v86, v86, v87
	s_waitcnt lgkmcnt(3)
	v_mfma_f32_16x16x32_bf16 v[138:141], v[190:193], v[150:153], v[138:141]
	v_cvt_pk_bf16_f32 v87, v88, v89
	s_add_u32 m0, s80, 17408
	s_nop 0
	global_load_lds_dwordx4 v249, s[100:101]
	v_mfma_f32_16x16x32_bf16 v[142:145], v[190:193], v[166:169], v[142:145]
	ds_read_b128 v[190:193], v236 offset:61440
	v_cvt_pk_bf16_f32 v88, v94, v95
	v_cvt_pk_bf16_f32 v89, v96, v97
	s_waitcnt lgkmcnt(3)
	v_mfma_f32_16x16x32_bf16 v[114:117], v[178:181], v[154:157], v[114:117]
	v_add_f32_e32 v250, v98, v250
	v_mfma_f32_16x16x32_bf16 v[118:121], v[178:181], v[170:173], v[118:121]
	ds_read_b128 v[178:181], v237 offset:49152
	v_add_f32_e32 v250, v99, v250
	v_add_f32_e32 v250, v100, v250
	s_waitcnt lgkmcnt(3)
	v_mfma_f32_16x16x32_bf16 v[122:125], v[182:185], v[154:157], v[122:125]
	v_add_f32_e32 v250, v101, v250
	v_mfma_f32_16x16x32_bf16 v[126:129], v[182:185], v[170:173], v[126:129]
	ds_read_b128 v[182:185], v237 offset:53248
	v_add_f32_e32 v250, v106, v250
	v_add_f32_e32 v250, v107, v250
	s_waitcnt lgkmcnt(3)
	v_mfma_f32_16x16x32_bf16 v[130:133], v[186:189], v[154:157], v[130:133]
	v_add_f32_e32 v250, v108, v250
	ds_read_b64_tr_b16 v[202:203], v238 offset:32768
	ds_read_b64_tr_b16 v[204:205], v238 offset:36864
	v_mfma_f32_16x16x32_bf16 v[134:137], v[186:189], v[170:173], v[134:137]
	ds_read_b128 v[186:189], v237 offset:57344
	v_add_f32_e32 v250, v109, v250
	v_cvt_pk_bf16_f32 v98, v98, v99
	s_waitcnt lgkmcnt(5)
	v_mfma_f32_16x16x32_bf16 v[138:141], v[190:193], v[154:157], v[138:141]
	v_cvt_pk_bf16_f32 v99, v100, v101
	ds_read_b64_tr_b16 v[206:207], v239 offset:32768
	ds_read_b64_tr_b16 v[208:209], v239 offset:36864
	v_mfma_f32_16x16x32_bf16 v[142:145], v[190:193], v[170:173], v[142:145]
	ds_read_b128 v[190:193], v237 offset:61440
	v_cvt_pk_bf16_f32 v100, v106, v107
	v_cvt_pk_bf16_f32 v101, v108, v109
	s_waitcnt lgkmcnt(7)
	v_mfma_f32_16x16x32_bf16 v[114:117], v[178:181], v[158:161], v[114:117]
	v_add_f32_e32 v251, v102, v251
	ds_read_b64_tr_b16 v[210:211], v240 offset:32768
	ds_read_b64_tr_b16 v[212:213], v240 offset:36864
	v_mfma_f32_16x16x32_bf16 v[118:121], v[178:181], v[174:177], v[118:121]
	v_add_f32_e32 v251, v103, v251
	v_add_f32_e32 v251, v104, v251
	s_waitcnt lgkmcnt(8)
	v_mfma_f32_16x16x32_bf16 v[122:125], v[182:185], v[158:161], v[122:125]
	v_add_f32_e32 v251, v105, v251
	ds_read_b64_tr_b16 v[214:215], v241 offset:32768
	ds_read_b64_tr_b16 v[216:217], v241 offset:36864
	v_mfma_f32_16x16x32_bf16 v[126:129], v[182:185], v[174:177], v[126:129]
	v_add_f32_e32 v251, v110, v251
	v_add_f32_e32 v251, v111, v251
	s_waitcnt lgkmcnt(7)
	v_mfma_f32_16x16x32_bf16 v[130:133], v[186:189], v[158:161], v[130:133]
	v_add_f32_e32 v251, v112, v251
	ds_read_b64_tr_b16 v[218:219], v242 offset:32768
	ds_read_b64_tr_b16 v[220:221], v242 offset:36864
	v_mfma_f32_16x16x32_bf16 v[134:137], v[186:189], v[174:177], v[134:137]
	v_add_f32_e32 v251, v113, v251
	v_cvt_pk_bf16_f32 v102, v102, v103
	s_waitcnt lgkmcnt(6)
; #define SBAR() __builtin_amdgcn_sched_barrier(0)
; #define SLOAD(i, k0) do { sr_[i].vs0 = St::ld8(&Vh[(long)((k0) + sr) * LDK + sc]); sr_[i].vs1 = St::ld8(&Vh[(long)((k0) + 32 + sr) * LDK + sc]); \
;     sr_[i].ks0 = St::ld8(&Kh[(long)((k0) + sr) * LDK + sc]); sr_[i].ks1 = St::ld8(&Kh[(long)((k0) + 32 + sr) * LDK + sc]); } while (0)
; #define SWAIT() do { if constexpr (SDEPTH == 2) asm volatile("s_waitcnt vmcnt(4)" ::: "memory"); else asm volatile("s_waitcnt vmcnt(0)" ::: "memory"); } while (0)
; template <typename TQ> ...
;     ...
;   for (int j = 1; j + 1 < NT; j += 2) {
;     SBAR(); SLOAD(SO, (j + SDEPTH) * KVBLK); SBAR();
;     qkt(pB0, pB1, (bf16*)((char*)K_lds + SHM_K), qr, r32, hi, negm);
;     finishSM(pA0, pA1, l_reg, pa0, pa1, pa2, pa3); SBAR();
;     pv_d0(o, vb0, pa0, pa1, pa2, pa3); partialSM(pB0, pB1, mC);
;     __syncthreads(); SWAIT(); SWRITE(0, SE);
;     __syncthreads();
;     SBAR(); if (SDEPTH == 1 || j + 3 < NT) SLOAD(SE, (j + 1 + SDEPTH) * KVBLK); SBAR();
;     qkt(pA0, pA1, K_lds, qr, r32, hi, negm);
;     finishSM(pB0, pB1, l_reg, pa0, pa1, pa2, pa3); SBAR();
;     pv_d0(o, vb0 + (int)SHM_V, pa0, pa1, pa2, pa3); partialSM(pA0, pA1, mC);
;     __syncthreads(); SWAIT(); SWRITE(1, SO);
;     __syncthreads();
;   }
	v_mfma_f32_16x16x32_bf16 v[138:141], v[190:193], v[158:161], v[138:141]
	v_cvt_pk_bf16_f32 v103, v104, v105
	ds_read_b64_tr_b16 v[222:223], v243 offset:32768
	ds_read_b64_tr_b16 v[224:225], v243 offset:36864
	v_mfma_f32_16x16x32_bf16 v[142:145], v[190:193], v[174:177], v[142:145]
	v_cvt_pk_bf16_f32 v104, v110, v111
	v_cvt_pk_bf16_f32 v105, v112, v113
	v_mfma_f32_16x16x32_bf16 v[18:21], v[202:205], v[82:85], v[18:21]
	v_exp_f32_e32 v114, v114
	v_mfma_f32_16x16x32_bf16 v[22:25], v[202:205], v[86:89], v[22:25]
	ds_read_b64_tr_b16 v[202:203], v244 offset:32768
	ds_read_b64_tr_b16 v[204:205], v244 offset:36864
	v_exp_f32_e32 v115, v115
	v_mfma_f32_16x16x32_bf16 v[26:29], v[206:209], v[82:85], v[26:29]
	v_exp_f32_e32 v116, v116
	v_mfma_f32_16x16x32_bf16 v[30:33], v[206:209], v[86:89], v[30:33]
	ds_read_b64_tr_b16 v[206:207], v245 offset:32768
	ds_read_b64_tr_b16 v[208:209], v245 offset:36864
	v_exp_f32_e32 v117, v117
	s_waitcnt lgkmcnt(10)
	v_mfma_f32_16x16x32_bf16 v[34:37], v[210:213], v[82:85], v[34:37]
	v_exp_f32_e32 v118, v118
	v_mfma_f32_16x16x32_bf16 v[38:41], v[210:213], v[86:89], v[38:41]
	ds_read_b64_tr_b16 v[210:211], v238 offset:40960
	ds_read_b64_tr_b16 v[212:213], v238 offset:45056
	v_exp_f32_e32 v119, v119
	s_waitcnt lgkmcnt(10)
	v_mfma_f32_16x16x32_bf16 v[42:45], v[214:217], v[82:85], v[42:45]
	v_exp_f32_e32 v120, v120
	v_mfma_f32_16x16x32_bf16 v[46:49], v[214:217], v[86:89], v[46:49]
	ds_read_b64_tr_b16 v[214:215], v239 offset:40960
	ds_read_b64_tr_b16 v[216:217], v239 offset:45056
	v_exp_f32_e32 v121, v121
	s_waitcnt lgkmcnt(10)
	v_mfma_f32_16x16x32_bf16 v[50:53], v[218:221], v[82:85], v[50:53]
	v_exp_f32_e32 v122, v122
	v_mfma_f32_16x16x32_bf16 v[54:57], v[218:221], v[86:89], v[54:57]
	ds_read_b64_tr_b16 v[218:219], v240 offset:40960
	ds_read_b64_tr_b16 v[220:221], v240 offset:45056
	v_exp_f32_e32 v123, v123
	s_waitcnt lgkmcnt(10)
	v_mfma_f32_16x16x32_bf16 v[58:61], v[222:225], v[82:85], v[58:61]
	v_exp_f32_e32 v124, v124
	v_mfma_f32_16x16x32_bf16 v[62:65], v[222:225], v[86:89], v[62:65]
	ds_read_b64_tr_b16 v[222:223], v241 offset:40960
	ds_read_b64_tr_b16 v[224:225], v241 offset:45056
	v_exp_f32_e32 v125, v125
	s_waitcnt lgkmcnt(10)
	v_mfma_f32_16x16x32_bf16 v[66:69], v[202:205], v[82:85], v[66:69]
	v_exp_f32_e32 v126, v126
	v_mfma_f32_16x16x32_bf16 v[70:73], v[202:205], v[86:89], v[70:73]
	ds_read_b64_tr_b16 v[202:203], v242 offset:40960
	ds_read_b64_tr_b16 v[204:205], v242 offset:45056
	v_exp_f32_e32 v127, v127
	s_waitcnt lgkmcnt(10)
	v_mfma_f32_16x16x32_bf16 v[74:77], v[206:209], v[82:85], v[74:77]
	v_exp_f32_e32 v128, v128
	v_mfma_f32_16x16x32_bf16 v[78:81], v[206:209], v[86:89], v[78:81]
	ds_read_b64_tr_b16 v[206:207], v243 offset:40960
	ds_read_b64_tr_b16 v[208:209], v243 offset:45056
	v_exp_f32_e32 v129, v129
	s_waitcnt lgkmcnt(10)
	v_mfma_f32_16x16x32_bf16 v[18:21], v[210:213], v[98:101], v[18:21]
	v_exp_f32_e32 v130, v130
	v_mfma_f32_16x16x32_bf16 v[22:25], v[210:213], v[102:105], v[22:25]
	ds_read_b64_tr_b16 v[210:211], v244 offset:40960
	ds_read_b64_tr_b16 v[212:213], v244 offset:45056
	v_exp_f32_e32 v131, v131
	s_waitcnt lgkmcnt(10)
	v_mfma_f32_16x16x32_bf16 v[26:29], v[214:217], v[98:101], v[26:29]
	v_exp_f32_e32 v132, v132
	v_mfma_f32_16x16x32_bf16 v[30:33], v[214:217], v[102:105], v[30:33]
	ds_read_b64_tr_b16 v[214:215], v245 offset:40960
	ds_read_b64_tr_b16 v[216:217], v245 offset:45056
	v_exp_f32_e32 v133, v133
	s_waitcnt lgkmcnt(10)
	v_mfma_f32_16x16x32_bf16 v[34:37], v[218:221], v[98:101], v[34:37]
	v_exp_f32_e32 v134, v134
	v_mfma_f32_16x16x32_bf16 v[38:41], v[218:221], v[102:105], v[38:41]
	v_exp_f32_e32 v135, v135
	s_waitcnt lgkmcnt(8)
	v_mfma_f32_16x16x32_bf16 v[42:45], v[222:225], v[98:101], v[42:45]
	v_exp_f32_e32 v136, v136
	v_mfma_f32_16x16x32_bf16 v[46:49], v[222:225], v[102:105], v[46:49]
	v_exp_f32_e32 v137, v137
	s_waitcnt lgkmcnt(6)
	v_mfma_f32_16x16x32_bf16 v[50:53], v[202:205], v[98:101], v[50:53]
	v_exp_f32_e32 v138, v138
	ds_read_b128 v[178:181], v234 offset:0
	v_mfma_f32_16x16x32_bf16 v[54:57], v[202:205], v[102:105], v[54:57]
	v_exp_f32_e32 v139, v139
	s_waitcnt lgkmcnt(5)
	v_mfma_f32_16x16x32_bf16 v[58:61], v[206:209], v[98:101], v[58:61]
	v_exp_f32_e32 v140, v140
	ds_read_b128 v[182:185], v234 offset:4096
	v_mfma_f32_16x16x32_bf16 v[62:65], v[206:209], v[102:105], v[62:65]
	v_exp_f32_e32 v141, v141
	s_waitcnt lgkmcnt(4)
	v_mfma_f32_16x16x32_bf16 v[66:69], v[210:213], v[98:101], v[66:69]
	v_exp_f32_e32 v142, v142
	ds_read_b128 v[186:189], v234 offset:8192
	v_mfma_f32_16x16x32_bf16 v[70:73], v[210:213], v[102:105], v[70:73]
	v_exp_f32_e32 v143, v143
	s_waitcnt lgkmcnt(3)
	v_mfma_f32_16x16x32_bf16 v[74:77], v[214:217], v[98:101], v[74:77]
	v_exp_f32_e32 v144, v144
	ds_read_b128 v[190:193], v234 offset:12288
	v_mfma_f32_16x16x32_bf16 v[78:81], v[214:217], v[102:105], v[78:81]
	v_exp_f32_e32 v145, v145
	s_waitcnt vmcnt(4)
	s_barrier
; #define SBAR() __builtin_amdgcn_sched_barrier(0)
; #define SLOAD(i, k0) do { sr_[i].vs0 = St::ld8(&Vh[(long)((k0) + sr) * LDK + sc]); sr_[i].vs1 = St::ld8(&Vh[(long)((k0) + 32 + sr) * LDK + sc]); \
;     sr_[i].ks0 = St::ld8(&Kh[(long)((k0) + sr) * LDK + sc]); sr_[i].ks1 = St::ld8(&Kh[(long)((k0) + 32 + sr) * LDK + sc]); } while (0)
; #define SWAIT() do { if constexpr (SDEPTH == 2) asm volatile("s_waitcnt vmcnt(4)" ::: "memory"); else asm volatile("s_waitcnt vmcnt(0)" ::: "memory"); } while (0)
; template <typename TQ> ...
;     ...
;   for (int j = 1; j + 1 < NT; j += 2) {
;     SBAR(); SLOAD(SO, (j + SDEPTH) * KVBLK); SBAR();
;     qkt(pB0, pB1, (bf16*)((char*)K_lds + SHM_K), qr, r32, hi, negm);
;     finishSM(pA0, pA1, l_reg, pa0, pa1, pa2, pa3); SBAR();
;     pv_d0(o, vb0, pa0, pa1, pa2, pa3); partialSM(pB0, pB1, mC);
;     __syncthreads(); SWAIT(); SWRITE(0, SE);
;     __syncthreads();
;     SBAR(); if (SDEPTH == 1 || j + 3 < NT) SLOAD(SE, (j + 1 + SDEPTH) * KVBLK); SBAR();
;     qkt(pA0, pA1, K_lds, qr, r32, hi, negm);
;     finishSM(pB0, pB1, l_reg, pa0, pa1, pa2, pa3); SBAR();
;     pv_d0(o, vb0 + (int)SHM_V, pa0, pa1, pa2, pa3); partialSM(pA0, pA1, mC);
;     __syncthreads(); SWAIT(); SWRITE(1, SO);
;     __syncthreads();
;   }
	s_waitcnt lgkmcnt(3)
	v_mfma_f32_16x16x32_bf16 v[82:85], v[178:181], v[146:149], v[2:5]
	v_add_f32_e32 v250, v114, v250
	s_add_u32 s98, s98, 0x8000
	s_addc_u32 s99, s99, 0
	s_add_u32 s100, s100, 0x8000
	s_addc_u32 s101, s101, 0
	v_mfma_f32_16x16x32_bf16 v[86:89], v[178:181], v[162:165], v[2:5]
	ds_read_b128 v[178:181], v235 offset:0
	v_add_f32_e32 v250, v115, v250
	v_add_f32_e32 v250, v116, v250
	s_waitcnt lgkmcnt(3)
	v_mfma_f32_16x16x32_bf16 v[90:93], v[182:185], v[146:149], v[2:5]
	v_add_f32_e32 v250, v117, v250
	s_add_u32 m0, s79, 49152
	s_nop 0
	global_load_lds_dwordx4 v246, s[98:99]
	v_mfma_f32_16x16x32_bf16 v[94:97], v[182:185], v[162:165], v[2:5]
	ds_read_b128 v[182:185], v235 offset:4096
	v_add_f32_e32 v250, v122, v250
	v_add_f32_e32 v250, v123, v250
	s_waitcnt lgkmcnt(3)
	v_mfma_f32_16x16x32_bf16 v[98:101], v[186:189], v[146:149], v[2:5]
	v_add_f32_e32 v250, v124, v250
	v_mfma_f32_16x16x32_bf16 v[102:105], v[186:189], v[162:165], v[2:5]
	ds_read_b128 v[186:189], v235 offset:8192
	v_add_f32_e32 v250, v125, v250
	v_cvt_pk_bf16_f32 v114, v114, v115
	s_waitcnt lgkmcnt(3)
	v_mfma_f32_16x16x32_bf16 v[106:109], v[190:193], v[146:149], v[2:5]
	v_cvt_pk_bf16_f32 v115, v116, v117
	s_add_u32 m0, s79, 50176
	s_nop 0
	global_load_lds_dwordx4 v247, s[98:99]
	v_mfma_f32_16x16x32_bf16 v[110:113], v[190:193], v[162:165], v[2:5]
	ds_read_b128 v[190:193], v235 offset:12288
	v_cvt_pk_bf16_f32 v116, v122, v123
	v_cvt_pk_bf16_f32 v117, v124, v125
	s_waitcnt lgkmcnt(3)
	v_mfma_f32_16x16x32_bf16 v[82:85], v[178:181], v[150:153], v[82:85]
	v_add_f32_e32 v251, v118, v251
	v_mfma_f32_16x16x32_bf16 v[86:89], v[178:181], v[166:169], v[86:89]
	ds_read_b128 v[178:181], v236 offset:0
	v_add_f32_e32 v251, v119, v251
	v_add_f32_e32 v251, v120, v251
	s_waitcnt lgkmcnt(3)
	v_mfma_f32_16x16x32_bf16 v[90:93], v[182:185], v[150:153], v[90:93]
	v_add_f32_e32 v251, v121, v251
	s_add_u32 m0, s80, 32768
	s_nop 0
	global_load_lds_dwordx4 v248, s[100:101]
	v_mfma_f32_16x16x32_bf16 v[94:97], v[182:185], v[166:169], v[94:97]
	ds_read_b128 v[182:185], v236 offset:4096
	v_add_f32_e32 v251, v126, v251
	v_add_f32_e32 v251, v127, v251
	s_waitcnt lgkmcnt(3)
	v_mfma_f32_16x16x32_bf16 v[98:101], v[186:189], v[150:153], v[98:101]
	v_add_f32_e32 v251, v128, v251
	v_mfma_f32_16x16x32_bf16 v[102:105], v[186:189], v[166:169], v[102:105]
	ds_read_b128 v[186:189], v236 offset:8192
	v_add_f32_e32 v251, v129, v251
	v_cvt_pk_bf16_f32 v118, v118, v119
	s_waitcnt lgkmcnt(3)
	v_mfma_f32_16x16x32_bf16 v[106:109], v[190:193], v[150:153], v[106:109]
	v_cvt_pk_bf16_f32 v119, v120, v121
	s_add_u32 m0, s80, 33792
	s_nop 0
	global_load_lds_dwordx4 v249, s[100:101]
	v_mfma_f32_16x16x32_bf16 v[110:113], v[190:193], v[166:169], v[110:113]
	ds_read_b128 v[190:193], v236 offset:12288
	v_cvt_pk_bf16_f32 v120, v126, v127
	v_cvt_pk_bf16_f32 v121, v128, v129
	s_waitcnt lgkmcnt(3)
	v_mfma_f32_16x16x32_bf16 v[82:85], v[178:181], v[154:157], v[82:85]
	v_add_f32_e32 v250, v130, v250
	v_mfma_f32_16x16x32_bf16 v[86:89], v[178:181], v[170:173], v[86:89]
	ds_read_b128 v[178:181], v237 offset:0
	v_add_f32_e32 v250, v131, v250
	v_add_f32_e32 v250, v132, v250
	s_waitcnt lgkmcnt(3)
	v_mfma_f32_16x16x32_bf16 v[90:93], v[182:185], v[154:157], v[90:93]
	v_add_f32_e32 v250, v133, v250
	v_mfma_f32_16x16x32_bf16 v[94:97], v[182:185], v[170:173], v[94:97]
	ds_read_b128 v[182:185], v237 offset:4096
	v_add_f32_e32 v250, v138, v250
	v_add_f32_e32 v250, v139, v250
	s_waitcnt lgkmcnt(3)
	v_mfma_f32_16x16x32_bf16 v[98:101], v[186:189], v[154:157], v[98:101]
	v_add_f32_e32 v250, v140, v250
	ds_read_b64_tr_b16 v[202:203], v238 offset:49152
	ds_read_b64_tr_b16 v[204:205], v238 offset:53248
	v_mfma_f32_16x16x32_bf16 v[102:105], v[186:189], v[170:173], v[102:105]
	ds_read_b128 v[186:189], v237 offset:8192
	v_add_f32_e32 v250, v141, v250
	v_cvt_pk_bf16_f32 v130, v130, v131
	s_waitcnt lgkmcnt(5)
	v_mfma_f32_16x16x32_bf16 v[106:109], v[190:193], v[154:157], v[106:109]
	v_cvt_pk_bf16_f32 v131, v132, v133
	ds_read_b64_tr_b16 v[206:207], v239 offset:49152
	ds_read_b64_tr_b16 v[208:209], v239 offset:53248
	v_mfma_f32_16x16x32_bf16 v[110:113], v[190:193], v[170:173], v[110:113]
	ds_read_b128 v[190:193], v237 offset:12288
	v_cvt_pk_bf16_f32 v132, v138, v139
	v_cvt_pk_bf16_f32 v133, v140, v141
	s_waitcnt lgkmcnt(7)
	v_mfma_f32_16x16x32_bf16 v[82:85], v[178:181], v[158:161], v[82:85]
	v_add_f32_e32 v251, v134, v251
	ds_read_b64_tr_b16 v[210:211], v240 offset:49152
	ds_read_b64_tr_b16 v[212:213], v240 offset:53248
	v_mfma_f32_16x16x32_bf16 v[86:89], v[178:181], v[174:177], v[86:89]
	v_add_f32_e32 v251, v135, v251
	v_add_f32_e32 v251, v136, v251
	s_waitcnt lgkmcnt(8)
	v_mfma_f32_16x16x32_bf16 v[90:93], v[182:185], v[158:161], v[90:93]
	v_add_f32_e32 v251, v137, v251
	ds_read_b64_tr_b16 v[214:215], v241 offset:49152
	ds_read_b64_tr_b16 v[216:217], v241 offset:53248
	v_mfma_f32_16x16x32_bf16 v[94:97], v[182:185], v[174:177], v[94:97]
	v_add_f32_e32 v251, v142, v251
	v_add_f32_e32 v251, v143, v251
	s_waitcnt lgkmcnt(7)
	v_mfma_f32_16x16x32_bf16 v[98:101], v[186:189], v[158:161], v[98:101]
	v_add_f32_e32 v251, v144, v251
	ds_read_b64_tr_b16 v[218:219], v242 offset:49152
	ds_read_b64_tr_b16 v[220:221], v242 offset:53248
	v_mfma_f32_16x16x32_bf16 v[102:105], v[186:189], v[174:177], v[102:105]
	v_add_f32_e32 v251, v145, v251
	v_cvt_pk_bf16_f32 v134, v134, v135
	s_waitcnt lgkmcnt(6)
; #define SBAR() __builtin_amdgcn_sched_barrier(0)
; #define SLOAD(i, k0) do { sr_[i].vs0 = St::ld8(&Vh[(long)((k0) + sr) * LDK + sc]); sr_[i].vs1 = St::ld8(&Vh[(long)((k0) + 32 + sr) * LDK + sc]); \
;     sr_[i].ks0 = St::ld8(&Kh[(long)((k0) + sr) * LDK + sc]); sr_[i].ks1 = St::ld8(&Kh[(long)((k0) + 32 + sr) * LDK + sc]); } while (0)
; #define SWAIT() do { if constexpr (SDEPTH == 2) asm volatile("s_waitcnt vmcnt(4)" ::: "memory"); else asm volatile("s_waitcnt vmcnt(0)" ::: "memory"); } while (0)
; template <typename TQ> ...
;     ...
;   for (int j = 1; j + 1 < NT; j += 2) {
;     SBAR(); SLOAD(SO, (j + SDEPTH) * KVBLK); SBAR();
;     qkt(pB0, pB1, (bf16*)((char*)K_lds + SHM_K), qr, r32, hi, negm);
;     finishSM(pA0, pA1, l_reg, pa0, pa1, pa2, pa3); SBAR();
;     pv_d0(o, vb0, pa0, pa1, pa2, pa3); partialSM(pB0, pB1, mC);
;     __syncthreads(); SWAIT(); SWRITE(0, SE);
;     __syncthreads();
;     SBAR(); if (SDEPTH == 1 || j + 3 < NT) SLOAD(SE, (j + 1 + SDEPTH) * KVBLK); SBAR();
;     qkt(pA0, pA1, K_lds, qr, r32, hi, negm);
;     finishSM(pB0, pB1, l_reg, pa0, pa1, pa2, pa3); SBAR();
;     pv_d0(o, vb0 + (int)SHM_V, pa0, pa1, pa2, pa3); partialSM(pA0, pA1, mC);
;     __syncthreads(); SWAIT(); SWRITE(1, SO);
;     __syncthreads();
;   }
	v_mfma_f32_16x16x32_bf16 v[106:109], v[190:193], v[158:161], v[106:109]
	v_cvt_pk_bf16_f32 v135, v136, v137
	ds_read_b64_tr_b16 v[222:223], v243 offset:49152
	ds_read_b64_tr_b16 v[224:225], v243 offset:53248
	v_mfma_f32_16x16x32_bf16 v[110:113], v[190:193], v[174:177], v[110:113]
	v_cvt_pk_bf16_f32 v136, v142, v143
	v_cvt_pk_bf16_f32 v137, v144, v145
	v_mfma_f32_16x16x32_bf16 v[18:21], v[202:205], v[114:117], v[18:21]
	v_exp_f32_e32 v82, v82
	v_mfma_f32_16x16x32_bf16 v[22:25], v[202:205], v[118:121], v[22:25]
	ds_read_b64_tr_b16 v[202:203], v244 offset:49152
	ds_read_b64_tr_b16 v[204:205], v244 offset:53248
	v_exp_f32_e32 v83, v83
	v_mfma_f32_16x16x32_bf16 v[26:29], v[206:209], v[114:117], v[26:29]
	v_exp_f32_e32 v84, v84
	v_mfma_f32_16x16x32_bf16 v[30:33], v[206:209], v[118:121], v[30:33]
	ds_read_b64_tr_b16 v[206:207], v245 offset:49152
	ds_read_b64_tr_b16 v[208:209], v245 offset:53248
	v_exp_f32_e32 v85, v85
	s_waitcnt lgkmcnt(10)
	v_mfma_f32_16x16x32_bf16 v[34:37], v[210:213], v[114:117], v[34:37]
	v_exp_f32_e32 v86, v86
	v_mfma_f32_16x16x32_bf16 v[38:41], v[210:213], v[118:121], v[38:41]
	ds_read_b64_tr_b16 v[210:211], v238 offset:57344
	ds_read_b64_tr_b16 v[212:213], v238 offset:61440
	v_exp_f32_e32 v87, v87
	s_waitcnt lgkmcnt(10)
	v_mfma_f32_16x16x32_bf16 v[42:45], v[214:217], v[114:117], v[42:45]
	v_exp_f32_e32 v88, v88
	v_mfma_f32_16x16x32_bf16 v[46:49], v[214:217], v[118:121], v[46:49]
	ds_read_b64_tr_b16 v[214:215], v239 offset:57344
	ds_read_b64_tr_b16 v[216:217], v239 offset:61440
	v_exp_f32_e32 v89, v89
	s_waitcnt lgkmcnt(10)
	v_mfma_f32_16x16x32_bf16 v[50:53], v[218:221], v[114:117], v[50:53]
	v_exp_f32_e32 v90, v90
	v_mfma_f32_16x16x32_bf16 v[54:57], v[218:221], v[118:121], v[54:57]
	ds_read_b64_tr_b16 v[218:219], v240 offset:57344
	ds_read_b64_tr_b16 v[220:221], v240 offset:61440
	v_exp_f32_e32 v91, v91
	s_waitcnt lgkmcnt(10)
	v_mfma_f32_16x16x32_bf16 v[58:61], v[222:225], v[114:117], v[58:61]
	v_exp_f32_e32 v92, v92
	v_mfma_f32_16x16x32_bf16 v[62:65], v[222:225], v[118:121], v[62:65]
	ds_read_b64_tr_b16 v[222:223], v241 offset:57344
	ds_read_b64_tr_b16 v[224:225], v241 offset:61440
	v_exp_f32_e32 v93, v93
	s_waitcnt lgkmcnt(10)
	v_mfma_f32_16x16x32_bf16 v[66:69], v[202:205], v[114:117], v[66:69]
	v_exp_f32_e32 v94, v94
	v_mfma_f32_16x16x32_bf16 v[70:73], v[202:205], v[118:121], v[70:73]
	ds_read_b64_tr_b16 v[202:203], v242 offset:57344
	ds_read_b64_tr_b16 v[204:205], v242 offset:61440
	v_exp_f32_e32 v95, v95
	s_waitcnt lgkmcnt(10)
	v_mfma_f32_16x16x32_bf16 v[74:77], v[206:209], v[114:117], v[74:77]
	v_exp_f32_e32 v96, v96
	v_mfma_f32_16x16x32_bf16 v[78:81], v[206:209], v[118:121], v[78:81]
	ds_read_b64_tr_b16 v[206:207], v243 offset:57344
	ds_read_b64_tr_b16 v[208:209], v243 offset:61440
	v_exp_f32_e32 v97, v97
	s_waitcnt lgkmcnt(10)
	v_mfma_f32_16x16x32_bf16 v[18:21], v[210:213], v[130:133], v[18:21]
	v_exp_f32_e32 v98, v98
	v_mfma_f32_16x16x32_bf16 v[22:25], v[210:213], v[134:137], v[22:25]
	ds_read_b64_tr_b16 v[210:211], v244 offset:57344
	ds_read_b64_tr_b16 v[212:213], v244 offset:61440
	v_exp_f32_e32 v99, v99
	s_waitcnt lgkmcnt(10)
	v_mfma_f32_16x16x32_bf16 v[26:29], v[214:217], v[130:133], v[26:29]
	v_exp_f32_e32 v100, v100
	v_mfma_f32_16x16x32_bf16 v[30:33], v[214:217], v[134:137], v[30:33]
	ds_read_b64_tr_b16 v[214:215], v245 offset:57344
	ds_read_b64_tr_b16 v[216:217], v245 offset:61440
	v_exp_f32_e32 v101, v101
	s_waitcnt lgkmcnt(10)
	v_mfma_f32_16x16x32_bf16 v[34:37], v[218:221], v[130:133], v[34:37]
	v_exp_f32_e32 v102, v102
	v_mfma_f32_16x16x32_bf16 v[38:41], v[218:221], v[134:137], v[38:41]
	v_exp_f32_e32 v103, v103
	s_waitcnt lgkmcnt(8)
	v_mfma_f32_16x16x32_bf16 v[42:45], v[222:225], v[130:133], v[42:45]
	v_exp_f32_e32 v104, v104
	v_mfma_f32_16x16x32_bf16 v[46:49], v[222:225], v[134:137], v[46:49]
	v_exp_f32_e32 v105, v105
	s_waitcnt lgkmcnt(6)
	v_mfma_f32_16x16x32_bf16 v[50:53], v[202:205], v[130:133], v[50:53]
	v_exp_f32_e32 v106, v106
	ds_read_b128 v[178:181], v234 offset:16384
	v_mfma_f32_16x16x32_bf16 v[54:57], v[202:205], v[134:137], v[54:57]
	v_exp_f32_e32 v107, v107
	s_waitcnt lgkmcnt(5)
	v_mfma_f32_16x16x32_bf16 v[58:61], v[206:209], v[130:133], v[58:61]
	v_exp_f32_e32 v108, v108
	ds_read_b128 v[182:185], v234 offset:20480
	v_mfma_f32_16x16x32_bf16 v[62:65], v[206:209], v[134:137], v[62:65]
	v_exp_f32_e32 v109, v109
	s_waitcnt lgkmcnt(4)
	v_mfma_f32_16x16x32_bf16 v[66:69], v[210:213], v[130:133], v[66:69]
	v_exp_f32_e32 v110, v110
	ds_read_b128 v[186:189], v234 offset:24576
	v_mfma_f32_16x16x32_bf16 v[70:73], v[210:213], v[134:137], v[70:73]
	v_exp_f32_e32 v111, v111
	s_waitcnt lgkmcnt(3)
	v_mfma_f32_16x16x32_bf16 v[74:77], v[214:217], v[130:133], v[74:77]
	v_exp_f32_e32 v112, v112
	ds_read_b128 v[190:193], v234 offset:28672
	v_mfma_f32_16x16x32_bf16 v[78:81], v[214:217], v[134:137], v[78:81]
	v_exp_f32_e32 v113, v113
	s_waitcnt vmcnt(4)
	s_add_i32 s15, s15, 1
	s_cmp_lt_u32 s15, 32
	s_cbranch_scc1 .Lattn_loop
	s_barrier
; #define SBAR() __builtin_amdgcn_sched_barrier(0)
; template <typename TQ> ...
;     ...
;   SBAR(); qkt(pB0, pB1, (bf16*)((char*)K_lds + SHM_K), qr, r32, hi, negm);
;   finishSM(pA0, pA1, l_reg, pa0, pa1, pa2, pa3); SBAR();
;   pv_d0(o, vb0, pa0, pa1, pa2, pa3); partialSM(pB0, pB1, mC);
;   __syncthreads();
;   finishSM(pB0, pB1, l_reg, pa0, pa1, pa2, pa3); SBAR();
;   pv_d0(o, vb0 + (int)SHM_V, pa0, pa1, pa2, pa3);
	s_waitcnt lgkmcnt(3)
	v_mfma_f32_16x16x32_bf16 v[114:117], v[178:181], v[146:149], v[2:5]
	v_add_f32_e32 v250, v82, v250
	s_add_u32 s98, s98, 0x8000
	s_addc_u32 s99, s99, 0
	s_add_u32 s100, s100, 0x8000
	s_addc_u32 s101, s101, 0
	v_mfma_f32_16x16x32_bf16 v[118:121], v[178:181], v[162:165], v[2:5]
	ds_read_b128 v[178:181], v235 offset:16384
	v_add_f32_e32 v250, v83, v250
	v_add_f32_e32 v250, v84, v250
	s_waitcnt lgkmcnt(3)
	v_mfma_f32_16x16x32_bf16 v[122:125], v[182:185], v[146:149], v[2:5]
	v_add_f32_e32 v250, v85, v250
	s_add_u32 m0, s80, 49152
	s_nop 0
	global_load_lds_dwordx4 v248, s[100:101]
	v_mfma_f32_16x16x32_bf16 v[126:129], v[182:185], v[162:165], v[2:5]
	ds_read_b128 v[182:185], v235 offset:20480
	v_add_f32_e32 v250, v90, v250
	v_add_f32_e32 v250, v91, v250
	s_waitcnt lgkmcnt(3)
	v_mfma_f32_16x16x32_bf16 v[130:133], v[186:189], v[146:149], v[2:5]
	v_add_f32_e32 v250, v92, v250
	v_mfma_f32_16x16x32_bf16 v[134:137], v[186:189], v[162:165], v[2:5]
	ds_read_b128 v[186:189], v235 offset:24576
	v_add_f32_e32 v250, v93, v250
	v_cvt_pk_bf16_f32 v82, v82, v83
	s_waitcnt lgkmcnt(3)
	v_mfma_f32_16x16x32_bf16 v[138:141], v[190:193], v[146:149], v[2:5]
	v_cvt_pk_bf16_f32 v83, v84, v85
	s_add_u32 m0, s80, 50176
	s_nop 0
	global_load_lds_dwordx4 v249, s[100:101]
	v_mfma_f32_16x16x32_bf16 v[142:145], v[190:193], v[162:165], v[2:5]
	ds_read_b128 v[190:193], v235 offset:28672
	v_cvt_pk_bf16_f32 v84, v90, v91
	v_cvt_pk_bf16_f32 v85, v92, v93
	s_waitcnt lgkmcnt(3)
	v_mfma_f32_16x16x32_bf16 v[114:117], v[178:181], v[150:153], v[114:117]
	v_add_f32_e32 v251, v86, v251
	v_mfma_f32_16x16x32_bf16 v[118:121], v[178:181], v[166:169], v[118:121]
	ds_read_b128 v[178:181], v236 offset:16384
	v_add_f32_e32 v251, v87, v251
	v_add_f32_e32 v251, v88, v251
	s_waitcnt lgkmcnt(3)
	v_mfma_f32_16x16x32_bf16 v[122:125], v[182:185], v[150:153], v[122:125]
	v_add_f32_e32 v251, v89, v251
	v_mfma_f32_16x16x32_bf16 v[126:129], v[182:185], v[166:169], v[126:129]
	ds_read_b128 v[182:185], v236 offset:20480
	v_add_f32_e32 v251, v94, v251
	v_add_f32_e32 v251, v95, v251
	s_waitcnt lgkmcnt(3)
	v_mfma_f32_16x16x32_bf16 v[130:133], v[186:189], v[150:153], v[130:133]
	v_add_f32_e32 v251, v96, v251
	v_mfma_f32_16x16x32_bf16 v[134:137], v[186:189], v[166:169], v[134:137]
	ds_read_b128 v[186:189], v236 offset:24576
	v_add_f32_e32 v251, v97, v251
	v_cvt_pk_bf16_f32 v86, v86, v87
	s_waitcnt lgkmcnt(3)
	v_mfma_f32_16x16x32_bf16 v[138:141], v[190:193], v[150:153], v[138:141]
	v_cvt_pk_bf16_f32 v87, v88, v89
	v_mfma_f32_16x16x32_bf16 v[142:145], v[190:193], v[166:169], v[142:145]
	ds_read_b128 v[190:193], v236 offset:28672
	v_cvt_pk_bf16_f32 v88, v94, v95
	v_cvt_pk_bf16_f32 v89, v96, v97
	s_waitcnt lgkmcnt(3)
	v_mfma_f32_16x16x32_bf16 v[114:117], v[178:181], v[154:157], v[114:117]
	v_add_f32_e32 v250, v98, v250
	v_mfma_f32_16x16x32_bf16 v[118:121], v[178:181], v[170:173], v[118:121]
	ds_read_b128 v[178:181], v237 offset:16384
	v_add_f32_e32 v250, v99, v250
	v_add_f32_e32 v250, v100, v250
	s_waitcnt lgkmcnt(3)
	v_mfma_f32_16x16x32_bf16 v[122:125], v[182:185], v[154:157], v[122:125]
	v_add_f32_e32 v250, v101, v250
	v_mfma_f32_16x16x32_bf16 v[126:129], v[182:185], v[170:173], v[126:129]
	ds_read_b128 v[182:185], v237 offset:20480
	v_add_f32_e32 v250, v106, v250
	v_add_f32_e32 v250, v107, v250
	s_waitcnt lgkmcnt(3)
	v_mfma_f32_16x16x32_bf16 v[130:133], v[186:189], v[154:157], v[130:133]
	v_add_f32_e32 v250, v108, v250
	ds_read_b64_tr_b16 v[202:203], v238 offset:0
	ds_read_b64_tr_b16 v[204:205], v238 offset:4096
	v_mfma_f32_16x16x32_bf16 v[134:137], v[186:189], v[170:173], v[134:137]
	ds_read_b128 v[186:189], v237 offset:24576
	v_add_f32_e32 v250, v109, v250
	v_cvt_pk_bf16_f32 v98, v98, v99
	s_waitcnt lgkmcnt(5)
	v_mfma_f32_16x16x32_bf16 v[138:141], v[190:193], v[154:157], v[138:141]
	v_cvt_pk_bf16_f32 v99, v100, v101
	ds_read_b64_tr_b16 v[206:207], v239 offset:0
	ds_read_b64_tr_b16 v[208:209], v239 offset:4096
	v_mfma_f32_16x16x32_bf16 v[142:145], v[190:193], v[170:173], v[142:145]
	ds_read_b128 v[190:193], v237 offset:28672
	v_cvt_pk_bf16_f32 v100, v106, v107
	v_cvt_pk_bf16_f32 v101, v108, v109
	s_waitcnt lgkmcnt(7)
	v_mfma_f32_16x16x32_bf16 v[114:117], v[178:181], v[158:161], v[114:117]
	v_add_f32_e32 v251, v102, v251
	ds_read_b64_tr_b16 v[210:211], v240 offset:0
	ds_read_b64_tr_b16 v[212:213], v240 offset:4096
	v_mfma_f32_16x16x32_bf16 v[118:121], v[178:181], v[174:177], v[118:121]
	v_add_f32_e32 v251, v103, v251
	v_add_f32_e32 v251, v104, v251
	s_waitcnt lgkmcnt(8)
	v_mfma_f32_16x16x32_bf16 v[122:125], v[182:185], v[158:161], v[122:125]
	v_add_f32_e32 v251, v105, v251
	ds_read_b64_tr_b16 v[214:215], v241 offset:0
	ds_read_b64_tr_b16 v[216:217], v241 offset:4096
	v_mfma_f32_16x16x32_bf16 v[126:129], v[182:185], v[174:177], v[126:129]
	v_add_f32_e32 v251, v110, v251
	v_add_f32_e32 v251, v111, v251
	s_waitcnt lgkmcnt(7)
	v_mfma_f32_16x16x32_bf16 v[130:133], v[186:189], v[158:161], v[130:133]
	v_add_f32_e32 v251, v112, v251
	ds_read_b64_tr_b16 v[218:219], v242 offset:0
	ds_read_b64_tr_b16 v[220:221], v242 offset:4096
	v_mfma_f32_16x16x32_bf16 v[134:137], v[186:189], v[174:177], v[134:137]
	v_add_f32_e32 v251, v113, v251
	v_cvt_pk_bf16_f32 v102, v102, v103
	s_waitcnt lgkmcnt(6)
; #define SBAR() __builtin_amdgcn_sched_barrier(0)
; template <typename TQ> ...
;     ...
;   SBAR(); qkt(pB0, pB1, (bf16*)((char*)K_lds + SHM_K), qr, r32, hi, negm);
;   finishSM(pA0, pA1, l_reg, pa0, pa1, pa2, pa3); SBAR();
;   pv_d0(o, vb0, pa0, pa1, pa2, pa3); partialSM(pB0, pB1, mC);
;   __syncthreads();
;   finishSM(pB0, pB1, l_reg, pa0, pa1, pa2, pa3); SBAR();
;   pv_d0(o, vb0 + (int)SHM_V, pa0, pa1, pa2, pa3);
	v_mfma_f32_16x16x32_bf16 v[138:141], v[190:193], v[158:161], v[138:141]
	v_cvt_pk_bf16_f32 v103, v104, v105
	ds_read_b64_tr_b16 v[222:223], v243 offset:0
	ds_read_b64_tr_b16 v[224:225], v243 offset:4096
	v_mfma_f32_16x16x32_bf16 v[142:145], v[190:193], v[174:177], v[142:145]
	v_cvt_pk_bf16_f32 v104, v110, v111
	v_cvt_pk_bf16_f32 v105, v112, v113
	v_mfma_f32_16x16x32_bf16 v[18:21], v[202:205], v[82:85], v[18:21]
	v_exp_f32_e32 v114, v114
	v_mfma_f32_16x16x32_bf16 v[22:25], v[202:205], v[86:89], v[22:25]
	ds_read_b64_tr_b16 v[202:203], v244 offset:0
	ds_read_b64_tr_b16 v[204:205], v244 offset:4096
	v_exp_f32_e32 v115, v115
	v_mfma_f32_16x16x32_bf16 v[26:29], v[206:209], v[82:85], v[26:29]
	v_exp_f32_e32 v116, v116
	v_mfma_f32_16x16x32_bf16 v[30:33], v[206:209], v[86:89], v[30:33]
	ds_read_b64_tr_b16 v[206:207], v245 offset:0
	ds_read_b64_tr_b16 v[208:209], v245 offset:4096
	v_exp_f32_e32 v117, v117
	s_waitcnt lgkmcnt(10)
	v_mfma_f32_16x16x32_bf16 v[34:37], v[210:213], v[82:85], v[34:37]
	v_exp_f32_e32 v118, v118
	v_mfma_f32_16x16x32_bf16 v[38:41], v[210:213], v[86:89], v[38:41]
	ds_read_b64_tr_b16 v[210:211], v238 offset:8192
	ds_read_b64_tr_b16 v[212:213], v238 offset:12288
	v_exp_f32_e32 v119, v119
	s_waitcnt lgkmcnt(10)
	v_mfma_f32_16x16x32_bf16 v[42:45], v[214:217], v[82:85], v[42:45]
	v_exp_f32_e32 v120, v120
	v_mfma_f32_16x16x32_bf16 v[46:49], v[214:217], v[86:89], v[46:49]
	ds_read_b64_tr_b16 v[214:215], v239 offset:8192
	ds_read_b64_tr_b16 v[216:217], v239 offset:12288
	v_exp_f32_e32 v121, v121
	s_waitcnt lgkmcnt(10)
	v_mfma_f32_16x16x32_bf16 v[50:53], v[218:221], v[82:85], v[50:53]
	v_exp_f32_e32 v122, v122
	v_mfma_f32_16x16x32_bf16 v[54:57], v[218:221], v[86:89], v[54:57]
	ds_read_b64_tr_b16 v[218:219], v240 offset:8192
	ds_read_b64_tr_b16 v[220:221], v240 offset:12288
	v_exp_f32_e32 v123, v123
	s_waitcnt lgkmcnt(10)
	v_mfma_f32_16x16x32_bf16 v[58:61], v[222:225], v[82:85], v[58:61]
	v_exp_f32_e32 v124, v124
	v_mfma_f32_16x16x32_bf16 v[62:65], v[222:225], v[86:89], v[62:65]
	ds_read_b64_tr_b16 v[222:223], v241 offset:8192
	ds_read_b64_tr_b16 v[224:225], v241 offset:12288
	v_exp_f32_e32 v125, v125
	s_waitcnt lgkmcnt(10)
	v_mfma_f32_16x16x32_bf16 v[66:69], v[202:205], v[82:85], v[66:69]
	v_exp_f32_e32 v126, v126
	v_mfma_f32_16x16x32_bf16 v[70:73], v[202:205], v[86:89], v[70:73]
	ds_read_b64_tr_b16 v[202:203], v242 offset:8192
	ds_read_b64_tr_b16 v[204:205], v242 offset:12288
	v_exp_f32_e32 v127, v127
	s_waitcnt lgkmcnt(10)
	v_mfma_f32_16x16x32_bf16 v[74:77], v[206:209], v[82:85], v[74:77]
	v_exp_f32_e32 v128, v128
	v_mfma_f32_16x16x32_bf16 v[78:81], v[206:209], v[86:89], v[78:81]
	ds_read_b64_tr_b16 v[206:207], v243 offset:8192
	ds_read_b64_tr_b16 v[208:209], v243 offset:12288
	v_exp_f32_e32 v129, v129
	s_waitcnt lgkmcnt(10)
	v_mfma_f32_16x16x32_bf16 v[18:21], v[210:213], v[98:101], v[18:21]
	v_exp_f32_e32 v130, v130
	v_mfma_f32_16x16x32_bf16 v[22:25], v[210:213], v[102:105], v[22:25]
	ds_read_b64_tr_b16 v[210:211], v244 offset:8192
	ds_read_b64_tr_b16 v[212:213], v244 offset:12288
	v_exp_f32_e32 v131, v131
	s_waitcnt lgkmcnt(10)
	v_mfma_f32_16x16x32_bf16 v[26:29], v[214:217], v[98:101], v[26:29]
	v_exp_f32_e32 v132, v132
	v_mfma_f32_16x16x32_bf16 v[30:33], v[214:217], v[102:105], v[30:33]
	ds_read_b64_tr_b16 v[214:215], v245 offset:8192
	ds_read_b64_tr_b16 v[216:217], v245 offset:12288
	v_exp_f32_e32 v133, v133
	s_waitcnt lgkmcnt(10)
	v_mfma_f32_16x16x32_bf16 v[34:37], v[218:221], v[98:101], v[34:37]
	v_exp_f32_e32 v134, v134
	v_mfma_f32_16x16x32_bf16 v[38:41], v[218:221], v[102:105], v[38:41]
	v_exp_f32_e32 v135, v135
	s_waitcnt lgkmcnt(8)
	v_mfma_f32_16x16x32_bf16 v[42:45], v[222:225], v[98:101], v[42:45]
	v_exp_f32_e32 v136, v136
	v_mfma_f32_16x16x32_bf16 v[46:49], v[222:225], v[102:105], v[46:49]
	v_exp_f32_e32 v137, v137
	s_waitcnt lgkmcnt(6)
	v_mfma_f32_16x16x32_bf16 v[50:53], v[202:205], v[98:101], v[50:53]
	v_exp_f32_e32 v138, v138
	ds_read_b128 v[178:181], v234 offset:32768
	v_mfma_f32_16x16x32_bf16 v[54:57], v[202:205], v[102:105], v[54:57]
	v_exp_f32_e32 v139, v139
	s_waitcnt lgkmcnt(5)
	v_mfma_f32_16x16x32_bf16 v[58:61], v[206:209], v[98:101], v[58:61]
	v_exp_f32_e32 v140, v140
	ds_read_b128 v[182:185], v234 offset:36864
	v_mfma_f32_16x16x32_bf16 v[62:65], v[206:209], v[102:105], v[62:65]
	v_exp_f32_e32 v141, v141
	s_waitcnt lgkmcnt(4)
	v_mfma_f32_16x16x32_bf16 v[66:69], v[210:213], v[98:101], v[66:69]
	v_exp_f32_e32 v142, v142
	ds_read_b128 v[186:189], v234 offset:40960
	v_mfma_f32_16x16x32_bf16 v[70:73], v[210:213], v[102:105], v[70:73]
	v_exp_f32_e32 v143, v143
	s_waitcnt lgkmcnt(3)
	v_mfma_f32_16x16x32_bf16 v[74:77], v[214:217], v[98:101], v[74:77]
	v_exp_f32_e32 v144, v144
	ds_read_b128 v[190:193], v234 offset:45056
	v_mfma_f32_16x16x32_bf16 v[78:81], v[214:217], v[102:105], v[78:81]
	v_exp_f32_e32 v145, v145
	s_waitcnt vmcnt(2)
	s_barrier
; #define SBAR() __builtin_amdgcn_sched_barrier(0)
; template <typename TQ> ...
;     ...
;   SBAR(); qkt(pB0, pB1, (bf16*)((char*)K_lds + SHM_K), qr, r32, hi, negm);
;   finishSM(pA0, pA1, l_reg, pa0, pa1, pa2, pa3); SBAR();
;   pv_d0(o, vb0, pa0, pa1, pa2, pa3); partialSM(pB0, pB1, mC);
;   __syncthreads();
;   finishSM(pB0, pB1, l_reg, pa0, pa1, pa2, pa3); SBAR();
;   pv_d0(o, vb0 + (int)SHM_V, pa0, pa1, pa2, pa3);
	s_waitcnt lgkmcnt(3)
	v_mfma_f32_16x16x32_bf16 v[82:85], v[178:181], v[146:149], v[2:5]
	v_add_f32_e32 v250, v114, v250
	v_mfma_f32_16x16x32_bf16 v[86:89], v[178:181], v[162:165], v[2:5]
	ds_read_b128 v[178:181], v235 offset:32768
	v_add_f32_e32 v250, v115, v250
	v_add_f32_e32 v250, v116, v250
	s_waitcnt lgkmcnt(3)
	v_mfma_f32_16x16x32_bf16 v[90:93], v[182:185], v[146:149], v[2:5]
	v_add_f32_e32 v250, v117, v250
	v_mfma_f32_16x16x32_bf16 v[94:97], v[182:185], v[162:165], v[2:5]
	ds_read_b128 v[182:185], v235 offset:36864
	v_add_f32_e32 v250, v122, v250
	v_add_f32_e32 v250, v123, v250
	s_waitcnt lgkmcnt(3)
	v_mfma_f32_16x16x32_bf16 v[98:101], v[186:189], v[146:149], v[2:5]
	v_add_f32_e32 v250, v124, v250
	v_mfma_f32_16x16x32_bf16 v[102:105], v[186:189], v[162:165], v[2:5]
	ds_read_b128 v[186:189], v235 offset:40960
	v_add_f32_e32 v250, v125, v250
	v_cvt_pk_bf16_f32 v114, v114, v115
	s_waitcnt lgkmcnt(3)
	v_mfma_f32_16x16x32_bf16 v[106:109], v[190:193], v[146:149], v[2:5]
	v_cvt_pk_bf16_f32 v115, v116, v117
	v_mfma_f32_16x16x32_bf16 v[110:113], v[190:193], v[162:165], v[2:5]
	ds_read_b128 v[190:193], v235 offset:45056
	v_cvt_pk_bf16_f32 v116, v122, v123
	v_cvt_pk_bf16_f32 v117, v124, v125
	s_waitcnt lgkmcnt(3)
	v_mfma_f32_16x16x32_bf16 v[82:85], v[178:181], v[150:153], v[82:85]
	v_add_f32_e32 v251, v118, v251
	v_mfma_f32_16x16x32_bf16 v[86:89], v[178:181], v[166:169], v[86:89]
	ds_read_b128 v[178:181], v236 offset:32768
	v_add_f32_e32 v251, v119, v251
	v_add_f32_e32 v251, v120, v251
	s_waitcnt lgkmcnt(3)
	v_mfma_f32_16x16x32_bf16 v[90:93], v[182:185], v[150:153], v[90:93]
	v_add_f32_e32 v251, v121, v251
	v_mfma_f32_16x16x32_bf16 v[94:97], v[182:185], v[166:169], v[94:97]
	ds_read_b128 v[182:185], v236 offset:36864
	v_add_f32_e32 v251, v126, v251
	v_add_f32_e32 v251, v127, v251
	s_waitcnt lgkmcnt(3)
	v_mfma_f32_16x16x32_bf16 v[98:101], v[186:189], v[150:153], v[98:101]
	v_add_f32_e32 v251, v128, v251
	v_mfma_f32_16x16x32_bf16 v[102:105], v[186:189], v[166:169], v[102:105]
	ds_read_b128 v[186:189], v236 offset:40960
	v_add_f32_e32 v251, v129, v251
	v_cvt_pk_bf16_f32 v118, v118, v119
	s_waitcnt lgkmcnt(3)
	v_mfma_f32_16x16x32_bf16 v[106:109], v[190:193], v[150:153], v[106:109]
	v_cvt_pk_bf16_f32 v119, v120, v121
	v_mfma_f32_16x16x32_bf16 v[110:113], v[190:193], v[166:169], v[110:113]
	ds_read_b128 v[190:193], v236 offset:45056
	v_cvt_pk_bf16_f32 v120, v126, v127
	v_cvt_pk_bf16_f32 v121, v128, v129
	s_waitcnt lgkmcnt(3)
	v_mfma_f32_16x16x32_bf16 v[82:85], v[178:181], v[154:157], v[82:85]
	v_add_f32_e32 v250, v130, v250
	v_mfma_f32_16x16x32_bf16 v[86:89], v[178:181], v[170:173], v[86:89]
	ds_read_b128 v[178:181], v237 offset:32768
	v_add_f32_e32 v250, v131, v250
	v_add_f32_e32 v250, v132, v250
	s_waitcnt lgkmcnt(3)
	v_mfma_f32_16x16x32_bf16 v[90:93], v[182:185], v[154:157], v[90:93]
	v_add_f32_e32 v250, v133, v250
	v_mfma_f32_16x16x32_bf16 v[94:97], v[182:185], v[170:173], v[94:97]
	ds_read_b128 v[182:185], v237 offset:36864
	v_add_f32_e32 v250, v138, v250
	v_add_f32_e32 v250, v139, v250
	s_waitcnt lgkmcnt(3)
	v_mfma_f32_16x16x32_bf16 v[98:101], v[186:189], v[154:157], v[98:101]
	v_add_f32_e32 v250, v140, v250
	ds_read_b64_tr_b16 v[202:203], v238 offset:16384
	ds_read_b64_tr_b16 v[204:205], v238 offset:20480
	v_mfma_f32_16x16x32_bf16 v[102:105], v[186:189], v[170:173], v[102:105]
	ds_read_b128 v[186:189], v237 offset:40960
	v_add_f32_e32 v250, v141, v250
	v_cvt_pk_bf16_f32 v130, v130, v131
	s_waitcnt lgkmcnt(5)
	v_mfma_f32_16x16x32_bf16 v[106:109], v[190:193], v[154:157], v[106:109]
	v_cvt_pk_bf16_f32 v131, v132, v133
	ds_read_b64_tr_b16 v[206:207], v239 offset:16384
	ds_read_b64_tr_b16 v[208:209], v239 offset:20480
	v_mfma_f32_16x16x32_bf16 v[110:113], v[190:193], v[170:173], v[110:113]
	ds_read_b128 v[190:193], v237 offset:45056
	v_cvt_pk_bf16_f32 v132, v138, v139
	v_cvt_pk_bf16_f32 v133, v140, v141
	s_waitcnt lgkmcnt(7)
	v_mfma_f32_16x16x32_bf16 v[82:85], v[178:181], v[158:161], v[82:85]
	v_add_f32_e32 v251, v134, v251
	ds_read_b64_tr_b16 v[210:211], v240 offset:16384
	ds_read_b64_tr_b16 v[212:213], v240 offset:20480
	v_mfma_f32_16x16x32_bf16 v[86:89], v[178:181], v[174:177], v[86:89]
	v_add_f32_e32 v251, v135, v251
	v_add_f32_e32 v251, v136, v251
	s_waitcnt lgkmcnt(8)
	v_mfma_f32_16x16x32_bf16 v[90:93], v[182:185], v[158:161], v[90:93]
	v_add_f32_e32 v251, v137, v251
	ds_read_b64_tr_b16 v[214:215], v241 offset:16384
	ds_read_b64_tr_b16 v[216:217], v241 offset:20480
	v_mfma_f32_16x16x32_bf16 v[94:97], v[182:185], v[174:177], v[94:97]
	v_add_f32_e32 v251, v142, v251
	v_add_f32_e32 v251, v143, v251
	s_waitcnt lgkmcnt(7)
	v_mfma_f32_16x16x32_bf16 v[98:101], v[186:189], v[158:161], v[98:101]
	v_add_f32_e32 v251, v144, v251
	ds_read_b64_tr_b16 v[218:219], v242 offset:16384
	ds_read_b64_tr_b16 v[220:221], v242 offset:20480
	v_mfma_f32_16x16x32_bf16 v[102:105], v[186:189], v[174:177], v[102:105]
	v_add_f32_e32 v251, v145, v251
	v_cvt_pk_bf16_f32 v134, v134, v135
	s_waitcnt lgkmcnt(6)
	v_mfma_f32_16x16x32_bf16 v[106:109], v[190:193], v[158:161], v[106:109]
	v_cvt_pk_bf16_f32 v135, v136, v137
	ds_read_b64_tr_b16 v[222:223], v243 offset:16384
	ds_read_b64_tr_b16 v[224:225], v243 offset:20480
	v_mfma_f32_16x16x32_bf16 v[110:113], v[190:193], v[174:177], v[110:113]
	v_cvt_pk_bf16_f32 v136, v142, v143
	v_cvt_pk_bf16_f32 v137, v144, v145
	v_mfma_f32_16x16x32_bf16 v[18:21], v[202:205], v[114:117], v[18:21]
	v_exp_f32_e32 v82, v82
	v_mfma_f32_16x16x32_bf16 v[22:25], v[202:205], v[118:121], v[22:25]
	ds_read_b64_tr_b16 v[202:203], v244 offset:16384
	ds_read_b64_tr_b16 v[204:205], v244 offset:20480
	v_exp_f32_e32 v83, v83
	v_mfma_f32_16x16x32_bf16 v[26:29], v[206:209], v[114:117], v[26:29]
	v_exp_f32_e32 v84, v84
	v_mfma_f32_16x16x32_bf16 v[30:33], v[206:209], v[118:121], v[30:33]
	ds_read_b64_tr_b16 v[206:207], v245 offset:16384
	ds_read_b64_tr_b16 v[208:209], v245 offset:20480
	v_exp_f32_e32 v85, v85
	s_waitcnt lgkmcnt(10)
; #define SBAR() __builtin_amdgcn_sched_barrier(0)
; template <typename TQ> ...
;     ...
;   SBAR(); qkt(pB0, pB1, (bf16*)((char*)K_lds + SHM_K), qr, r32, hi, negm);
;   finishSM(pA0, pA1, l_reg, pa0, pa1, pa2, pa3); SBAR();
;   pv_d0(o, vb0, pa0, pa1, pa2, pa3); partialSM(pB0, pB1, mC);
;   __syncthreads();
;   finishSM(pB0, pB1, l_reg, pa0, pa1, pa2, pa3); SBAR();
;   pv_d0(o, vb0 + (int)SHM_V, pa0, pa1, pa2, pa3);
	v_mfma_f32_16x16x32_bf16 v[34:37], v[210:213], v[114:117], v[34:37]
	v_exp_f32_e32 v86, v86
	v_mfma_f32_16x16x32_bf16 v[38:41], v[210:213], v[118:121], v[38:41]
	ds_read_b64_tr_b16 v[210:211], v238 offset:24576
	ds_read_b64_tr_b16 v[212:213], v238 offset:28672
	v_exp_f32_e32 v87, v87
	s_waitcnt lgkmcnt(10)
	v_mfma_f32_16x16x32_bf16 v[42:45], v[214:217], v[114:117], v[42:45]
	v_exp_f32_e32 v88, v88
	v_mfma_f32_16x16x32_bf16 v[46:49], v[214:217], v[118:121], v[46:49]
	ds_read_b64_tr_b16 v[214:215], v239 offset:24576
	ds_read_b64_tr_b16 v[216:217], v239 offset:28672
	v_exp_f32_e32 v89, v89
	s_waitcnt lgkmcnt(10)
	v_mfma_f32_16x16x32_bf16 v[50:53], v[218:221], v[114:117], v[50:53]
	v_exp_f32_e32 v90, v90
	v_mfma_f32_16x16x32_bf16 v[54:57], v[218:221], v[118:121], v[54:57]
	ds_read_b64_tr_b16 v[218:219], v240 offset:24576
	ds_read_b64_tr_b16 v[220:221], v240 offset:28672
	v_exp_f32_e32 v91, v91
	s_waitcnt lgkmcnt(10)
	v_mfma_f32_16x16x32_bf16 v[58:61], v[222:225], v[114:117], v[58:61]
	v_exp_f32_e32 v92, v92
	v_mfma_f32_16x16x32_bf16 v[62:65], v[222:225], v[118:121], v[62:65]
	ds_read_b64_tr_b16 v[222:223], v241 offset:24576
	ds_read_b64_tr_b16 v[224:225], v241 offset:28672
	v_exp_f32_e32 v93, v93
	s_waitcnt lgkmcnt(10)
	v_mfma_f32_16x16x32_bf16 v[66:69], v[202:205], v[114:117], v[66:69]
	v_exp_f32_e32 v94, v94
	v_mfma_f32_16x16x32_bf16 v[70:73], v[202:205], v[118:121], v[70:73]
	ds_read_b64_tr_b16 v[202:203], v242 offset:24576
	ds_read_b64_tr_b16 v[204:205], v242 offset:28672
	v_exp_f32_e32 v95, v95
	s_waitcnt lgkmcnt(10)
	v_mfma_f32_16x16x32_bf16 v[74:77], v[206:209], v[114:117], v[74:77]
	v_exp_f32_e32 v96, v96
	v_mfma_f32_16x16x32_bf16 v[78:81], v[206:209], v[118:121], v[78:81]
	ds_read_b64_tr_b16 v[206:207], v243 offset:24576
	ds_read_b64_tr_b16 v[208:209], v243 offset:28672
	v_exp_f32_e32 v97, v97
	s_waitcnt lgkmcnt(10)
	v_mfma_f32_16x16x32_bf16 v[18:21], v[210:213], v[130:133], v[18:21]
	v_exp_f32_e32 v98, v98
	v_mfma_f32_16x16x32_bf16 v[22:25], v[210:213], v[134:137], v[22:25]
	ds_read_b64_tr_b16 v[210:211], v244 offset:24576
	ds_read_b64_tr_b16 v[212:213], v244 offset:28672
	v_exp_f32_e32 v99, v99
	s_waitcnt lgkmcnt(10)
	v_mfma_f32_16x16x32_bf16 v[26:29], v[214:217], v[130:133], v[26:29]
	v_exp_f32_e32 v100, v100
	v_mfma_f32_16x16x32_bf16 v[30:33], v[214:217], v[134:137], v[30:33]
	ds_read_b64_tr_b16 v[214:215], v245 offset:24576
	ds_read_b64_tr_b16 v[216:217], v245 offset:28672
	v_exp_f32_e32 v101, v101
	s_waitcnt lgkmcnt(10)
	v_mfma_f32_16x16x32_bf16 v[34:37], v[218:221], v[130:133], v[34:37]
	v_exp_f32_e32 v102, v102
	v_mfma_f32_16x16x32_bf16 v[38:41], v[218:221], v[134:137], v[38:41]
	v_exp_f32_e32 v103, v103
	s_waitcnt lgkmcnt(8)
	v_mfma_f32_16x16x32_bf16 v[42:45], v[222:225], v[130:133], v[42:45]
	v_exp_f32_e32 v104, v104
	v_mfma_f32_16x16x32_bf16 v[46:49], v[222:225], v[134:137], v[46:49]
	v_exp_f32_e32 v105, v105
	s_waitcnt lgkmcnt(6)
	v_mfma_f32_16x16x32_bf16 v[50:53], v[202:205], v[130:133], v[50:53]
	v_exp_f32_e32 v106, v106
	ds_read_b128 v[178:181], v234 offset:49152
	v_mfma_f32_16x16x32_bf16 v[54:57], v[202:205], v[134:137], v[54:57]
	v_exp_f32_e32 v107, v107
	s_waitcnt lgkmcnt(5)
	v_mfma_f32_16x16x32_bf16 v[58:61], v[206:209], v[130:133], v[58:61]
	v_exp_f32_e32 v108, v108
	ds_read_b128 v[182:185], v234 offset:53248
	v_mfma_f32_16x16x32_bf16 v[62:65], v[206:209], v[134:137], v[62:65]
	v_exp_f32_e32 v109, v109
	s_waitcnt lgkmcnt(4)
	v_mfma_f32_16x16x32_bf16 v[66:69], v[210:213], v[130:133], v[66:69]
	v_exp_f32_e32 v110, v110
	ds_read_b128 v[186:189], v234 offset:57344
	v_mfma_f32_16x16x32_bf16 v[70:73], v[210:213], v[134:137], v[70:73]
	v_exp_f32_e32 v111, v111
	s_waitcnt lgkmcnt(3)
	v_mfma_f32_16x16x32_bf16 v[74:77], v[214:217], v[130:133], v[74:77]
	v_exp_f32_e32 v112, v112
	ds_read_b128 v[190:193], v234 offset:61440
	v_mfma_f32_16x16x32_bf16 v[78:81], v[214:217], v[134:137], v[78:81]
	v_exp_f32_e32 v113, v113
	s_waitcnt vmcnt(0)
	s_barrier
	s_waitcnt lgkmcnt(3)
	v_mfma_f32_16x16x32_bf16 v[114:117], v[178:181], v[146:149], v[2:5]
	v_add_f32_e32 v250, v82, v250
	v_mfma_f32_16x16x32_bf16 v[118:121], v[178:181], v[162:165], v[2:5]
	ds_read_b128 v[178:181], v235 offset:49152
	v_add_f32_e32 v250, v83, v250
	v_add_f32_e32 v250, v84, v250
	s_waitcnt lgkmcnt(3)
	v_mfma_f32_16x16x32_bf16 v[122:125], v[182:185], v[146:149], v[2:5]
	v_add_f32_e32 v250, v85, v250
	v_mfma_f32_16x16x32_bf16 v[126:129], v[182:185], v[162:165], v[2:5]
	ds_read_b128 v[182:185], v235 offset:53248
	v_add_f32_e32 v250, v90, v250
	v_add_f32_e32 v250, v91, v250
	s_waitcnt lgkmcnt(3)
	v_mfma_f32_16x16x32_bf16 v[130:133], v[186:189], v[146:149], v[2:5]
	v_add_f32_e32 v250, v92, v250
	v_mfma_f32_16x16x32_bf16 v[134:137], v[186:189], v[162:165], v[2:5]
	ds_read_b128 v[186:189], v235 offset:57344
	v_add_f32_e32 v250, v93, v250
	v_cvt_pk_bf16_f32 v82, v82, v83
	s_waitcnt lgkmcnt(3)
	v_mfma_f32_16x16x32_bf16 v[138:141], v[190:193], v[146:149], v[2:5]
	v_cvt_pk_bf16_f32 v83, v84, v85
	v_mfma_f32_16x16x32_bf16 v[142:145], v[190:193], v[162:165], v[2:5]
	ds_read_b128 v[190:193], v235 offset:61440
	v_cvt_pk_bf16_f32 v84, v90, v91
	v_cvt_pk_bf16_f32 v85, v92, v93
	s_waitcnt lgkmcnt(3)
	v_mfma_f32_16x16x32_bf16 v[114:117], v[178:181], v[150:153], v[114:117]
	v_add_f32_e32 v251, v86, v251
	v_mfma_f32_16x16x32_bf16 v[118:121], v[178:181], v[166:169], v[118:121]
	ds_read_b128 v[178:181], v236 offset:49152
	v_add_f32_e32 v251, v87, v251
	v_add_f32_e32 v251, v88, v251
	s_waitcnt lgkmcnt(3)
	v_mfma_f32_16x16x32_bf16 v[122:125], v[182:185], v[150:153], v[122:125]
	v_add_f32_e32 v251, v89, v251
	v_mfma_f32_16x16x32_bf16 v[126:129], v[182:185], v[166:169], v[126:129]
	ds_read_b128 v[182:185], v236 offset:53248
	v_add_f32_e32 v251, v94, v251
	v_add_f32_e32 v251, v95, v251
	s_waitcnt lgkmcnt(3)
; #define SBAR() __builtin_amdgcn_sched_barrier(0)
; template <typename TQ> ...
;     ...
;   SBAR(); qkt(pB0, pB1, (bf16*)((char*)K_lds + SHM_K), qr, r32, hi, negm);
;   finishSM(pA0, pA1, l_reg, pa0, pa1, pa2, pa3); SBAR();
;   pv_d0(o, vb0, pa0, pa1, pa2, pa3); partialSM(pB0, pB1, mC);
;   __syncthreads();
;   finishSM(pB0, pB1, l_reg, pa0, pa1, pa2, pa3); SBAR();
;   pv_d0(o, vb0 + (int)SHM_V, pa0, pa1, pa2, pa3);
	v_mfma_f32_16x16x32_bf16 v[130:133], v[186:189], v[150:153], v[130:133]
	v_add_f32_e32 v251, v96, v251
	v_mfma_f32_16x16x32_bf16 v[134:137], v[186:189], v[166:169], v[134:137]
	ds_read_b128 v[186:189], v236 offset:57344
	v_add_f32_e32 v251, v97, v251
	v_cvt_pk_bf16_f32 v86, v86, v87
	s_waitcnt lgkmcnt(3)
	v_mfma_f32_16x16x32_bf16 v[138:141], v[190:193], v[150:153], v[138:141]
	v_cvt_pk_bf16_f32 v87, v88, v89
	v_mfma_f32_16x16x32_bf16 v[142:145], v[190:193], v[166:169], v[142:145]
	ds_read_b128 v[190:193], v236 offset:61440
	v_cvt_pk_bf16_f32 v88, v94, v95
	v_cvt_pk_bf16_f32 v89, v96, v97
	s_waitcnt lgkmcnt(3)
	v_mfma_f32_16x16x32_bf16 v[114:117], v[178:181], v[154:157], v[114:117]
	v_add_f32_e32 v250, v98, v250
	v_mfma_f32_16x16x32_bf16 v[118:121], v[178:181], v[170:173], v[118:121]
	ds_read_b128 v[178:181], v237 offset:49152
	v_add_f32_e32 v250, v99, v250
	v_add_f32_e32 v250, v100, v250
	s_waitcnt lgkmcnt(3)
	v_mfma_f32_16x16x32_bf16 v[122:125], v[182:185], v[154:157], v[122:125]
	v_add_f32_e32 v250, v101, v250
	v_mfma_f32_16x16x32_bf16 v[126:129], v[182:185], v[170:173], v[126:129]
	ds_read_b128 v[182:185], v237 offset:53248
	v_add_f32_e32 v250, v106, v250
	v_add_f32_e32 v250, v107, v250
	s_waitcnt lgkmcnt(3)
	v_mfma_f32_16x16x32_bf16 v[130:133], v[186:189], v[154:157], v[130:133]
	v_add_f32_e32 v250, v108, v250
	ds_read_b64_tr_b16 v[202:203], v238 offset:32768
	ds_read_b64_tr_b16 v[204:205], v238 offset:36864
	v_mfma_f32_16x16x32_bf16 v[134:137], v[186:189], v[170:173], v[134:137]
	ds_read_b128 v[186:189], v237 offset:57344
	v_add_f32_e32 v250, v109, v250
	v_cvt_pk_bf16_f32 v98, v98, v99
	s_waitcnt lgkmcnt(5)
	v_mfma_f32_16x16x32_bf16 v[138:141], v[190:193], v[154:157], v[138:141]
	v_cvt_pk_bf16_f32 v99, v100, v101
	ds_read_b64_tr_b16 v[206:207], v239 offset:32768
	ds_read_b64_tr_b16 v[208:209], v239 offset:36864
	v_mfma_f32_16x16x32_bf16 v[142:145], v[190:193], v[170:173], v[142:145]
	ds_read_b128 v[190:193], v237 offset:61440
	v_cvt_pk_bf16_f32 v100, v106, v107
	v_cvt_pk_bf16_f32 v101, v108, v109
	s_waitcnt lgkmcnt(7)
	v_mfma_f32_16x16x32_bf16 v[114:117], v[178:181], v[158:161], v[114:117]
	v_add_f32_e32 v251, v102, v251
	ds_read_b64_tr_b16 v[210:211], v240 offset:32768
	ds_read_b64_tr_b16 v[212:213], v240 offset:36864
	v_mfma_f32_16x16x32_bf16 v[118:121], v[178:181], v[174:177], v[118:121]
	v_add_f32_e32 v251, v103, v251
	v_add_f32_e32 v251, v104, v251
	s_waitcnt lgkmcnt(8)
	v_mfma_f32_16x16x32_bf16 v[122:125], v[182:185], v[158:161], v[122:125]
	v_add_f32_e32 v251, v105, v251
	ds_read_b64_tr_b16 v[214:215], v241 offset:32768
	ds_read_b64_tr_b16 v[216:217], v241 offset:36864
	v_mfma_f32_16x16x32_bf16 v[126:129], v[182:185], v[174:177], v[126:129]
	v_add_f32_e32 v251, v110, v251
	v_add_f32_e32 v251, v111, v251
	s_waitcnt lgkmcnt(7)
	v_mfma_f32_16x16x32_bf16 v[130:133], v[186:189], v[158:161], v[130:133]
	v_add_f32_e32 v251, v112, v251
	ds_read_b64_tr_b16 v[218:219], v242 offset:32768
	ds_read_b64_tr_b16 v[220:221], v242 offset:36864
	v_mfma_f32_16x16x32_bf16 v[134:137], v[186:189], v[174:177], v[134:137]
	v_add_f32_e32 v251, v113, v251
	v_cvt_pk_bf16_f32 v102, v102, v103
	s_waitcnt lgkmcnt(6)
	v_mfma_f32_16x16x32_bf16 v[138:141], v[190:193], v[158:161], v[138:141]
	v_cvt_pk_bf16_f32 v103, v104, v105
	ds_read_b64_tr_b16 v[222:223], v243 offset:32768
	ds_read_b64_tr_b16 v[224:225], v243 offset:36864
	v_mfma_f32_16x16x32_bf16 v[142:145], v[190:193], v[174:177], v[142:145]
	v_cvt_pk_bf16_f32 v104, v110, v111
	v_cvt_pk_bf16_f32 v105, v112, v113
	v_mfma_f32_16x16x32_bf16 v[18:21], v[202:205], v[82:85], v[18:21]
	v_exp_f32_e32 v114, v114
	v_mfma_f32_16x16x32_bf16 v[22:25], v[202:205], v[86:89], v[22:25]
	ds_read_b64_tr_b16 v[202:203], v244 offset:32768
	ds_read_b64_tr_b16 v[204:205], v244 offset:36864
	v_exp_f32_e32 v115, v115
	v_mfma_f32_16x16x32_bf16 v[26:29], v[206:209], v[82:85], v[26:29]
	v_exp_f32_e32 v116, v116
	v_mfma_f32_16x16x32_bf16 v[30:33], v[206:209], v[86:89], v[30:33]
	ds_read_b64_tr_b16 v[206:207], v245 offset:32768
	ds_read_b64_tr_b16 v[208:209], v245 offset:36864
	v_exp_f32_e32 v117, v117
	s_waitcnt lgkmcnt(10)
	v_mfma_f32_16x16x32_bf16 v[34:37], v[210:213], v[82:85], v[34:37]
	v_exp_f32_e32 v118, v118
	v_mfma_f32_16x16x32_bf16 v[38:41], v[210:213], v[86:89], v[38:41]
	ds_read_b64_tr_b16 v[210:211], v238 offset:40960
	ds_read_b64_tr_b16 v[212:213], v238 offset:45056
	v_exp_f32_e32 v119, v119
	s_waitcnt lgkmcnt(10)
	v_mfma_f32_16x16x32_bf16 v[42:45], v[214:217], v[82:85], v[42:45]
	v_exp_f32_e32 v120, v120
	v_mfma_f32_16x16x32_bf16 v[46:49], v[214:217], v[86:89], v[46:49]
	ds_read_b64_tr_b16 v[214:215], v239 offset:40960
	ds_read_b64_tr_b16 v[216:217], v239 offset:45056
	v_exp_f32_e32 v121, v121
	s_waitcnt lgkmcnt(10)
	v_mfma_f32_16x16x32_bf16 v[50:53], v[218:221], v[82:85], v[50:53]
	v_exp_f32_e32 v122, v122
	v_mfma_f32_16x16x32_bf16 v[54:57], v[218:221], v[86:89], v[54:57]
	ds_read_b64_tr_b16 v[218:219], v240 offset:40960
	ds_read_b64_tr_b16 v[220:221], v240 offset:45056
	v_exp_f32_e32 v123, v123
	s_waitcnt lgkmcnt(10)
	v_mfma_f32_16x16x32_bf16 v[58:61], v[222:225], v[82:85], v[58:61]
	v_exp_f32_e32 v124, v124
	v_mfma_f32_16x16x32_bf16 v[62:65], v[222:225], v[86:89], v[62:65]
	ds_read_b64_tr_b16 v[222:223], v241 offset:40960
	ds_read_b64_tr_b16 v[224:225], v241 offset:45056
	v_exp_f32_e32 v125, v125
	s_waitcnt lgkmcnt(10)
	v_mfma_f32_16x16x32_bf16 v[66:69], v[202:205], v[82:85], v[66:69]
	v_exp_f32_e32 v126, v126
	v_mfma_f32_16x16x32_bf16 v[70:73], v[202:205], v[86:89], v[70:73]
	ds_read_b64_tr_b16 v[202:203], v242 offset:40960
	ds_read_b64_tr_b16 v[204:205], v242 offset:45056
	v_exp_f32_e32 v127, v127
	s_waitcnt lgkmcnt(10)
; #define SBAR() __builtin_amdgcn_sched_barrier(0)
; template <typename TQ> ...
;     ...
;   SBAR(); qkt(pB0, pB1, (bf16*)((char*)K_lds + SHM_K), qr, r32, hi, negm);
;   finishSM(pA0, pA1, l_reg, pa0, pa1, pa2, pa3); SBAR();
;   pv_d0(o, vb0, pa0, pa1, pa2, pa3); partialSM(pB0, pB1, mC);
;   __syncthreads();
;   finishSM(pB0, pB1, l_reg, pa0, pa1, pa2, pa3); SBAR();
;   pv_d0(o, vb0 + (int)SHM_V, pa0, pa1, pa2, pa3);
	v_mfma_f32_16x16x32_bf16 v[74:77], v[206:209], v[82:85], v[74:77]
	v_exp_f32_e32 v128, v128
	v_mfma_f32_16x16x32_bf16 v[78:81], v[206:209], v[86:89], v[78:81]
	ds_read_b64_tr_b16 v[206:207], v243 offset:40960
	ds_read_b64_tr_b16 v[208:209], v243 offset:45056
	v_exp_f32_e32 v129, v129
	s_waitcnt lgkmcnt(10)
	v_mfma_f32_16x16x32_bf16 v[18:21], v[210:213], v[98:101], v[18:21]
	v_exp_f32_e32 v130, v130
	v_mfma_f32_16x16x32_bf16 v[22:25], v[210:213], v[102:105], v[22:25]
	ds_read_b64_tr_b16 v[210:211], v244 offset:40960
	ds_read_b64_tr_b16 v[212:213], v244 offset:45056
	v_exp_f32_e32 v131, v131
	s_waitcnt lgkmcnt(10)
	v_mfma_f32_16x16x32_bf16 v[26:29], v[214:217], v[98:101], v[26:29]
	v_exp_f32_e32 v132, v132
	v_mfma_f32_16x16x32_bf16 v[30:33], v[214:217], v[102:105], v[30:33]
	ds_read_b64_tr_b16 v[214:215], v245 offset:40960
	ds_read_b64_tr_b16 v[216:217], v245 offset:45056
	v_exp_f32_e32 v133, v133
	s_waitcnt lgkmcnt(10)
	v_mfma_f32_16x16x32_bf16 v[34:37], v[218:221], v[98:101], v[34:37]
	v_exp_f32_e32 v134, v134
	v_mfma_f32_16x16x32_bf16 v[38:41], v[218:221], v[102:105], v[38:41]
	v_exp_f32_e32 v135, v135
	s_waitcnt lgkmcnt(8)
	v_mfma_f32_16x16x32_bf16 v[42:45], v[222:225], v[98:101], v[42:45]
	v_exp_f32_e32 v136, v136
	v_mfma_f32_16x16x32_bf16 v[46:49], v[222:225], v[102:105], v[46:49]
	v_exp_f32_e32 v137, v137
	s_waitcnt lgkmcnt(6)
	v_mfma_f32_16x16x32_bf16 v[50:53], v[202:205], v[98:101], v[50:53]
	v_exp_f32_e32 v138, v138
	v_mfma_f32_16x16x32_bf16 v[54:57], v[202:205], v[102:105], v[54:57]
	v_exp_f32_e32 v139, v139
	s_waitcnt lgkmcnt(4)
	v_mfma_f32_16x16x32_bf16 v[58:61], v[206:209], v[98:101], v[58:61]
	v_exp_f32_e32 v140, v140
	v_mfma_f32_16x16x32_bf16 v[62:65], v[206:209], v[102:105], v[62:65]
	v_exp_f32_e32 v141, v141
	s_waitcnt lgkmcnt(2)
	v_mfma_f32_16x16x32_bf16 v[66:69], v[210:213], v[98:101], v[66:69]
	v_exp_f32_e32 v142, v142
	v_mfma_f32_16x16x32_bf16 v[70:73], v[210:213], v[102:105], v[70:73]
	v_exp_f32_e32 v143, v143
	s_waitcnt lgkmcnt(0)
	v_mfma_f32_16x16x32_bf16 v[74:77], v[214:217], v[98:101], v[74:77]
	v_exp_f32_e32 v144, v144
	v_mfma_f32_16x16x32_bf16 v[78:81], v[214:217], v[102:105], v[78:81]
	v_exp_f32_e32 v145, v145
	s_waitcnt vmcnt(0)
	v_add_f32_e32 v250, v114, v250
	v_add_f32_e32 v250, v115, v250
	v_add_f32_e32 v250, v116, v250
	v_add_f32_e32 v250, v117, v250
	v_add_f32_e32 v250, v122, v250
	v_add_f32_e32 v250, v123, v250
	v_add_f32_e32 v250, v124, v250
	v_add_f32_e32 v250, v125, v250
	v_cvt_pk_bf16_f32 v114, v114, v115
	v_cvt_pk_bf16_f32 v115, v116, v117
	v_cvt_pk_bf16_f32 v116, v122, v123
	v_cvt_pk_bf16_f32 v117, v124, v125
	v_add_f32_e32 v251, v118, v251
	v_add_f32_e32 v251, v119, v251
	v_add_f32_e32 v251, v120, v251
	v_add_f32_e32 v251, v121, v251
	v_add_f32_e32 v251, v126, v251
	v_add_f32_e32 v251, v127, v251
	v_add_f32_e32 v251, v128, v251
	v_add_f32_e32 v251, v129, v251
	v_cvt_pk_bf16_f32 v118, v118, v119
	v_cvt_pk_bf16_f32 v119, v120, v121
	v_cvt_pk_bf16_f32 v120, v126, v127
	v_cvt_pk_bf16_f32 v121, v128, v129
	v_add_f32_e32 v250, v130, v250
	v_add_f32_e32 v250, v131, v250
	v_add_f32_e32 v250, v132, v250
	v_add_f32_e32 v250, v133, v250
	v_add_f32_e32 v250, v138, v250
	v_add_f32_e32 v250, v139, v250
	v_add_f32_e32 v250, v140, v250
	v_add_f32_e32 v250, v141, v250
	v_cvt_pk_bf16_f32 v130, v130, v131
	v_cvt_pk_bf16_f32 v131, v132, v133
	v_cvt_pk_bf16_f32 v132, v138, v139
	v_cvt_pk_bf16_f32 v133, v140, v141
	v_add_f32_e32 v251, v134, v251
	v_add_f32_e32 v251, v135, v251
	v_add_f32_e32 v251, v136, v251
	v_add_f32_e32 v251, v137, v251
	v_add_f32_e32 v251, v142, v251
	v_add_f32_e32 v251, v143, v251
	v_add_f32_e32 v251, v144, v251
	v_add_f32_e32 v251, v145, v251
	v_cvt_pk_bf16_f32 v134, v134, v135
	v_cvt_pk_bf16_f32 v135, v136, v137
	v_cvt_pk_bf16_f32 v136, v142, v143
	v_cvt_pk_bf16_f32 v137, v144, v145
	ds_read_b64_tr_b16 v[202:203], v238 offset:49152
	ds_read_b64_tr_b16 v[204:205], v238 offset:53248
	ds_read_b64_tr_b16 v[206:207], v239 offset:49152
	ds_read_b64_tr_b16 v[208:209], v239 offset:53248
	ds_read_b64_tr_b16 v[210:211], v240 offset:49152
	ds_read_b64_tr_b16 v[212:213], v240 offset:53248
	ds_read_b64_tr_b16 v[214:215], v241 offset:49152
	ds_read_b64_tr_b16 v[216:217], v241 offset:53248
	ds_read_b64_tr_b16 v[218:219], v242 offset:49152
	ds_read_b64_tr_b16 v[220:221], v242 offset:53248
	ds_read_b64_tr_b16 v[222:223], v243 offset:49152
	ds_read_b64_tr_b16 v[224:225], v243 offset:53248
	s_waitcnt lgkmcnt(10)
	v_mfma_f32_16x16x32_bf16 v[18:21], v[202:205], v[114:117], v[18:21]
	v_mfma_f32_16x16x32_bf16 v[22:25], v[202:205], v[118:121], v[22:25]
	ds_read_b64_tr_b16 v[202:203], v244 offset:49152
	ds_read_b64_tr_b16 v[204:205], v244 offset:53248
	s_waitcnt lgkmcnt(10)
	v_mfma_f32_16x16x32_bf16 v[26:29], v[206:209], v[114:117], v[26:29]
	v_mfma_f32_16x16x32_bf16 v[30:33], v[206:209], v[118:121], v[30:33]
	ds_read_b64_tr_b16 v[206:207], v245 offset:49152
	ds_read_b64_tr_b16 v[208:209], v245 offset:53248
	s_waitcnt lgkmcnt(10)
	v_mfma_f32_16x16x32_bf16 v[34:37], v[210:213], v[114:117], v[34:37]
	v_mfma_f32_16x16x32_bf16 v[38:41], v[210:213], v[118:121], v[38:41]
	ds_read_b64_tr_b16 v[210:211], v238 offset:57344
	ds_read_b64_tr_b16 v[212:213], v238 offset:61440
	s_waitcnt lgkmcnt(10)
	v_mfma_f32_16x16x32_bf16 v[42:45], v[214:217], v[114:117], v[42:45]
	v_mfma_f32_16x16x32_bf16 v[46:49], v[214:217], v[118:121], v[46:49]
	ds_read_b64_tr_b16 v[214:215], v239 offset:57344
	ds_read_b64_tr_b16 v[216:217], v239 offset:61440
	s_waitcnt lgkmcnt(10)
	v_mfma_f32_16x16x32_bf16 v[50:53], v[218:221], v[114:117], v[50:53]
	v_mfma_f32_16x16x32_bf16 v[54:57], v[218:221], v[118:121], v[54:57]
	ds_read_b64_tr_b16 v[218:219], v240 offset:57344
	ds_read_b64_tr_b16 v[220:221], v240 offset:61440
	s_waitcnt lgkmcnt(10)
; #define SBAR() __builtin_amdgcn_sched_barrier(0)
; __device__ __forceinline__ int crow(int r, int hi) { return (r & 3) + 8 * (r >> 2) + 4 * hi; }
; template <typename TQ> ...
;     ...
;   finishSM(pB0, pB1, l_reg, pa0, pa1, pa2, pa3); SBAR();
;   pv_d0(o, vb0 + (int)SHM_V, pa0, pa1, pa2, pa3);
;   if (hi == 0) li_l[r32] = l_reg; asm volatile("s_waitcnt lgkmcnt(0)" ::: "memory");
;   float rli[16];
; #pragma unroll
;   for (int r = 0; r < 16; ++r) rli[r] = __builtin_amdgcn_rcpf(li_l[crow(r, hi)]);
;   int le = (int)(threadIdx.x & 63u); asm volatile("" : "+v"(le));
;   const int r32e = le & 31, hie = le >> 5;
;   bf16* Ow = Ob + (long)(wid * QBLK) * LDO;
; #pragma unroll
;   for (int r = 0; r < 16; ++r) { int orow = crow(r, hie);
;     for (int d0 = 0; d0 < 4; ++d0) Ow[(long)orow * LDO + d0 * 32 + r32e] = __float2bfloat16(o[d0][r] * rli[r]); }
	v_mfma_f32_16x16x32_bf16 v[58:61], v[222:225], v[114:117], v[58:61]
	v_mfma_f32_16x16x32_bf16 v[62:65], v[222:225], v[118:121], v[62:65]
	ds_read_b64_tr_b16 v[222:223], v241 offset:57344
	ds_read_b64_tr_b16 v[224:225], v241 offset:61440
	s_waitcnt lgkmcnt(10)
	v_mfma_f32_16x16x32_bf16 v[66:69], v[202:205], v[114:117], v[66:69]
	v_mfma_f32_16x16x32_bf16 v[70:73], v[202:205], v[118:121], v[70:73]
	ds_read_b64_tr_b16 v[202:203], v242 offset:57344
	ds_read_b64_tr_b16 v[204:205], v242 offset:61440
	s_waitcnt lgkmcnt(10)
	v_mfma_f32_16x16x32_bf16 v[74:77], v[206:209], v[114:117], v[74:77]
	v_mfma_f32_16x16x32_bf16 v[78:81], v[206:209], v[118:121], v[78:81]
	ds_read_b64_tr_b16 v[206:207], v243 offset:57344
	ds_read_b64_tr_b16 v[208:209], v243 offset:61440
	s_waitcnt lgkmcnt(10)
	v_mfma_f32_16x16x32_bf16 v[18:21], v[210:213], v[130:133], v[18:21]
	v_mfma_f32_16x16x32_bf16 v[22:25], v[210:213], v[134:137], v[22:25]
	ds_read_b64_tr_b16 v[210:211], v244 offset:57344
	ds_read_b64_tr_b16 v[212:213], v244 offset:61440
	s_waitcnt lgkmcnt(10)
	v_mfma_f32_16x16x32_bf16 v[26:29], v[214:217], v[130:133], v[26:29]
	v_mfma_f32_16x16x32_bf16 v[30:33], v[214:217], v[134:137], v[30:33]
	ds_read_b64_tr_b16 v[214:215], v245 offset:57344
	ds_read_b64_tr_b16 v[216:217], v245 offset:61440
	s_waitcnt lgkmcnt(10)
	v_mfma_f32_16x16x32_bf16 v[34:37], v[218:221], v[130:133], v[34:37]
	v_mfma_f32_16x16x32_bf16 v[38:41], v[218:221], v[134:137], v[38:41]
	s_waitcnt lgkmcnt(8)
	v_mfma_f32_16x16x32_bf16 v[42:45], v[222:225], v[130:133], v[42:45]
	v_mfma_f32_16x16x32_bf16 v[46:49], v[222:225], v[134:137], v[46:49]
	s_waitcnt lgkmcnt(6)
	v_mfma_f32_16x16x32_bf16 v[50:53], v[202:205], v[130:133], v[50:53]
	v_mfma_f32_16x16x32_bf16 v[54:57], v[202:205], v[134:137], v[54:57]
	s_waitcnt lgkmcnt(4)
	v_mfma_f32_16x16x32_bf16 v[58:61], v[206:209], v[130:133], v[58:61]
	v_mfma_f32_16x16x32_bf16 v[62:65], v[206:209], v[134:137], v[62:65]
	s_waitcnt lgkmcnt(2)
	v_mfma_f32_16x16x32_bf16 v[66:69], v[210:213], v[130:133], v[66:69]
	v_mfma_f32_16x16x32_bf16 v[70:73], v[210:213], v[134:137], v[70:73]
	s_waitcnt lgkmcnt(0)
	v_mfma_f32_16x16x32_bf16 v[74:77], v[214:217], v[130:133], v[74:77]
	v_mfma_f32_16x16x32_bf16 v[78:81], v[214:217], v[134:137], v[78:81]
	s_setprio 0
	ds_swizzle_b32 v6, v250 offset:swizzle(SWAP,16)
	s_waitcnt lgkmcnt(0)
	v_add_f32_e32 v250, v250, v6
	v_mov_b32_e32 v6, v250
	s_nop 1
	v_permlane32_swap_b32_e32 v250, v6
	v_add_f32_e32 v250, v250, v6
	v_rcp_f32_e32 v250, v250
	ds_swizzle_b32 v6, v251 offset:swizzle(SWAP,16)
	s_waitcnt lgkmcnt(0)
	v_add_f32_e32 v251, v251, v6
	v_mov_b32_e32 v6, v251
	s_nop 1
	v_permlane32_swap_b32_e32 v251, v6
	v_add_f32_e32 v251, v251, v6
	v_rcp_f32_e32 v251, v251
	s_add_u32 s12, s71, s48
	s_addc_u32 s13, s72, s49
	v_add_u32_e32 v201, s52, v16
	v_lshlrev_b32_e32 v201, 11, v201
	v_lshl_or_b32 v7, v17, 3, v201
	v_add_u32_e32 v200, 0x8000, v7
	v_mul_f32_e32 v18, v18, v250
	v_mul_f32_e32 v19, v19, v250
	v_mul_f32_e32 v20, v20, v250
	v_mul_f32_e32 v21, v21, v250
	v_cvt_pk_bf16_f32 v18, v18, v19
	v_cvt_pk_bf16_f32 v19, v20, v21
	global_store_dwordx2 v7, v[18:19], s[12:13] offset:0
	v_mul_f32_e32 v22, v22, v251
	v_mul_f32_e32 v23, v23, v251
	v_mul_f32_e32 v24, v24, v251
	v_mul_f32_e32 v25, v25, v251
	v_cvt_pk_bf16_f32 v22, v22, v23
	v_cvt_pk_bf16_f32 v23, v24, v25
	global_store_dwordx2 v200, v[22:23], s[12:13] offset:0
	v_mul_f32_e32 v26, v26, v250
	v_mul_f32_e32 v27, v27, v250
	v_mul_f32_e32 v28, v28, v250
	v_mul_f32_e32 v29, v29, v250
	v_cvt_pk_bf16_f32 v26, v26, v27
	v_cvt_pk_bf16_f32 v27, v28, v29
	global_store_dwordx2 v7, v[26:27], s[12:13] offset:32
	v_mul_f32_e32 v30, v30, v251
	v_mul_f32_e32 v31, v31, v251
	v_mul_f32_e32 v32, v32, v251
	v_mul_f32_e32 v33, v33, v251
	v_cvt_pk_bf16_f32 v30, v30, v31
	v_cvt_pk_bf16_f32 v31, v32, v33
	global_store_dwordx2 v200, v[30:31], s[12:13] offset:32
	v_mul_f32_e32 v34, v34, v250
	v_mul_f32_e32 v35, v35, v250
	v_mul_f32_e32 v36, v36, v250
	v_mul_f32_e32 v37, v37, v250
	v_cvt_pk_bf16_f32 v34, v34, v35
	v_cvt_pk_bf16_f32 v35, v36, v37
	global_store_dwordx2 v7, v[34:35], s[12:13] offset:64
	v_mul_f32_e32 v38, v38, v251
	v_mul_f32_e32 v39, v39, v251
	v_mul_f32_e32 v40, v40, v251
	v_mul_f32_e32 v41, v41, v251
	v_cvt_pk_bf16_f32 v38, v38, v39
	v_cvt_pk_bf16_f32 v39, v40, v41
	global_store_dwordx2 v200, v[38:39], s[12:13] offset:64
	v_mul_f32_e32 v42, v42, v250
	v_mul_f32_e32 v43, v43, v250
	v_mul_f32_e32 v44, v44, v250
	v_mul_f32_e32 v45, v45, v250
	v_cvt_pk_bf16_f32 v42, v42, v43
	v_cvt_pk_bf16_f32 v43, v44, v45
	global_store_dwordx2 v7, v[42:43], s[12:13] offset:96
	v_mul_f32_e32 v46, v46, v251
	v_mul_f32_e32 v47, v47, v251
	v_mul_f32_e32 v48, v48, v251
	v_mul_f32_e32 v49, v49, v251
	v_cvt_pk_bf16_f32 v46, v46, v47
	v_cvt_pk_bf16_f32 v47, v48, v49
	global_store_dwordx2 v200, v[46:47], s[12:13] offset:96
	v_mul_f32_e32 v50, v50, v250
	v_mul_f32_e32 v51, v51, v250
	v_mul_f32_e32 v52, v52, v250
	v_mul_f32_e32 v53, v53, v250
	v_cvt_pk_bf16_f32 v50, v50, v51
	v_cvt_pk_bf16_f32 v51, v52, v53
	global_store_dwordx2 v7, v[50:51], s[12:13] offset:128
	v_mul_f32_e32 v54, v54, v251
	v_mul_f32_e32 v55, v55, v251
	v_mul_f32_e32 v56, v56, v251
	v_mul_f32_e32 v57, v57, v251
	v_cvt_pk_bf16_f32 v54, v54, v55
	v_cvt_pk_bf16_f32 v55, v56, v57
	global_store_dwordx2 v200, v[54:55], s[12:13] offset:128
	v_mul_f32_e32 v58, v58, v250
	v_mul_f32_e32 v59, v59, v250
	v_mul_f32_e32 v60, v60, v250
	v_mul_f32_e32 v61, v61, v250
	v_cvt_pk_bf16_f32 v58, v58, v59
	v_cvt_pk_bf16_f32 v59, v60, v61
	global_store_dwordx2 v7, v[58:59], s[12:13] offset:160
	v_mul_f32_e32 v62, v62, v251
	v_mul_f32_e32 v63, v63, v251
	v_mul_f32_e32 v64, v64, v251
	v_mul_f32_e32 v65, v65, v251
	v_cvt_pk_bf16_f32 v62, v62, v63
	v_cvt_pk_bf16_f32 v63, v64, v65
	global_store_dwordx2 v200, v[62:63], s[12:13] offset:160
	v_mul_f32_e32 v66, v66, v250
	v_mul_f32_e32 v67, v67, v250
	v_mul_f32_e32 v68, v68, v250
	v_mul_f32_e32 v69, v69, v250
	v_cvt_pk_bf16_f32 v66, v66, v67
	v_cvt_pk_bf16_f32 v67, v68, v69
	global_store_dwordx2 v7, v[66:67], s[12:13] offset:192
	v_mul_f32_e32 v70, v70, v251
	v_mul_f32_e32 v71, v71, v251
	v_mul_f32_e32 v72, v72, v251
	v_mul_f32_e32 v73, v73, v251
	v_cvt_pk_bf16_f32 v70, v70, v71
	v_cvt_pk_bf16_f32 v71, v72, v73
	global_store_dwordx2 v200, v[70:71], s[12:13] offset:192
	v_mul_f32_e32 v74, v74, v250
	v_mul_f32_e32 v75, v75, v250
	v_mul_f32_e32 v76, v76, v250
	v_mul_f32_e32 v77, v77, v250
	v_cvt_pk_bf16_f32 v74, v74, v75
	v_cvt_pk_bf16_f32 v75, v76, v77
	global_store_dwordx2 v7, v[74:75], s[12:13] offset:224
	v_mul_f32_e32 v78, v78, v251
	v_mul_f32_e32 v79, v79, v251
	v_mul_f32_e32 v80, v80, v251
	v_mul_f32_e32 v81, v81, v251
	v_cvt_pk_bf16_f32 v78, v78, v79
	v_cvt_pk_bf16_f32 v79, v80, v81
	global_store_dwordx2 v200, v[78:79], s[12:13] offset:224
	s_add_i32 s74, s74, 1
	s_add_i32 s94, s94, 1
	s_cmp_eq_u32 s74, s66
	s_cselect_b64 s[0:1], -1, 0
	s_barrier
	s_branch .LBB0_818
